# hyena: the two block-private spectrum reloads of the odd half issued together (one wait instead of two)
# baseline (speedup 1.0000x reference)
; __device__ __forceinline__ float2 cmul(float2 a, float2 b) { return make_float2(a.x * b.x - a.y * b.y, a.x * b.y + a.y * b.x); }
; __device__ __forceinline__ float2 csub(float2 a, float2 b) { return make_float2(a.x - b.x, a.y - b.y); }
; __device__ __forceinline__ int fpos(int k) { return ((k & 15) << 10) | (((k >> 4) & 31) << 5) | (k >> 9); }
; __device__ __forceinline__ float2 unpack_h2(unsigned w) { return make_float2(__uint_as_float(w << 16), __uint_as_float(w & 0xffff0000u)); }
; template <int MODE> __device__ __forceinline__ void hyena_unit(KP p, int pair, float2* X, int wave_id) {
;     ...
;         const int jb = ((tid >> 5) & 15) | ((tid & 31) << 4);
;         const int jp0 = half ? (SEQ - 1 - jb) : ((SEQ - jb) & (SEQ - 1));
;         const bool special = (half == 0) && (tid == 0);
;         const int chq = special ? 0 : (fpos(jp0) >> 5);
;         const float2* xq = X + 33 * chq;
;         u32x4 kq[8], kpv[8];
;         ld32_sc0(KS + 32 * chq, kq);
;         if (half) ld32_sc0(KS + n0, kpv);
;         else {
; #pragma unroll
;           for (int i = 0; i < 8; ++i) kpv[i] = kown[i]; }
;         float2 wr[32];
; #pragma unroll
;         for (int i = 0; i < 8; ++i) {
;           const u32x4 kp = kpv[i];
; #pragma unroll
;           for (int k = 0; k < 4; ++k) {
;             const int c = 4 * i + k;
;             const int e1 = 31 - c, e2 = (32 - c) & 31;
;             const float2 Zp = xc[c]; float2 Zq = xq[special ? e2 : e1]; Zq.y = -Zq.y;
;             const float2 Kp = unpack_h2(kp[k]);
;             float2 Kq = unpack_h2(special ? kq[e2 >> 2][e2 & 3] : kq[e1 >> 2][e1 & 3]); Kq.y = -Kq.y;
;             const float2 Ua = make_float2(0.5f * (Zp.x + Zq.x), 0.5f * (Zp.y + Zq.y));
;             const float2 dz = csub(Zp, Zq); const float2 Ub = make_float2(0.5f * dz.y, -0.5f * dz.x);
;             const float2 Ka = make_float2(0.5f * (Kp.x + Kq.x), 0.5f * (Kp.y + Kq.y));
;             const float2 dk = csub(Kp, Kq); const float2 Kb = make_float2(0.5f * dk.y, -0.5f * dk.x);
;             const float2 P = cmul(Ua, Ka), Q = cmul(Ub, Kb);
;             wr[c] = make_float2(P.x - Q.y, P.y + Q.x);
.LBB0_118:
	s_or_b64 exec, exec, s[12:13]
	v_lshlrev_b32_e32 v138, 7, v96
	v_lshl_add_u64 v[98:99], s[30:31], 0, v[138:139]
	global_load_dwordx4 v[64:67], v[98:99], off sc0 sc1
	global_load_dwordx4 v[68:71], v[98:99], off offset:16 sc0 sc1
	global_load_dwordx4 v[72:75], v[98:99], off offset:32 sc0 sc1
	global_load_dwordx4 v[76:79], v[98:99], off offset:48 sc0 sc1
	global_load_dwordx4 v[80:83], v[98:99], off offset:64 sc0 sc1
	global_load_dwordx4 v[84:87], v[98:99], off offset:80 sc0 sc1
	global_load_dwordx4 v[88:91], v[98:99], off offset:96 sc0 sc1
	global_load_dwordx4 v[92:95], v[98:99], off offset:112 sc0 sc1
	v_lshlrev_b32_e32 v112, 5, v145
	s_andn2_b64 vcc, exec, s[4:5]
	v_ashrrev_i32_e32 v113, 31, v112
	s_cbranch_vccnz .LBB0_120
	v_lshl_add_u64 v[98:99], v[112:113], 2, s[30:31]
	global_load_dwordx4 v[60:63], v[98:99], off sc0 sc1
	global_load_dwordx4 v[56:59], v[98:99], off offset:16 sc0 sc1
	global_load_dwordx4 v[52:55], v[98:99], off offset:32 sc0 sc1
	global_load_dwordx4 v[48:51], v[98:99], off offset:48 sc0 sc1
	global_load_dwordx4 v[44:47], v[98:99], off offset:64 sc0 sc1
	global_load_dwordx4 v[40:43], v[98:99], off offset:80 sc0 sc1
	global_load_dwordx4 v[36:39], v[98:99], off offset:96 sc0 sc1
	global_load_dwordx4 v[32:35], v[98:99], off offset:112 sc0 sc1
	s_waitcnt vmcnt(0)
.LBB0_120:
	s_waitcnt vmcnt(0)
	s_movk_i32 s10, 0x108
	v_mad_i32_i24 v98, v96, s10, 0
	v_mul_lo_u32 v96, v145, s10
	v_mov_b32_e32 v100, 0xf8
	v_add_u32_e32 v142, 0, v96
	v_cndmask_b32_e64 v96, v100, 0, s[8:9]
	v_add_u32_e32 v96, v98, v96
	v_mov_b32_e32 v102, 0xf0
	ds_read_b64 v[96:97], v96
	v_cndmask_b32_e64 v100, v102, v100, s[8:9]
	v_cndmask_b32_e64 v101, v95, v64, s[8:9]
	v_mov_b32_e32 v111, 0xe8
	v_lshlrev_b32_e32 v116, 16, v101
	v_and_b32_e32 v117, 0xffff0000, v101
	v_add_u32_e32 v108, v98, v100
	v_cndmask_b32_e64 v109, v111, v102, s[8:9]
	ds_read2_b64 v[100:103], v142 offset1:1
	ds_read2_b64 v[104:107], v142 offset0:2 offset1:3
	v_lshlrev_b32_e32 v99, 16, v60
	v_and_b32_e32 v60, 0xffff0000, v60
	v_mov_b32_e32 v120, 0xe0
	s_waitcnt lgkmcnt(1)
	v_sub_f32_e32 v119, v101, v97
	v_add_f32_e32 v97, v101, v97
	v_sub_f32_e32 v101, v60, v117
	v_add_f32_e32 v118, v100, v96
	v_mul_f32_e32 v119, 0.5, v119
	v_sub_f32_e32 v96, v100, v96
	v_add_f32_e32 v100, v116, v99
	v_mul_f32_e32 v101, 0.5, v101
	v_mul_f32_e32 v118, 0.5, v118
	v_mul_f32_e32 v100, 0.5, v100
	v_sub_f32_e32 v99, v99, v116
	v_mul_f32_e32 v116, v101, v119
	v_mul_f32_e32 v96, -0.5, v96
	v_add_f32_e32 v60, v117, v60
	v_mul_f32_e32 v99, -0.5, v99
	v_fma_f32 v116, v100, v118, -v116
	v_mul_f32_e32 v100, v100, v119
	v_mul_f32_e32 v97, 0.5, v97
	v_mul_f32_e32 v60, 0.5, v60
	v_fmac_f32_e32 v100, v101, v118
	v_mul_f32_e32 v101, v99, v96
	v_fma_f32 v101, v60, v97, -v101
	v_mul_f32_e32 v97, v99, v97
	v_cndmask_b32_e64 v99, 2, 3, s[8:9]
	v_add_u32_e32 v110, v98, v109
	v_cndmask_b32_e64 v109, v120, v111, s[8:9]
	v_fmac_f32_e32 v97, v60, v96
	v_cmp_eq_u32_e32 vcc, 1, v99
	v_add_u32_e32 v114, v98, v109
	v_sub_f32_e32 v96, v116, v97
	v_add_f32_e32 v97, v100, v101
	v_cndmask_b32_e32 v100, v92, v93, vcc
	v_cmp_eq_u32_e64 s[10:11], 2, v99
	ds_read_b64 v[108:109], v108
	ds_read_b64 v[110:111], v110
	ds_read_b64 v[114:115], v114
	v_cndmask_b32_e64 v100, v100, v94, s[10:11]
	v_cmp_eq_u32_e64 s[12:13], 3, v99
	v_lshlrev_b32_e32 v60, 16, v61
	v_and_b32_e32 v61, 0xffff0000, v61
	v_cndmask_b32_e64 v99, v100, v95, s[12:13]
	v_lshlrev_b32_e32 v100, 16, v99
	v_and_b32_e32 v99, 0xffff0000, v99
	s_waitcnt lgkmcnt(2)
	v_add_f32_e32 v101, v102, v108
	v_sub_f32_e32 v116, v103, v109
	v_sub_f32_e32 v102, v102, v108
	v_add_f32_e32 v103, v103, v109
	v_add_f32_e32 v108, v100, v60
	v_sub_f32_e32 v109, v61, v99
	v_mul_f32_e32 v116, 0.5, v116
	v_mul_f32_e32 v108, 0.5, v108
	v_mul_f32_e32 v109, 0.5, v109
	v_sub_f32_e32 v60, v60, v100
	v_mul_f32_e32 v101, 0.5, v101
	v_mul_f32_e32 v102, -0.5, v102
	v_add_f32_e32 v61, v99, v61
	v_mul_f32_e32 v60, -0.5, v60
	v_mul_f32_e32 v99, v109, v116
	v_mul_f32_e32 v100, v108, v116
	v_mul_f32_e32 v103, 0.5, v103
	v_mul_f32_e32 v61, 0.5, v61
	v_fma_f32 v99, v108, v101, -v99
	v_fmac_f32_e32 v100, v109, v101
	v_mul_f32_e32 v101, v60, v102
	v_fma_f32 v101, v61, v103, -v101
	v_mul_f32_e32 v60, v60, v103
	v_fmac_f32_e32 v60, v61, v102
	v_add_f32_e32 v61, v100, v101
	v_cndmask_b32_e64 v100, 1, 2, s[8:9]
	v_cmp_eq_u32_e64 s[14:15], 1, v100
	v_cmp_eq_u32_e64 s[16:17], 2, v100
	v_cmp_eq_u32_e64 s[18:19], 3, v100
	v_cndmask_b32_e64 v101, v92, v93, s[14:15]
	v_cndmask_b32_e64 v94, v101, v94, s[16:17]
	v_cndmask_b32_e64 v94, v94, v95, s[18:19]
	v_sub_f32_e32 v60, v99, v60
	v_lshlrev_b32_e32 v99, 16, v62
	v_and_b32_e32 v62, 0xffff0000, v62
	v_lshlrev_b32_e32 v95, 16, v94
	v_and_b32_e32 v94, 0xffff0000, v94
	s_waitcnt lgkmcnt(1)
	v_add_f32_e32 v100, v104, v110
	v_sub_f32_e32 v101, v105, v111
	v_sub_f32_e32 v102, v104, v110
	v_add_f32_e32 v103, v105, v111
	v_add_f32_e32 v104, v95, v99
	v_sub_f32_e32 v105, v62, v94
	v_mul_f32_e32 v101, 0.5, v101
	v_mul_f32_e32 v104, 0.5, v104
	v_mul_f32_e32 v105, 0.5, v105
	v_sub_f32_e32 v95, v99, v95
	v_mul_f32_e32 v100, 0.5, v100
	v_mul_f32_e32 v103, 0.5, v103
	v_mul_f32_e32 v102, -0.5, v102
	v_add_f32_e32 v62, v94, v62
	v_mul_f32_e32 v94, -0.5, v95
	v_mul_f32_e32 v95, v105, v101
	v_mul_f32_e32 v99, v104, v101
	v_mul_f32_e32 v62, 0.5, v62
	v_fma_f32 v95, v104, v100, -v95
	v_fmac_f32_e32 v99, v105, v100
	v_mul_f32_e32 v100, v94, v102
	v_mul_f32_e32 v94, v94, v103
	v_fma_f32 v100, v62, v103, -v100
	v_fmac_f32_e32 v94, v62, v102
	v_sub_f32_e32 v94, v95, v94
	v_add_f32_e32 v95, v99, v100
	v_cndmask_b32_e64 v99, 0, 1, s[8:9]
	v_cmp_eq_u32_e64 s[20:21], 1, v99
	v_lshlrev_b32_e32 v62, 16, v63
	v_and_b32_e32 v63, 0xffff0000, v63
	v_cndmask_b32_e64 v93, v92, v93, s[20:21]
	v_lshlrev_b32_e32 v101, 16, v93
	v_and_b32_e32 v93, 0xffff0000, v93
	s_waitcnt lgkmcnt(0)
; __device__ __forceinline__ float2 cmul(float2 a, float2 b) { return make_float2(a.x * b.x - a.y * b.y, a.x * b.y + a.y * b.x); }
; __device__ __forceinline__ float2 csub(float2 a, float2 b) { return make_float2(a.x - b.x, a.y - b.y); }
; __device__ __forceinline__ float2 unpack_h2(unsigned w) { return make_float2(__uint_as_float(w << 16), __uint_as_float(w & 0xffff0000u)); }
; template <int MODE> __device__ __forceinline__ void hyena_unit(KP p, int pair, float2* X, int wave_id) {
;     ...
;         for (int i = 0; i < 8; ++i) {
;           const u32x4 kp = kpv[i];
; #pragma unroll
;           for (int k = 0; k < 4; ++k) {
;             const int c = 4 * i + k;
;             const int e1 = 31 - c, e2 = (32 - c) & 31;
;             const float2 Zp = xc[c]; float2 Zq = xq[special ? e2 : e1]; Zq.y = -Zq.y;
;             const float2 Kp = unpack_h2(kp[k]);
;             float2 Kq = unpack_h2(special ? kq[e2 >> 2][e2 & 3] : kq[e1 >> 2][e1 & 3]); Kq.y = -Kq.y;
;             const float2 Ua = make_float2(0.5f * (Zp.x + Zq.x), 0.5f * (Zp.y + Zq.y));
;             const float2 dz = csub(Zp, Zq); const float2 Ub = make_float2(0.5f * dz.y, -0.5f * dz.x);
;             const float2 Ka = make_float2(0.5f * (Kp.x + Kq.x), 0.5f * (Kp.y + Kq.y));
;             const float2 dk = csub(Kp, Kq); const float2 Kb = make_float2(0.5f * dk.y, -0.5f * dk.x);
;             const float2 P = cmul(Ua, Ka), Q = cmul(Ub, Kb);
;             wr[c] = make_float2(P.x - Q.y, P.y + Q.x);
	v_add_f32_e32 v102, v106, v114
	v_sub_f32_e32 v103, v107, v115
	v_sub_f32_e32 v104, v106, v114
	v_add_f32_e32 v105, v107, v115
	v_add_f32_e32 v106, v101, v62
	v_sub_f32_e32 v107, v63, v93
	v_mul_f32_e32 v103, 0.5, v103
	v_mul_f32_e32 v106, 0.5, v106
	v_mul_f32_e32 v107, 0.5, v107
	v_sub_f32_e32 v62, v62, v101
	v_mul_f32_e32 v102, 0.5, v102
	v_mul_f32_e32 v105, 0.5, v105
	v_mul_f32_e32 v104, -0.5, v104
	v_add_f32_e32 v63, v93, v63
	v_mul_f32_e32 v62, -0.5, v62
	v_mul_f32_e32 v93, v107, v103
	v_mul_f32_e32 v101, v106, v103
	v_mov_b32_e32 v110, 0xd8
	v_mul_f32_e32 v63, 0.5, v63
	v_fma_f32 v93, v106, v102, -v93
	v_fmac_f32_e32 v101, v107, v102
	v_mul_f32_e32 v102, v62, v104
	v_mul_f32_e32 v62, v62, v105
	v_cndmask_b32_e64 v100, v110, v120, s[8:9]
	v_fma_f32 v102, v63, v105, -v102
	v_fmac_f32_e32 v62, v63, v104
	v_sub_f32_e32 v62, v93, v62
	v_add_f32_e32 v63, v101, v102
	v_add_u32_e32 v93, v98, v100
	v_mov_b32_e32 v101, 0xd0
	ds_read_b64 v[108:109], v93
	v_cndmask_b32_e64 v100, v101, v110, s[8:9]
	v_mov_b32_e32 v115, 0xc8
	v_add_u32_e32 v110, v98, v100
	v_cndmask_b32_e64 v111, v115, v101, s[8:9]
	ds_read2_b64 v[100:103], v142 offset0:4 offset1:5
	ds_read2_b64 v[104:107], v142 offset0:6 offset1:7
	v_cndmask_b32_e64 v92, v91, v92, s[8:9]
	v_lshlrev_b32_e32 v93, 16, v56
	v_and_b32_e32 v56, 0xffff0000, v56
	v_lshlrev_b32_e32 v118, 16, v92
	v_and_b32_e32 v92, 0xffff0000, v92
	s_waitcnt lgkmcnt(1)
	v_sub_f32_e32 v120, v101, v109
	v_add_f32_e32 v101, v101, v109
	v_sub_f32_e32 v109, v56, v92
	v_add_f32_e32 v119, v100, v108
	v_mul_f32_e32 v120, 0.5, v120
	v_sub_f32_e32 v100, v100, v108
	v_add_f32_e32 v108, v118, v93
	v_mul_f32_e32 v109, 0.5, v109
	v_sub_f32_e32 v93, v93, v118
	v_mul_f32_e32 v119, 0.5, v119
	v_mul_f32_e32 v108, 0.5, v108
	v_add_f32_e32 v56, v92, v56
	v_mul_f32_e32 v92, -0.5, v93
	v_mul_f32_e32 v93, v109, v120
	v_mov_b32_e32 v121, 0xc0
	v_mul_f32_e32 v101, 0.5, v101
	v_mul_f32_e32 v100, -0.5, v100
	v_fma_f32 v93, v108, v119, -v93
	v_mul_f32_e32 v108, v108, v120
	v_add_u32_e32 v114, v98, v111
	v_cndmask_b32_e64 v111, v121, v115, s[8:9]
	v_mul_f32_e32 v56, 0.5, v56
	v_fmac_f32_e32 v108, v109, v119
	v_mul_f32_e32 v109, v92, v100
	v_mul_f32_e32 v92, v92, v101
	v_add_u32_e32 v116, v98, v111
	v_fmac_f32_e32 v92, v56, v100
	v_cndmask_b32_e32 v100, v88, v89, vcc
	ds_read_b64 v[110:111], v110
	ds_read_b64 v[114:115], v114
	ds_read_b64 v[116:117], v116
	v_cndmask_b32_e64 v100, v100, v90, s[10:11]
	v_cndmask_b32_e64 v100, v100, v91, s[12:13]
	v_fma_f32 v109, v56, v101, -v109
	v_lshlrev_b32_e32 v56, 16, v57
	v_and_b32_e32 v57, 0xffff0000, v57
	v_lshlrev_b32_e32 v101, 16, v100
	v_and_b32_e32 v100, 0xffff0000, v100
	v_sub_f32_e32 v92, v93, v92
	v_add_f32_e32 v93, v108, v109
	s_waitcnt lgkmcnt(2)
	v_add_f32_e32 v108, v102, v110
	v_sub_f32_e32 v109, v103, v111
	v_sub_f32_e32 v102, v102, v110
	v_add_f32_e32 v103, v103, v111
	v_add_f32_e32 v110, v101, v56
	v_sub_f32_e32 v111, v57, v100
	v_mul_f32_e32 v109, 0.5, v109
	v_mul_f32_e32 v110, 0.5, v110
	v_mul_f32_e32 v111, 0.5, v111
	v_sub_f32_e32 v56, v56, v101
	v_mul_f32_e32 v108, 0.5, v108
	v_mul_f32_e32 v102, -0.5, v102
	v_add_f32_e32 v57, v100, v57
	v_mul_f32_e32 v56, -0.5, v56
	v_mul_f32_e32 v100, v111, v109
	v_mul_f32_e32 v101, v110, v109
	v_mul_f32_e32 v103, 0.5, v103
	v_mul_f32_e32 v57, 0.5, v57
	v_fma_f32 v100, v110, v108, -v100
	v_fmac_f32_e32 v101, v111, v108
	v_mul_f32_e32 v108, v56, v102
	v_fma_f32 v108, v57, v103, -v108
	v_mul_f32_e32 v56, v56, v103
	v_fmac_f32_e32 v56, v57, v102
	v_add_f32_e32 v57, v101, v108
	v_cndmask_b32_e64 v101, v88, v89, s[14:15]
	v_cndmask_b32_e64 v90, v101, v90, s[16:17]
	v_cndmask_b32_e64 v90, v90, v91, s[18:19]
	v_sub_f32_e32 v56, v100, v56
	v_lshlrev_b32_e32 v100, 16, v58
	v_and_b32_e32 v58, 0xffff0000, v58
	v_lshlrev_b32_e32 v91, 16, v90
	v_and_b32_e32 v90, 0xffff0000, v90
	s_waitcnt lgkmcnt(1)
	v_add_f32_e32 v101, v104, v114
	v_sub_f32_e32 v102, v105, v115
	v_sub_f32_e32 v103, v104, v114
	v_add_f32_e32 v104, v105, v115
	v_add_f32_e32 v105, v91, v100
	v_sub_f32_e32 v108, v58, v90
	v_mul_f32_e32 v102, 0.5, v102
	v_mul_f32_e32 v105, 0.5, v105
	v_mul_f32_e32 v108, 0.5, v108
	v_sub_f32_e32 v91, v100, v91
	v_mul_f32_e32 v101, 0.5, v101
	v_mul_f32_e32 v104, 0.5, v104
	v_mul_f32_e32 v103, -0.5, v103
	v_add_f32_e32 v58, v90, v58
	v_mul_f32_e32 v90, -0.5, v91
	v_mul_f32_e32 v91, v108, v102
	v_mul_f32_e32 v100, v105, v102
	v_mul_f32_e32 v58, 0.5, v58
	v_fma_f32 v91, v105, v101, -v91
	v_fmac_f32_e32 v100, v108, v101
	v_mul_f32_e32 v101, v90, v103
	v_mul_f32_e32 v90, v90, v104
	v_fma_f32 v101, v58, v104, -v101
	v_fmac_f32_e32 v90, v58, v103
	v_cndmask_b32_e64 v89, v88, v89, s[20:21]
	v_sub_f32_e32 v90, v91, v90
	v_add_f32_e32 v91, v100, v101
	v_lshlrev_b32_e32 v58, 16, v59
	v_and_b32_e32 v59, 0xffff0000, v59
	v_lshlrev_b32_e32 v101, 16, v89
	v_and_b32_e32 v89, 0xffff0000, v89
	s_waitcnt lgkmcnt(0)
	v_add_f32_e32 v102, v106, v116
	v_sub_f32_e32 v103, v107, v117
	v_sub_f32_e32 v104, v106, v116
	v_add_f32_e32 v105, v107, v117
	v_add_f32_e32 v106, v101, v58
	v_sub_f32_e32 v107, v59, v89
	v_mul_f32_e32 v103, 0.5, v103
	v_mul_f32_e32 v106, 0.5, v106
	v_mul_f32_e32 v107, 0.5, v107
	v_sub_f32_e32 v58, v58, v101
	v_mul_f32_e32 v102, 0.5, v102
	v_mul_f32_e32 v105, 0.5, v105
	v_mul_f32_e32 v104, -0.5, v104
	v_add_f32_e32 v59, v89, v59
	v_mul_f32_e32 v58, -0.5, v58
	v_mul_f32_e32 v89, v107, v103
	v_mul_f32_e32 v101, v106, v103
	v_mov_b32_e32 v110, 0xb8
	v_mul_f32_e32 v59, 0.5, v59
	v_fma_f32 v89, v106, v102, -v89
	v_fmac_f32_e32 v101, v107, v102
	v_mul_f32_e32 v102, v58, v104
	v_mul_f32_e32 v58, v58, v105
	v_cndmask_b32_e64 v100, v110, v121, s[8:9]
	v_fma_f32 v102, v59, v105, -v102
	v_fmac_f32_e32 v58, v59, v104
	v_sub_f32_e32 v58, v89, v58
	v_add_f32_e32 v59, v101, v102
	v_add_u32_e32 v89, v98, v100
	v_mov_b32_e32 v101, 0xb0
	ds_read_b64 v[108:109], v89
	v_cndmask_b32_e64 v100, v101, v110, s[8:9]
	v_mov_b32_e32 v115, 0xa8
	v_add_u32_e32 v110, v98, v100
	v_cndmask_b32_e64 v111, v115, v101, s[8:9]
	ds_read2_b64 v[100:103], v142 offset0:8 offset1:9
	ds_read2_b64 v[104:107], v142 offset0:10 offset1:11
	v_cndmask_b32_e64 v88, v87, v88, s[8:9]
	v_lshlrev_b32_e32 v89, 16, v52
	v_and_b32_e32 v52, 0xffff0000, v52
	v_lshlrev_b32_e32 v118, 16, v88
	v_and_b32_e32 v88, 0xffff0000, v88
	s_waitcnt lgkmcnt(1)
; __device__ __forceinline__ float2 cmul(float2 a, float2 b) { return make_float2(a.x * b.x - a.y * b.y, a.x * b.y + a.y * b.x); }
; __device__ __forceinline__ float2 csub(float2 a, float2 b) { return make_float2(a.x - b.x, a.y - b.y); }
; __device__ __forceinline__ float2 unpack_h2(unsigned w) { return make_float2(__uint_as_float(w << 16), __uint_as_float(w & 0xffff0000u)); }
; template <int MODE> __device__ __forceinline__ void hyena_unit(KP p, int pair, float2* X, int wave_id) {
;     ...
;         for (int i = 0; i < 8; ++i) {
;           const u32x4 kp = kpv[i];
; #pragma unroll
;           for (int k = 0; k < 4; ++k) {
;             const int c = 4 * i + k;
;             const int e1 = 31 - c, e2 = (32 - c) & 31;
;             const float2 Zp = xc[c]; float2 Zq = xq[special ? e2 : e1]; Zq.y = -Zq.y;
;             const float2 Kp = unpack_h2(kp[k]);
;             float2 Kq = unpack_h2(special ? kq[e2 >> 2][e2 & 3] : kq[e1 >> 2][e1 & 3]); Kq.y = -Kq.y;
;             const float2 Ua = make_float2(0.5f * (Zp.x + Zq.x), 0.5f * (Zp.y + Zq.y));
;             const float2 dz = csub(Zp, Zq); const float2 Ub = make_float2(0.5f * dz.y, -0.5f * dz.x);
;             const float2 Ka = make_float2(0.5f * (Kp.x + Kq.x), 0.5f * (Kp.y + Kq.y));
;             const float2 dk = csub(Kp, Kq); const float2 Kb = make_float2(0.5f * dk.y, -0.5f * dk.x);
;             const float2 P = cmul(Ua, Ka), Q = cmul(Ub, Kb);
;             wr[c] = make_float2(P.x - Q.y, P.y + Q.x);
	v_sub_f32_e32 v120, v101, v109
	v_add_f32_e32 v101, v101, v109
	v_sub_f32_e32 v109, v52, v88
	v_add_f32_e32 v119, v100, v108
	v_mul_f32_e32 v120, 0.5, v120
	v_sub_f32_e32 v100, v100, v108
	v_add_f32_e32 v108, v118, v89
	v_mul_f32_e32 v109, 0.5, v109
	v_sub_f32_e32 v89, v89, v118
	v_mul_f32_e32 v119, 0.5, v119
	v_mul_f32_e32 v108, 0.5, v108
	v_add_f32_e32 v52, v88, v52
	v_mul_f32_e32 v88, -0.5, v89
	v_mul_f32_e32 v89, v109, v120
	v_mov_b32_e32 v121, 0xa0
	v_mul_f32_e32 v101, 0.5, v101
	v_mul_f32_e32 v100, -0.5, v100
	v_fma_f32 v89, v108, v119, -v89
	v_mul_f32_e32 v108, v108, v120
	v_add_u32_e32 v114, v98, v111
	v_cndmask_b32_e64 v111, v121, v115, s[8:9]
	v_mul_f32_e32 v52, 0.5, v52
	v_fmac_f32_e32 v108, v109, v119
	v_mul_f32_e32 v109, v88, v100
	v_mul_f32_e32 v88, v88, v101
	v_add_u32_e32 v116, v98, v111
	v_fmac_f32_e32 v88, v52, v100
	v_cndmask_b32_e32 v100, v84, v85, vcc
	ds_read_b64 v[110:111], v110
	ds_read_b64 v[114:115], v114
	ds_read_b64 v[116:117], v116
	v_cndmask_b32_e64 v100, v100, v86, s[10:11]
	v_cndmask_b32_e64 v100, v100, v87, s[12:13]
	v_fma_f32 v109, v52, v101, -v109
	v_lshlrev_b32_e32 v52, 16, v53
	v_and_b32_e32 v53, 0xffff0000, v53
	v_lshlrev_b32_e32 v101, 16, v100
	v_and_b32_e32 v100, 0xffff0000, v100
	v_sub_f32_e32 v88, v89, v88
	v_add_f32_e32 v89, v108, v109
	s_waitcnt lgkmcnt(2)
	v_add_f32_e32 v108, v102, v110
	v_sub_f32_e32 v109, v103, v111
	v_sub_f32_e32 v102, v102, v110
	v_add_f32_e32 v103, v103, v111
	v_add_f32_e32 v110, v101, v52
	v_sub_f32_e32 v111, v53, v100
	v_mul_f32_e32 v109, 0.5, v109
	v_mul_f32_e32 v110, 0.5, v110
	v_mul_f32_e32 v111, 0.5, v111
	v_sub_f32_e32 v52, v52, v101
	v_mul_f32_e32 v108, 0.5, v108
	v_mul_f32_e32 v102, -0.5, v102
	v_add_f32_e32 v53, v100, v53
	v_mul_f32_e32 v52, -0.5, v52
	v_mul_f32_e32 v100, v111, v109
	v_mul_f32_e32 v101, v110, v109
	v_mul_f32_e32 v103, 0.5, v103
	v_mul_f32_e32 v53, 0.5, v53
	v_fma_f32 v100, v110, v108, -v100
	v_fmac_f32_e32 v101, v111, v108
	v_mul_f32_e32 v108, v52, v102
	v_fma_f32 v108, v53, v103, -v108
	v_mul_f32_e32 v52, v52, v103
	v_fmac_f32_e32 v52, v53, v102
	v_add_f32_e32 v53, v101, v108
	v_cndmask_b32_e64 v101, v84, v85, s[14:15]
	v_cndmask_b32_e64 v86, v101, v86, s[16:17]
	v_cndmask_b32_e64 v86, v86, v87, s[18:19]
	v_sub_f32_e32 v52, v100, v52
	v_lshlrev_b32_e32 v100, 16, v54
	v_and_b32_e32 v54, 0xffff0000, v54
	v_lshlrev_b32_e32 v87, 16, v86
	v_and_b32_e32 v86, 0xffff0000, v86
	s_waitcnt lgkmcnt(1)
	v_add_f32_e32 v101, v104, v114
	v_sub_f32_e32 v102, v105, v115
	v_sub_f32_e32 v103, v104, v114
	v_add_f32_e32 v104, v105, v115
	v_add_f32_e32 v105, v87, v100
	v_sub_f32_e32 v108, v54, v86
	v_mul_f32_e32 v102, 0.5, v102
	v_mul_f32_e32 v105, 0.5, v105
	v_mul_f32_e32 v108, 0.5, v108
	v_sub_f32_e32 v87, v100, v87
	v_mul_f32_e32 v101, 0.5, v101
	v_mul_f32_e32 v104, 0.5, v104
	v_mul_f32_e32 v103, -0.5, v103
	v_add_f32_e32 v54, v86, v54
	v_mul_f32_e32 v86, -0.5, v87
	v_mul_f32_e32 v87, v108, v102
	v_mul_f32_e32 v100, v105, v102
	v_mul_f32_e32 v54, 0.5, v54
	v_fma_f32 v87, v105, v101, -v87
	v_fmac_f32_e32 v100, v108, v101
	v_mul_f32_e32 v101, v86, v103
	v_mul_f32_e32 v86, v86, v104
	v_fma_f32 v101, v54, v104, -v101
	v_fmac_f32_e32 v86, v54, v103
	v_cndmask_b32_e64 v85, v84, v85, s[20:21]
	v_sub_f32_e32 v86, v87, v86
	v_add_f32_e32 v87, v100, v101
	v_lshlrev_b32_e32 v54, 16, v55
	v_and_b32_e32 v55, 0xffff0000, v55
	v_lshlrev_b32_e32 v101, 16, v85
	v_and_b32_e32 v85, 0xffff0000, v85
	s_waitcnt lgkmcnt(0)
	v_add_f32_e32 v102, v106, v116
	v_sub_f32_e32 v103, v107, v117
	v_sub_f32_e32 v104, v106, v116
	v_add_f32_e32 v105, v107, v117
	v_add_f32_e32 v106, v101, v54
	v_sub_f32_e32 v107, v55, v85
	v_mul_f32_e32 v103, 0.5, v103
	v_mul_f32_e32 v106, 0.5, v106
	v_mul_f32_e32 v107, 0.5, v107
	v_sub_f32_e32 v54, v54, v101
	v_mul_f32_e32 v102, 0.5, v102
	v_mul_f32_e32 v105, 0.5, v105
	v_mul_f32_e32 v104, -0.5, v104
	v_add_f32_e32 v55, v85, v55
	v_mul_f32_e32 v54, -0.5, v54
	v_mul_f32_e32 v85, v107, v103
	v_mul_f32_e32 v101, v106, v103
	v_mov_b32_e32 v110, 0x98
	v_mul_f32_e32 v55, 0.5, v55
	v_fma_f32 v85, v106, v102, -v85
	v_fmac_f32_e32 v101, v107, v102
	v_mul_f32_e32 v102, v54, v104
	v_mul_f32_e32 v54, v54, v105
	v_cndmask_b32_e64 v100, v110, v121, s[8:9]
	v_fma_f32 v102, v55, v105, -v102
	v_fmac_f32_e32 v54, v55, v104
	v_sub_f32_e32 v54, v85, v54
	v_add_f32_e32 v55, v101, v102
	v_add_u32_e32 v85, v98, v100
	v_mov_b32_e32 v101, 0x90
	ds_read_b64 v[108:109], v85
	v_cndmask_b32_e64 v100, v101, v110, s[8:9]
	v_mov_b32_e32 v115, 0x88
	v_add_u32_e32 v110, v98, v100
	v_cndmask_b32_e64 v111, v115, v101, s[8:9]
	ds_read2_b64 v[100:103], v142 offset0:12 offset1:13
	ds_read2_b64 v[104:107], v142 offset0:14 offset1:15
	v_cndmask_b32_e64 v84, v83, v84, s[8:9]
	v_lshlrev_b32_e32 v85, 16, v48
	v_and_b32_e32 v48, 0xffff0000, v48
	v_lshlrev_b32_e32 v118, 16, v84
	v_and_b32_e32 v84, 0xffff0000, v84
	s_waitcnt lgkmcnt(1)
	v_sub_f32_e32 v120, v101, v109
	v_add_f32_e32 v101, v101, v109
	v_sub_f32_e32 v109, v48, v84
	v_add_f32_e32 v119, v100, v108
	v_mul_f32_e32 v120, 0.5, v120
	v_sub_f32_e32 v100, v100, v108
	v_add_f32_e32 v108, v118, v85
	v_mul_f32_e32 v109, 0.5, v109
	v_sub_f32_e32 v85, v85, v118
	v_mul_f32_e32 v119, 0.5, v119
	v_mul_f32_e32 v108, 0.5, v108
	v_add_f32_e32 v48, v84, v48
	v_mul_f32_e32 v84, -0.5, v85
	v_mul_f32_e32 v85, v109, v120
	v_mov_b32_e32 v121, 0x80
	v_mul_f32_e32 v101, 0.5, v101
	v_mul_f32_e32 v100, -0.5, v100
	v_fma_f32 v85, v108, v119, -v85
	v_mul_f32_e32 v108, v108, v120
	v_add_u32_e32 v114, v98, v111
	v_cndmask_b32_e64 v111, v121, v115, s[8:9]
	v_mul_f32_e32 v48, 0.5, v48
	v_fmac_f32_e32 v108, v109, v119
	v_mul_f32_e32 v109, v84, v100
	v_mul_f32_e32 v84, v84, v101
	v_add_u32_e32 v116, v98, v111
	v_fmac_f32_e32 v84, v48, v100
	v_cndmask_b32_e32 v100, v80, v81, vcc
	ds_read_b64 v[110:111], v110
	ds_read_b64 v[114:115], v114
	ds_read_b64 v[116:117], v116
	v_cndmask_b32_e64 v100, v100, v82, s[10:11]
	v_cndmask_b32_e64 v100, v100, v83, s[12:13]
	v_fma_f32 v109, v48, v101, -v109
	v_lshlrev_b32_e32 v48, 16, v49
	v_and_b32_e32 v49, 0xffff0000, v49
	v_lshlrev_b32_e32 v101, 16, v100
	v_and_b32_e32 v100, 0xffff0000, v100
	v_sub_f32_e32 v84, v85, v84
	v_add_f32_e32 v85, v108, v109
	s_waitcnt lgkmcnt(2)
; __device__ __forceinline__ float2 cmul(float2 a, float2 b) { return make_float2(a.x * b.x - a.y * b.y, a.x * b.y + a.y * b.x); }
; __device__ __forceinline__ float2 csub(float2 a, float2 b) { return make_float2(a.x - b.x, a.y - b.y); }
; __device__ __forceinline__ float2 unpack_h2(unsigned w) { return make_float2(__uint_as_float(w << 16), __uint_as_float(w & 0xffff0000u)); }
; template <int MODE> __device__ __forceinline__ void hyena_unit(KP p, int pair, float2* X, int wave_id) {
;     ...
;         float2 wr[32];
; #pragma unroll
;         for (int i = 0; i < 8; ++i) {
;           const u32x4 kp = kpv[i];
; #pragma unroll
;           for (int k = 0; k < 4; ++k) {
;             const int c = 4 * i + k;
;             const int e1 = 31 - c, e2 = (32 - c) & 31;
;             const float2 Zp = xc[c]; float2 Zq = xq[special ? e2 : e1]; Zq.y = -Zq.y;
;             const float2 Kp = unpack_h2(kp[k]);
;             float2 Kq = unpack_h2(special ? kq[e2 >> 2][e2 & 3] : kq[e1 >> 2][e1 & 3]); Kq.y = -Kq.y;
;             const float2 Ua = make_float2(0.5f * (Zp.x + Zq.x), 0.5f * (Zp.y + Zq.y));
;             const float2 dz = csub(Zp, Zq); const float2 Ub = make_float2(0.5f * dz.y, -0.5f * dz.x);
;             const float2 Ka = make_float2(0.5f * (Kp.x + Kq.x), 0.5f * (Kp.y + Kq.y));
;             const float2 dk = csub(Kp, Kq); const float2 Kb = make_float2(0.5f * dk.y, -0.5f * dk.x);
;             const float2 P = cmul(Ua, Ka), Q = cmul(Ub, Kb);
;             wr[c] = make_float2(P.x - Q.y, P.y + Q.x);
;           }
;         }
	v_add_f32_e32 v108, v102, v110
	v_sub_f32_e32 v109, v103, v111
	v_sub_f32_e32 v102, v102, v110
	v_add_f32_e32 v103, v103, v111
	v_add_f32_e32 v110, v101, v48
	v_sub_f32_e32 v111, v49, v100
	v_mul_f32_e32 v109, 0.5, v109
	v_mul_f32_e32 v110, 0.5, v110
	v_mul_f32_e32 v111, 0.5, v111
	v_sub_f32_e32 v48, v48, v101
	v_mul_f32_e32 v108, 0.5, v108
	v_mul_f32_e32 v102, -0.5, v102
	v_add_f32_e32 v49, v100, v49
	v_mul_f32_e32 v48, -0.5, v48
	v_mul_f32_e32 v100, v111, v109
	v_mul_f32_e32 v101, v110, v109
	v_mul_f32_e32 v103, 0.5, v103
	v_mul_f32_e32 v49, 0.5, v49
	v_fma_f32 v100, v110, v108, -v100
	v_fmac_f32_e32 v101, v111, v108
	v_mul_f32_e32 v108, v48, v102
	v_fma_f32 v108, v49, v103, -v108
	v_mul_f32_e32 v48, v48, v103
	v_fmac_f32_e32 v48, v49, v102
	v_add_f32_e32 v49, v101, v108
	v_cndmask_b32_e64 v101, v80, v81, s[14:15]
	v_cndmask_b32_e64 v82, v101, v82, s[16:17]
	v_cndmask_b32_e64 v82, v82, v83, s[18:19]
	v_sub_f32_e32 v48, v100, v48
	v_lshlrev_b32_e32 v100, 16, v50
	v_and_b32_e32 v50, 0xffff0000, v50
	v_lshlrev_b32_e32 v83, 16, v82
	v_and_b32_e32 v82, 0xffff0000, v82
	s_waitcnt lgkmcnt(1)
	v_add_f32_e32 v101, v104, v114
	v_sub_f32_e32 v102, v105, v115
	v_sub_f32_e32 v103, v104, v114
	v_add_f32_e32 v104, v105, v115
	v_add_f32_e32 v105, v83, v100
	v_sub_f32_e32 v108, v50, v82
	v_mul_f32_e32 v102, 0.5, v102
	v_mul_f32_e32 v105, 0.5, v105
	v_mul_f32_e32 v108, 0.5, v108
	v_sub_f32_e32 v83, v100, v83
	v_mul_f32_e32 v101, 0.5, v101
	v_mul_f32_e32 v104, 0.5, v104
	v_mul_f32_e32 v103, -0.5, v103
	v_add_f32_e32 v50, v82, v50
	v_mul_f32_e32 v82, -0.5, v83
	v_mul_f32_e32 v83, v108, v102
	v_mul_f32_e32 v100, v105, v102
	v_mul_f32_e32 v50, 0.5, v50
	v_fma_f32 v83, v105, v101, -v83
	v_fmac_f32_e32 v100, v108, v101
	v_mul_f32_e32 v101, v82, v103
	v_mul_f32_e32 v82, v82, v104
	v_fma_f32 v101, v50, v104, -v101
	v_fmac_f32_e32 v82, v50, v103
	v_cndmask_b32_e64 v81, v80, v81, s[20:21]
	v_sub_f32_e32 v82, v83, v82
	v_add_f32_e32 v83, v100, v101
	v_lshlrev_b32_e32 v50, 16, v51
	v_and_b32_e32 v51, 0xffff0000, v51
	v_lshlrev_b32_e32 v101, 16, v81
	v_and_b32_e32 v81, 0xffff0000, v81
	s_waitcnt lgkmcnt(0)
	v_add_f32_e32 v102, v106, v116
	v_sub_f32_e32 v103, v107, v117
	v_sub_f32_e32 v104, v106, v116
	v_add_f32_e32 v105, v107, v117
	v_add_f32_e32 v106, v101, v50
	v_sub_f32_e32 v107, v51, v81
	v_mul_f32_e32 v103, 0.5, v103
	v_mul_f32_e32 v106, 0.5, v106
	v_mul_f32_e32 v107, 0.5, v107
	v_sub_f32_e32 v50, v50, v101
	v_mul_f32_e32 v102, 0.5, v102
	v_mul_f32_e32 v105, 0.5, v105
	v_mul_f32_e32 v104, -0.5, v104
	v_add_f32_e32 v51, v81, v51
	v_mul_f32_e32 v50, -0.5, v50
	v_mul_f32_e32 v81, v107, v103
	v_mul_f32_e32 v101, v106, v103
	v_mov_b32_e32 v110, 0x78
	v_mul_f32_e32 v51, 0.5, v51
	v_fma_f32 v81, v106, v102, -v81
	v_fmac_f32_e32 v101, v107, v102
	v_mul_f32_e32 v102, v50, v104
	v_mul_f32_e32 v50, v50, v105
	v_cndmask_b32_e64 v100, v110, v121, s[8:9]
	v_fma_f32 v102, v51, v105, -v102
	v_fmac_f32_e32 v50, v51, v104
	v_sub_f32_e32 v50, v81, v50
	v_add_f32_e32 v51, v101, v102
	v_add_u32_e32 v81, v98, v100
	v_mov_b32_e32 v101, 0x70
	ds_read_b64 v[108:109], v81
	v_cndmask_b32_e64 v100, v101, v110, s[8:9]
	v_mov_b32_e32 v115, 0x68
	v_add_u32_e32 v110, v98, v100
	v_cndmask_b32_e64 v111, v115, v101, s[8:9]
	ds_read2_b64 v[100:103], v142 offset0:16 offset1:17
	ds_read2_b64 v[104:107], v142 offset0:18 offset1:19
	v_cndmask_b32_e64 v80, v79, v80, s[8:9]
	v_lshlrev_b32_e32 v81, 16, v44
	v_and_b32_e32 v44, 0xffff0000, v44
	v_lshlrev_b32_e32 v118, 16, v80
	v_and_b32_e32 v80, 0xffff0000, v80
	s_waitcnt lgkmcnt(1)
	v_sub_f32_e32 v120, v101, v109
	v_add_f32_e32 v101, v101, v109
	v_sub_f32_e32 v109, v44, v80
	v_add_f32_e32 v119, v100, v108
	v_mul_f32_e32 v120, 0.5, v120
	v_sub_f32_e32 v100, v100, v108
	v_add_f32_e32 v108, v118, v81
	v_mul_f32_e32 v109, 0.5, v109
	v_sub_f32_e32 v81, v81, v118
	v_mul_f32_e32 v119, 0.5, v119
	v_mul_f32_e32 v108, 0.5, v108
	v_add_f32_e32 v44, v80, v44
	v_mul_f32_e32 v80, -0.5, v81
	v_mul_f32_e32 v81, v109, v120
	v_mov_b32_e32 v121, 0x60
	v_mul_f32_e32 v101, 0.5, v101
	v_mul_f32_e32 v100, -0.5, v100
	v_fma_f32 v81, v108, v119, -v81
	v_mul_f32_e32 v108, v108, v120
	v_add_u32_e32 v114, v98, v111
	v_cndmask_b32_e64 v111, v121, v115, s[8:9]
	v_mul_f32_e32 v44, 0.5, v44
	v_fmac_f32_e32 v108, v109, v119
	v_mul_f32_e32 v109, v80, v100
	v_mul_f32_e32 v80, v80, v101
	v_add_u32_e32 v116, v98, v111
	v_fmac_f32_e32 v80, v44, v100
	v_cndmask_b32_e32 v100, v76, v77, vcc
	ds_read_b64 v[110:111], v110
	ds_read_b64 v[114:115], v114
	ds_read_b64 v[116:117], v116
	v_cndmask_b32_e64 v100, v100, v78, s[10:11]
	v_cndmask_b32_e64 v100, v100, v79, s[12:13]
	v_fma_f32 v109, v44, v101, -v109
	v_lshlrev_b32_e32 v44, 16, v45
	v_and_b32_e32 v45, 0xffff0000, v45
	v_lshlrev_b32_e32 v101, 16, v100
	v_and_b32_e32 v100, 0xffff0000, v100
	v_sub_f32_e32 v80, v81, v80
	v_add_f32_e32 v81, v108, v109
	s_waitcnt lgkmcnt(2)
	v_add_f32_e32 v108, v102, v110
	v_sub_f32_e32 v109, v103, v111
	v_sub_f32_e32 v102, v102, v110
	v_add_f32_e32 v103, v103, v111
	v_add_f32_e32 v110, v101, v44
	v_sub_f32_e32 v111, v45, v100
	v_mul_f32_e32 v109, 0.5, v109
	v_mul_f32_e32 v110, 0.5, v110
	v_mul_f32_e32 v111, 0.5, v111
	v_sub_f32_e32 v44, v44, v101
	v_mul_f32_e32 v108, 0.5, v108
	v_mul_f32_e32 v102, -0.5, v102
	v_add_f32_e32 v45, v100, v45
	v_mul_f32_e32 v44, -0.5, v44
	v_mul_f32_e32 v100, v111, v109
	v_mul_f32_e32 v101, v110, v109
	v_mul_f32_e32 v103, 0.5, v103
	v_mul_f32_e32 v45, 0.5, v45
	v_fma_f32 v100, v110, v108, -v100
	v_fmac_f32_e32 v101, v111, v108
	v_mul_f32_e32 v108, v44, v102
	v_fma_f32 v108, v45, v103, -v108
	v_mul_f32_e32 v44, v44, v103
	v_fmac_f32_e32 v44, v45, v102
	v_add_f32_e32 v45, v101, v108
	v_cndmask_b32_e64 v101, v76, v77, s[14:15]
	v_cndmask_b32_e64 v78, v101, v78, s[16:17]
	v_cndmask_b32_e64 v78, v78, v79, s[18:19]
	v_sub_f32_e32 v44, v100, v44
	v_lshlrev_b32_e32 v100, 16, v46
	v_and_b32_e32 v46, 0xffff0000, v46
	v_lshlrev_b32_e32 v79, 16, v78
	v_and_b32_e32 v78, 0xffff0000, v78
	s_waitcnt lgkmcnt(1)
; __device__ __forceinline__ float2 cmul(float2 a, float2 b) { return make_float2(a.x * b.x - a.y * b.y, a.x * b.y + a.y * b.x); }
; __device__ __forceinline__ float2 csub(float2 a, float2 b) { return make_float2(a.x - b.x, a.y - b.y); }
; __device__ __forceinline__ float2 unpack_h2(unsigned w) { return make_float2(__uint_as_float(w << 16), __uint_as_float(w & 0xffff0000u)); }
; template <int MODE> __device__ __forceinline__ void hyena_unit(KP p, int pair, float2* X, int wave_id) {
;     ...
;         float2 wr[32];
; #pragma unroll
;         for (int i = 0; i < 8; ++i) {
;           const u32x4 kp = kpv[i];
; #pragma unroll
;           for (int k = 0; k < 4; ++k) {
;             const int c = 4 * i + k;
;             const int e1 = 31 - c, e2 = (32 - c) & 31;
;             const float2 Zp = xc[c]; float2 Zq = xq[special ? e2 : e1]; Zq.y = -Zq.y;
;             const float2 Kp = unpack_h2(kp[k]);
;             float2 Kq = unpack_h2(special ? kq[e2 >> 2][e2 & 3] : kq[e1 >> 2][e1 & 3]); Kq.y = -Kq.y;
;             const float2 Ua = make_float2(0.5f * (Zp.x + Zq.x), 0.5f * (Zp.y + Zq.y));
;             const float2 dz = csub(Zp, Zq); const float2 Ub = make_float2(0.5f * dz.y, -0.5f * dz.x);
;             const float2 Ka = make_float2(0.5f * (Kp.x + Kq.x), 0.5f * (Kp.y + Kq.y));
;             const float2 dk = csub(Kp, Kq); const float2 Kb = make_float2(0.5f * dk.y, -0.5f * dk.x);
;             const float2 P = cmul(Ua, Ka), Q = cmul(Ub, Kb);
;             wr[c] = make_float2(P.x - Q.y, P.y + Q.x);
;           }
;         }
	v_add_f32_e32 v101, v104, v114
	v_sub_f32_e32 v102, v105, v115
	v_sub_f32_e32 v103, v104, v114
	v_add_f32_e32 v104, v105, v115
	v_add_f32_e32 v105, v79, v100
	v_sub_f32_e32 v108, v46, v78
	v_mul_f32_e32 v102, 0.5, v102
	v_mul_f32_e32 v105, 0.5, v105
	v_mul_f32_e32 v108, 0.5, v108
	v_sub_f32_e32 v79, v100, v79
	v_mul_f32_e32 v101, 0.5, v101
	v_mul_f32_e32 v104, 0.5, v104
	v_mul_f32_e32 v103, -0.5, v103
	v_add_f32_e32 v46, v78, v46
	v_mul_f32_e32 v78, -0.5, v79
	v_mul_f32_e32 v79, v108, v102
	v_mul_f32_e32 v100, v105, v102
	v_mul_f32_e32 v46, 0.5, v46
	v_fma_f32 v79, v105, v101, -v79
	v_fmac_f32_e32 v100, v108, v101
	v_mul_f32_e32 v101, v78, v103
	v_mul_f32_e32 v78, v78, v104
	v_fma_f32 v101, v46, v104, -v101
	v_fmac_f32_e32 v78, v46, v103
	v_cndmask_b32_e64 v77, v76, v77, s[20:21]
	v_sub_f32_e32 v78, v79, v78
	v_add_f32_e32 v79, v100, v101
	v_lshlrev_b32_e32 v46, 16, v47
	v_and_b32_e32 v47, 0xffff0000, v47
	v_lshlrev_b32_e32 v101, 16, v77
	v_and_b32_e32 v77, 0xffff0000, v77
	s_waitcnt lgkmcnt(0)
	v_add_f32_e32 v102, v106, v116
	v_sub_f32_e32 v103, v107, v117
	v_sub_f32_e32 v104, v106, v116
	v_add_f32_e32 v105, v107, v117
	v_add_f32_e32 v106, v101, v46
	v_sub_f32_e32 v107, v47, v77
	v_mul_f32_e32 v103, 0.5, v103
	v_mul_f32_e32 v106, 0.5, v106
	v_mul_f32_e32 v107, 0.5, v107
	v_sub_f32_e32 v46, v46, v101
	v_mul_f32_e32 v102, 0.5, v102
	v_mul_f32_e32 v105, 0.5, v105
	v_mul_f32_e32 v104, -0.5, v104
	v_add_f32_e32 v47, v77, v47
	v_mul_f32_e32 v46, -0.5, v46
	v_mul_f32_e32 v77, v107, v103
	v_mul_f32_e32 v101, v106, v103
	v_mov_b32_e32 v110, 0x58
	v_mul_f32_e32 v47, 0.5, v47
	v_fma_f32 v77, v106, v102, -v77
	v_fmac_f32_e32 v101, v107, v102
	v_mul_f32_e32 v102, v46, v104
	v_mul_f32_e32 v46, v46, v105
	v_cndmask_b32_e64 v100, v110, v121, s[8:9]
	v_fma_f32 v102, v47, v105, -v102
	v_fmac_f32_e32 v46, v47, v104
	v_sub_f32_e32 v46, v77, v46
	v_add_f32_e32 v47, v101, v102
	v_add_u32_e32 v77, v98, v100
	v_mov_b32_e32 v101, 0x50
	ds_read_b64 v[108:109], v77
	v_cndmask_b32_e64 v100, v101, v110, s[8:9]
	v_add_u32_e32 v110, v98, v100
	v_cndmask_b32_e64 v111, v243, v101, s[8:9]
	ds_read2_b64 v[100:103], v142 offset0:20 offset1:21
	ds_read2_b64 v[104:107], v142 offset0:22 offset1:23
	v_cndmask_b32_e64 v76, v75, v76, s[8:9]
	v_lshlrev_b32_e32 v77, 16, v40
	v_and_b32_e32 v40, 0xffff0000, v40
	v_lshlrev_b32_e32 v118, 16, v76
	v_and_b32_e32 v76, 0xffff0000, v76
	s_waitcnt lgkmcnt(1)
	v_sub_f32_e32 v120, v101, v109
	v_add_f32_e32 v101, v101, v109
	v_sub_f32_e32 v109, v40, v76
	v_add_f32_e32 v119, v100, v108
	v_mul_f32_e32 v120, 0.5, v120
	v_sub_f32_e32 v100, v100, v108
	v_add_f32_e32 v108, v118, v77
	v_mul_f32_e32 v109, 0.5, v109
	v_sub_f32_e32 v77, v77, v118
	v_mul_f32_e32 v119, 0.5, v119
	v_mul_f32_e32 v108, 0.5, v108
	v_add_f32_e32 v40, v76, v40
	v_mul_f32_e32 v76, -0.5, v77
	v_mul_f32_e32 v77, v109, v120
	v_mul_f32_e32 v101, 0.5, v101
	v_mul_f32_e32 v100, -0.5, v100
	v_fma_f32 v77, v108, v119, -v77
	v_mul_f32_e32 v108, v108, v120
	v_add_u32_e32 v114, v98, v111
	v_cndmask_b32_e64 v111, 64, v243, s[8:9]
	v_mul_f32_e32 v40, 0.5, v40
	v_fmac_f32_e32 v108, v109, v119
	v_mul_f32_e32 v109, v76, v100
	v_mul_f32_e32 v76, v76, v101
	v_add_u32_e32 v116, v98, v111
	v_fmac_f32_e32 v76, v40, v100
	v_cndmask_b32_e32 v100, v72, v73, vcc
	ds_read_b64 v[110:111], v110
	ds_read_b64 v[114:115], v114
	ds_read_b64 v[116:117], v116
	v_cndmask_b32_e64 v100, v100, v74, s[10:11]
	v_cndmask_b32_e64 v100, v100, v75, s[12:13]
	v_fma_f32 v109, v40, v101, -v109
	v_lshlrev_b32_e32 v40, 16, v41
	v_and_b32_e32 v41, 0xffff0000, v41
	v_lshlrev_b32_e32 v101, 16, v100
	v_and_b32_e32 v100, 0xffff0000, v100
	v_sub_f32_e32 v76, v77, v76
	v_add_f32_e32 v77, v108, v109
	s_waitcnt lgkmcnt(2)
	v_add_f32_e32 v108, v102, v110
	v_sub_f32_e32 v109, v103, v111
	v_sub_f32_e32 v102, v102, v110
	v_add_f32_e32 v103, v103, v111
	v_add_f32_e32 v110, v101, v40
	v_sub_f32_e32 v111, v41, v100
	v_mul_f32_e32 v109, 0.5, v109
	v_mul_f32_e32 v110, 0.5, v110
	v_mul_f32_e32 v111, 0.5, v111
	v_sub_f32_e32 v40, v40, v101
	v_mul_f32_e32 v108, 0.5, v108
	v_mul_f32_e32 v102, -0.5, v102
	v_add_f32_e32 v41, v100, v41
	v_mul_f32_e32 v40, -0.5, v40
	v_mul_f32_e32 v100, v111, v109
	v_mul_f32_e32 v101, v110, v109
	v_mul_f32_e32 v103, 0.5, v103
	v_mul_f32_e32 v41, 0.5, v41
	v_fma_f32 v100, v110, v108, -v100
	v_fmac_f32_e32 v101, v111, v108
	v_mul_f32_e32 v108, v40, v102
	v_fma_f32 v108, v41, v103, -v108
	v_mul_f32_e32 v40, v40, v103
	v_fmac_f32_e32 v40, v41, v102
	v_add_f32_e32 v41, v101, v108
	v_cndmask_b32_e64 v101, v72, v73, s[14:15]
	v_cndmask_b32_e64 v74, v101, v74, s[16:17]
	v_cndmask_b32_e64 v74, v74, v75, s[18:19]
	v_sub_f32_e32 v40, v100, v40
	v_lshlrev_b32_e32 v100, 16, v42
	v_and_b32_e32 v42, 0xffff0000, v42
	v_lshlrev_b32_e32 v75, 16, v74
	v_and_b32_e32 v74, 0xffff0000, v74
	s_waitcnt lgkmcnt(1)
	v_add_f32_e32 v101, v104, v114
	v_sub_f32_e32 v102, v105, v115
	v_sub_f32_e32 v103, v104, v114
	v_add_f32_e32 v104, v105, v115
	v_add_f32_e32 v105, v75, v100
	v_sub_f32_e32 v108, v42, v74
	v_mul_f32_e32 v102, 0.5, v102
	v_mul_f32_e32 v105, 0.5, v105
	v_mul_f32_e32 v108, 0.5, v108
	v_sub_f32_e32 v75, v100, v75
	v_mul_f32_e32 v101, 0.5, v101
	v_mul_f32_e32 v104, 0.5, v104
	v_mul_f32_e32 v103, -0.5, v103
	v_add_f32_e32 v42, v74, v42
	v_mul_f32_e32 v74, -0.5, v75
	v_mul_f32_e32 v75, v108, v102
	v_mul_f32_e32 v100, v105, v102
	v_mul_f32_e32 v42, 0.5, v42
	v_fma_f32 v75, v105, v101, -v75
	v_fmac_f32_e32 v100, v108, v101
	v_mul_f32_e32 v101, v74, v103
	v_mul_f32_e32 v74, v74, v104
	v_fma_f32 v101, v42, v104, -v101
	v_fmac_f32_e32 v74, v42, v103
	v_cndmask_b32_e64 v73, v72, v73, s[20:21]
	v_sub_f32_e32 v74, v75, v74
	v_add_f32_e32 v75, v100, v101
	v_lshlrev_b32_e32 v42, 16, v43
	v_and_b32_e32 v43, 0xffff0000, v43
	v_lshlrev_b32_e32 v101, 16, v73
	v_and_b32_e32 v73, 0xffff0000, v73
	s_waitcnt lgkmcnt(0)
; __device__ __forceinline__ float2 cmul(float2 a, float2 b) { return make_float2(a.x * b.x - a.y * b.y, a.x * b.y + a.y * b.x); }
; __device__ __forceinline__ float2 csub(float2 a, float2 b) { return make_float2(a.x - b.x, a.y - b.y); }
; __device__ __forceinline__ float2 unpack_h2(unsigned w) { return make_float2(__uint_as_float(w << 16), __uint_as_float(w & 0xffff0000u)); }
; template <int MODE> __device__ __forceinline__ void hyena_unit(KP p, int pair, float2* X, int wave_id) {
;     ...
;         float2 wr[32];
; #pragma unroll
;         for (int i = 0; i < 8; ++i) {
;           const u32x4 kp = kpv[i];
; #pragma unroll
;           for (int k = 0; k < 4; ++k) {
;             const int c = 4 * i + k;
;             const int e1 = 31 - c, e2 = (32 - c) & 31;
;             const float2 Zp = xc[c]; float2 Zq = xq[special ? e2 : e1]; Zq.y = -Zq.y;
;             const float2 Kp = unpack_h2(kp[k]);
;             float2 Kq = unpack_h2(special ? kq[e2 >> 2][e2 & 3] : kq[e1 >> 2][e1 & 3]); Kq.y = -Kq.y;
;             const float2 Ua = make_float2(0.5f * (Zp.x + Zq.x), 0.5f * (Zp.y + Zq.y));
;             const float2 dz = csub(Zp, Zq); const float2 Ub = make_float2(0.5f * dz.y, -0.5f * dz.x);
;             const float2 Ka = make_float2(0.5f * (Kp.x + Kq.x), 0.5f * (Kp.y + Kq.y));
;             const float2 dk = csub(Kp, Kq); const float2 Kb = make_float2(0.5f * dk.y, -0.5f * dk.x);
;             const float2 P = cmul(Ua, Ka), Q = cmul(Ub, Kb);
;             wr[c] = make_float2(P.x - Q.y, P.y + Q.x);
;           }
;         }
	v_add_f32_e32 v102, v106, v116
	v_sub_f32_e32 v103, v107, v117
	v_sub_f32_e32 v104, v106, v116
	v_add_f32_e32 v105, v107, v117
	v_add_f32_e32 v106, v101, v42
	v_sub_f32_e32 v107, v43, v73
	v_mul_f32_e32 v103, 0.5, v103
	v_mul_f32_e32 v106, 0.5, v106
	v_mul_f32_e32 v107, 0.5, v107
	v_sub_f32_e32 v42, v42, v101
	v_mul_f32_e32 v102, 0.5, v102
	v_mul_f32_e32 v105, 0.5, v105
	v_mul_f32_e32 v104, -0.5, v104
	v_add_f32_e32 v43, v73, v43
	v_mul_f32_e32 v42, -0.5, v42
	v_mul_f32_e32 v73, v107, v103
	v_mul_f32_e32 v101, v106, v103
	v_mul_f32_e32 v43, 0.5, v43
	v_fma_f32 v73, v106, v102, -v73
	v_fmac_f32_e32 v101, v107, v102
	v_mul_f32_e32 v102, v42, v104
	v_mul_f32_e32 v42, v42, v105
	v_cndmask_b32_e64 v100, 56, 64, s[8:9]
	v_fmac_f32_e32 v42, v43, v104
	v_sub_f32_e32 v42, v73, v42
	v_add_u32_e32 v73, v98, v100
	v_fma_f32 v102, v43, v105, -v102
	ds_read_b64 v[108:109], v73
	v_cndmask_b32_e64 v100, 48, 56, s[8:9]
	v_add_f32_e32 v43, v101, v102
	v_add_u32_e32 v110, v98, v100
	ds_read2_b64 v[100:103], v142 offset0:24 offset1:25
	ds_read2_b64 v[104:107], v142 offset0:26 offset1:27
	v_cndmask_b32_e64 v72, v71, v72, s[8:9]
	v_lshlrev_b32_e32 v73, 16, v36
	v_and_b32_e32 v36, 0xffff0000, v36
	v_lshlrev_b32_e32 v118, 16, v72
	v_and_b32_e32 v72, 0xffff0000, v72
	s_waitcnt lgkmcnt(1)
	v_sub_f32_e32 v120, v101, v109
	v_add_f32_e32 v101, v101, v109
	v_sub_f32_e32 v109, v36, v72
	v_add_f32_e32 v119, v100, v108
	v_mul_f32_e32 v120, 0.5, v120
	v_sub_f32_e32 v100, v100, v108
	v_add_f32_e32 v108, v118, v73
	v_mul_f32_e32 v109, 0.5, v109
	v_sub_f32_e32 v73, v73, v118
	v_mul_f32_e32 v119, 0.5, v119
	v_mul_f32_e32 v108, 0.5, v108
	v_add_f32_e32 v36, v72, v36
	v_mul_f32_e32 v72, -0.5, v73
	v_mul_f32_e32 v73, v109, v120
	v_cndmask_b32_e64 v111, 40, 48, s[8:9]
	v_mul_f32_e32 v101, 0.5, v101
	v_mul_f32_e32 v100, -0.5, v100
	v_fma_f32 v73, v108, v119, -v73
	v_mul_f32_e32 v108, v108, v120
	v_add_u32_e32 v114, v98, v111
	v_cndmask_b32_e64 v111, 32, 40, s[8:9]
	v_mul_f32_e32 v36, 0.5, v36
	v_fmac_f32_e32 v108, v109, v119
	v_mul_f32_e32 v109, v72, v100
	v_mul_f32_e32 v72, v72, v101
	v_add_u32_e32 v116, v98, v111
	v_fmac_f32_e32 v72, v36, v100
	v_cndmask_b32_e32 v100, v68, v69, vcc
	ds_read_b64 v[110:111], v110
	ds_read_b64 v[114:115], v114
	ds_read_b64 v[116:117], v116
	v_cndmask_b32_e64 v100, v100, v70, s[10:11]
	v_cndmask_b32_e64 v100, v100, v71, s[12:13]
	v_fma_f32 v109, v36, v101, -v109
	v_lshlrev_b32_e32 v36, 16, v37
	v_and_b32_e32 v37, 0xffff0000, v37
	v_lshlrev_b32_e32 v101, 16, v100
	v_and_b32_e32 v100, 0xffff0000, v100
	v_sub_f32_e32 v72, v73, v72
	v_add_f32_e32 v73, v108, v109
	s_waitcnt lgkmcnt(2)
	v_add_f32_e32 v108, v102, v110
	v_sub_f32_e32 v109, v103, v111
	v_sub_f32_e32 v102, v102, v110
	v_add_f32_e32 v103, v103, v111
	v_add_f32_e32 v110, v101, v36
	v_sub_f32_e32 v111, v37, v100
	v_mul_f32_e32 v109, 0.5, v109
	v_mul_f32_e32 v110, 0.5, v110
	v_mul_f32_e32 v111, 0.5, v111
	v_sub_f32_e32 v36, v36, v101
	v_mul_f32_e32 v108, 0.5, v108
	v_mul_f32_e32 v102, -0.5, v102
	v_add_f32_e32 v37, v100, v37
	v_mul_f32_e32 v36, -0.5, v36
	v_mul_f32_e32 v100, v111, v109
	v_mul_f32_e32 v101, v110, v109
	v_mul_f32_e32 v103, 0.5, v103
	v_mul_f32_e32 v37, 0.5, v37
	v_fma_f32 v100, v110, v108, -v100
	v_fmac_f32_e32 v101, v111, v108
	v_mul_f32_e32 v108, v36, v102
	v_fma_f32 v108, v37, v103, -v108
	v_mul_f32_e32 v36, v36, v103
	v_fmac_f32_e32 v36, v37, v102
	v_add_f32_e32 v37, v101, v108
	v_cndmask_b32_e64 v101, v68, v69, s[14:15]
	v_cndmask_b32_e64 v70, v101, v70, s[16:17]
	v_cndmask_b32_e64 v70, v70, v71, s[18:19]
	v_sub_f32_e32 v36, v100, v36
	v_lshlrev_b32_e32 v100, 16, v38
	v_and_b32_e32 v38, 0xffff0000, v38
	v_lshlrev_b32_e32 v71, 16, v70
	v_and_b32_e32 v70, 0xffff0000, v70
	s_waitcnt lgkmcnt(1)
	v_add_f32_e32 v101, v104, v114
	v_sub_f32_e32 v102, v105, v115
	v_sub_f32_e32 v103, v104, v114
	v_add_f32_e32 v104, v105, v115
	v_add_f32_e32 v105, v71, v100
	v_sub_f32_e32 v108, v38, v70
	v_mul_f32_e32 v102, 0.5, v102
	v_mul_f32_e32 v105, 0.5, v105
	v_mul_f32_e32 v108, 0.5, v108
	v_sub_f32_e32 v71, v100, v71
	v_mul_f32_e32 v101, 0.5, v101
	v_mul_f32_e32 v104, 0.5, v104
	v_mul_f32_e32 v103, -0.5, v103
	v_add_f32_e32 v38, v70, v38
	v_mul_f32_e32 v70, -0.5, v71
	v_mul_f32_e32 v71, v108, v102
	v_mul_f32_e32 v100, v105, v102
	v_mul_f32_e32 v38, 0.5, v38
	v_fma_f32 v71, v105, v101, -v71
	v_fmac_f32_e32 v100, v108, v101
	v_mul_f32_e32 v101, v70, v103
	v_mul_f32_e32 v70, v70, v104
	v_fma_f32 v101, v38, v104, -v101
	v_fmac_f32_e32 v70, v38, v103
	v_cndmask_b32_e64 v69, v68, v69, s[20:21]
	v_sub_f32_e32 v70, v71, v70
	v_add_f32_e32 v71, v100, v101
	v_lshlrev_b32_e32 v38, 16, v39
	v_and_b32_e32 v39, 0xffff0000, v39
	v_lshlrev_b32_e32 v101, 16, v69
	v_and_b32_e32 v69, 0xffff0000, v69
	s_waitcnt lgkmcnt(0)
	v_add_f32_e32 v102, v106, v116
	v_sub_f32_e32 v103, v107, v117
	v_sub_f32_e32 v104, v106, v116
	v_add_f32_e32 v105, v107, v117
	v_add_f32_e32 v106, v101, v38
	v_sub_f32_e32 v107, v39, v69
	v_mul_f32_e32 v103, 0.5, v103
	v_mul_f32_e32 v106, 0.5, v106
	v_mul_f32_e32 v107, 0.5, v107
	v_sub_f32_e32 v38, v38, v101
	v_mul_f32_e32 v102, 0.5, v102
	v_mul_f32_e32 v105, 0.5, v105
	v_mul_f32_e32 v104, -0.5, v104
	v_add_f32_e32 v39, v69, v39
	v_mul_f32_e32 v38, -0.5, v38
	v_mul_f32_e32 v69, v107, v103
	v_mul_f32_e32 v101, v106, v103
	v_mul_f32_e32 v39, 0.5, v39
	v_fma_f32 v69, v106, v102, -v69
	v_fmac_f32_e32 v101, v107, v102
	v_mul_f32_e32 v102, v38, v104
	v_mul_f32_e32 v38, v38, v105
	v_cndmask_b32_e64 v100, 24, 32, s[8:9]
	v_fmac_f32_e32 v38, v39, v104
	v_sub_f32_e32 v38, v69, v38
	v_add_u32_e32 v69, v98, v100
	v_fma_f32 v102, v39, v105, -v102
	ds_read_b64 v[108:109], v69
	v_add_f32_e32 v39, v101, v102
	ds_read2_b64 v[100:103], v142 offset0:28 offset1:29
	ds_read2_b64 v[104:107], v142 offset0:30 offset1:31
	v_cndmask_b32_e64 v68, v67, v68, s[8:9]
	v_lshlrev_b32_e32 v114, 16, v32
	v_and_b32_e32 v32, 0xffff0000, v32
	v_and_b32_e32 v116, 0xffff0000, v68
	v_lshlrev_b32_e32 v115, 16, v68
	s_waitcnt lgkmcnt(1)
; __device__ __forceinline__ float2 cmul(float2 a, float2 b) { return make_float2(a.x * b.x - a.y * b.y, a.x * b.y + a.y * b.x); }
; __device__ __forceinline__ float2 csub(float2 a, float2 b) { return make_float2(a.x - b.x, a.y - b.y); }
; __device__ __forceinline__ float2 unpack_h2(unsigned w) { return make_float2(__uint_as_float(w << 16), __uint_as_float(w & 0xffff0000u)); }
; template <int MODE> __device__ __forceinline__ void hyena_unit(KP p, int pair, float2* X, int wave_id) {
;     ...
;         float2 wr[32];
; #pragma unroll
;         for (int i = 0; i < 8; ++i) {
;           const u32x4 kp = kpv[i];
; #pragma unroll
;           for (int k = 0; k < 4; ++k) {
;             const int c = 4 * i + k;
;             const int e1 = 31 - c, e2 = (32 - c) & 31;
;             const float2 Zp = xc[c]; float2 Zq = xq[special ? e2 : e1]; Zq.y = -Zq.y;
;             const float2 Kp = unpack_h2(kp[k]);
;             float2 Kq = unpack_h2(special ? kq[e2 >> 2][e2 & 3] : kq[e1 >> 2][e1 & 3]); Kq.y = -Kq.y;
;             const float2 Ua = make_float2(0.5f * (Zp.x + Zq.x), 0.5f * (Zp.y + Zq.y));
;             const float2 dz = csub(Zp, Zq); const float2 Ub = make_float2(0.5f * dz.y, -0.5f * dz.x);
;             const float2 Ka = make_float2(0.5f * (Kp.x + Kq.x), 0.5f * (Kp.y + Kq.y));
;             const float2 dk = csub(Kp, Kq); const float2 Kb = make_float2(0.5f * dk.y, -0.5f * dk.x);
;             const float2 P = cmul(Ua, Ka), Q = cmul(Ub, Kb);
;             wr[c] = make_float2(P.x - Q.y, P.y + Q.x);
;           }
;         }
;         __syncthreads();
; #pragma unroll
;         for (int c = 0; c < 32; ++c) xc[c] = wr[c];
;       }
;       __syncthreads();
	v_sub_f32_e32 v118, v101, v109
	v_add_f32_e32 v101, v101, v109
	v_sub_f32_e32 v109, v32, v116
	v_add_f32_e32 v117, v100, v108
	v_mul_f32_e32 v118, 0.5, v118
	v_sub_f32_e32 v100, v100, v108
	v_add_f32_e32 v108, v115, v114
	v_mul_f32_e32 v109, 0.5, v109
	v_mul_f32_e32 v117, 0.5, v117
	v_mul_f32_e32 v108, 0.5, v108
	v_sub_f32_e32 v114, v114, v115
	v_mul_f32_e32 v115, v109, v118
	v_mul_f32_e32 v100, -0.5, v100
	v_add_f32_e32 v32, v116, v32
	v_mul_f32_e32 v114, -0.5, v114
	v_fma_f32 v115, v108, v117, -v115
	v_mul_f32_e32 v108, v108, v118
	v_mul_f32_e32 v101, 0.5, v101
	v_mul_f32_e32 v32, 0.5, v32
	v_fmac_f32_e32 v108, v109, v117
	v_mul_f32_e32 v109, v114, v100
	v_cndmask_b32_e64 v69, 16, 24, s[8:9]
	v_fma_f32 v109, v32, v101, -v109
	v_mul_f32_e32 v101, v114, v101
	v_add_u32_e32 v68, v98, v69
	v_cndmask_b32_e64 v69, 8, 16, s[8:9]
	v_fmac_f32_e32 v101, v32, v100
	v_add_u32_e32 v110, v98, v69
	v_lshl_add_u32 v111, v99, 3, v98
	v_sub_f32_e32 v100, v115, v101
	v_add_f32_e32 v101, v108, v109
	v_cndmask_b32_e32 v108, v64, v65, vcc
	ds_read_b64 v[68:69], v68
	ds_read_b64 v[98:99], v110
	ds_read_b64 v[110:111], v111
	v_cndmask_b32_e64 v108, v108, v66, s[10:11]
	v_cndmask_b32_e64 v108, v108, v67, s[12:13]
	v_lshlrev_b32_e32 v32, 16, v33
	v_and_b32_e32 v33, 0xffff0000, v33
	v_lshlrev_b32_e32 v109, 16, v108
	v_and_b32_e32 v108, 0xffff0000, v108
	s_waitcnt lgkmcnt(2)
	v_sub_f32_e32 v115, v103, v69
	v_add_f32_e32 v69, v103, v69
	v_sub_f32_e32 v103, v33, v108
	v_add_f32_e32 v114, v102, v68
	v_mul_f32_e32 v115, 0.5, v115
	v_sub_f32_e32 v68, v102, v68
	v_add_f32_e32 v102, v109, v32
	v_mul_f32_e32 v103, 0.5, v103
	v_mul_f32_e32 v114, 0.5, v114
	v_mul_f32_e32 v102, 0.5, v102
	v_sub_f32_e32 v32, v32, v109
	v_add_f32_e32 v33, v108, v33
	v_mul_f32_e32 v108, v103, v115
	v_mul_f32_e32 v68, -0.5, v68
	v_mul_f32_e32 v32, -0.5, v32
	v_fma_f32 v108, v102, v114, -v108
	v_mul_f32_e32 v102, v102, v115
	v_mul_f32_e32 v69, 0.5, v69
	v_mul_f32_e32 v33, 0.5, v33
	v_fmac_f32_e32 v102, v103, v114
	v_mul_f32_e32 v103, v32, v68
	v_fma_f32 v103, v33, v69, -v103
	v_mul_f32_e32 v32, v32, v69
	v_cndmask_b32_e64 v69, v64, v65, s[14:15]
	v_cndmask_b32_e64 v66, v69, v66, s[16:17]
	v_cndmask_b32_e64 v66, v66, v67, s[18:19]
	v_fmac_f32_e32 v32, v33, v68
	v_lshlrev_b32_e32 v68, 16, v34
	v_and_b32_e32 v34, 0xffff0000, v34
	v_lshlrev_b32_e32 v67, 16, v66
	v_and_b32_e32 v66, 0xffff0000, v66
	v_add_f32_e32 v33, v102, v103
	s_waitcnt lgkmcnt(1)
	v_add_f32_e32 v69, v104, v98
	v_sub_f32_e32 v102, v105, v99
	v_sub_f32_e32 v98, v104, v98
	v_add_f32_e32 v103, v67, v68
	v_sub_f32_e32 v104, v34, v66
	v_mul_f32_e32 v102, 0.5, v102
	v_add_f32_e32 v99, v105, v99
	v_mul_f32_e32 v103, 0.5, v103
	v_mul_f32_e32 v104, 0.5, v104
	v_sub_f32_e32 v67, v68, v67
	v_mul_f32_e32 v69, 0.5, v69
	v_mul_f32_e32 v99, 0.5, v99
	v_mul_f32_e32 v98, -0.5, v98
	v_add_f32_e32 v34, v66, v34
	v_mul_f32_e32 v66, -0.5, v67
	v_mul_f32_e32 v67, v104, v102
	v_mul_f32_e32 v68, v103, v102
	v_mul_f32_e32 v34, 0.5, v34
	v_fma_f32 v67, v103, v69, -v67
	v_fmac_f32_e32 v68, v104, v69
	v_mul_f32_e32 v69, v66, v98
	v_mul_f32_e32 v66, v66, v99
	v_cndmask_b32_e64 v64, v64, v65, s[20:21]
	v_fma_f32 v69, v34, v99, -v69
	v_fmac_f32_e32 v66, v34, v98
	v_lshlrev_b32_e32 v34, 16, v35
	v_and_b32_e32 v35, 0xffff0000, v35
	v_lshlrev_b32_e32 v65, 16, v64
	v_and_b32_e32 v64, 0xffff0000, v64
	v_sub_f32_e32 v66, v67, v66
	v_add_f32_e32 v67, v68, v69
	s_waitcnt lgkmcnt(0)
	v_sub_f32_e32 v69, v107, v111
	v_add_f32_e32 v102, v65, v34
	v_sub_f32_e32 v103, v35, v64
	v_add_f32_e32 v68, v106, v110
	v_mul_f32_e32 v69, 0.5, v69
	v_sub_f32_e32 v98, v106, v110
	v_add_f32_e32 v99, v107, v111
	v_mul_f32_e32 v102, 0.5, v102
	v_mul_f32_e32 v103, 0.5, v103
	v_sub_f32_e32 v34, v34, v65
	v_mul_f32_e32 v68, 0.5, v68
	v_mul_f32_e32 v99, 0.5, v99
	v_mul_f32_e32 v98, -0.5, v98
	v_add_f32_e32 v35, v64, v35
	v_mul_f32_e32 v34, -0.5, v34
	v_mul_f32_e32 v64, v103, v69
	v_mul_f32_e32 v65, v102, v69
	v_mul_f32_e32 v35, 0.5, v35
	v_fma_f32 v64, v102, v68, -v64
	v_fmac_f32_e32 v65, v103, v68
	v_mul_f32_e32 v68, v34, v98
	v_mul_f32_e32 v34, v34, v99
	v_fma_f32 v68, v35, v99, -v68
	v_fmac_f32_e32 v34, v35, v98
	v_sub_f32_e32 v32, v108, v32
	v_sub_f32_e32 v34, v64, v34
	v_add_f32_e32 v35, v65, v68
	s_barrier
	ds_write2_b64 v142, v[96:97], v[60:61] offset1:1
	ds_write2_b64 v142, v[94:95], v[62:63] offset0:2 offset1:3
	ds_write2_b64 v142, v[92:93], v[56:57] offset0:4 offset1:5
	ds_write2_b64 v142, v[90:91], v[58:59] offset0:6 offset1:7
	ds_write2_b64 v142, v[88:89], v[52:53] offset0:8 offset1:9
	ds_write2_b64 v142, v[86:87], v[54:55] offset0:10 offset1:11
	ds_write2_b64 v142, v[84:85], v[48:49] offset0:12 offset1:13
	ds_write2_b64 v142, v[82:83], v[50:51] offset0:14 offset1:15
	ds_write2_b64 v142, v[80:81], v[44:45] offset0:16 offset1:17
	ds_write2_b64 v142, v[78:79], v[46:47] offset0:18 offset1:19
	ds_write2_b64 v142, v[76:77], v[40:41] offset0:20 offset1:21
	ds_write2_b64 v142, v[74:75], v[42:43] offset0:22 offset1:23
	ds_write2_b64 v142, v[72:73], v[36:37] offset0:24 offset1:25
	ds_write2_b64 v142, v[70:71], v[38:39] offset0:26 offset1:27
	ds_write2_b64 v142, v[100:101], v[32:33] offset0:28 offset1:29
	ds_write2_b64 v142, v[66:67], v[34:35] offset0:30 offset1:31
	s_waitcnt lgkmcnt(0)
	s_barrier
; __device__ __forceinline__ float2 cmul(float2 a, float2 b) { return make_float2(a.x * b.x - a.y * b.y, a.x * b.y + a.y * b.x); }
; __device__ __forceinline__ float2 cadd(float2 a, float2 b) { return make_float2(a.x + b.x, a.y + b.y); }
; __device__ __forceinline__ float2 csub(float2 a, float2 b) { return make_float2(a.x - b.x, a.y - b.y); }
; template <int R, int LOG, bool INV> __device__ __forceinline__ void reg_fft(float2 (&v)[R]) {
; #pragma unroll
;   for (int st = 0; st < LOG; ++st) {
;     const int ln = R >> st, h = ln >> 1;
; #pragma unroll
;     for (int blk = 0; blk < R; blk += ln)
; #pragma unroll
;       for (int j = 0; j < h; ++j) {
;         const float2 a = v[blk + j], b = v[blk + j + h];
;         v[blk + j] = cadd(a, b);
;         const float2 d = csub(a, b);
;         const int tk = j * (32 / ln);
;         if (tk == 0) v[blk + j + h] = d;
;         else if (tk == 8) v[blk + j + h] = INV ? make_float2(-d.y, d.x) : make_float2(d.y, -d.x);
;         else { const float c = tw32c(tk), s = tw32s(tk); v[blk + j + h] = cmul(d, make_float2(c, INV ? s : -s)); }
;       }
;     __builtin_amdgcn_sched_barrier(0);
;   }
; }
; __device__ __forceinline__ void fft_inv(float2* X, int tid) {
;   {
;     float2* xb = X + 33 * tid;
;     float2 v[32];
; #pragma unroll
;     for (int c = 0; c < 32; ++c) v[c] = xb[c];
;     __builtin_amdgcn_sched_barrier(0);
;     reg_fft<32, 5, true>(v);
; #pragma unroll
;     for (int x = 0; x < 32; ++x) xb[brev_n(x, 5)] = v[x];
;   }
	ds_read2_b64 v[80:83], v142 offset1:1
	ds_read2_b64 v[64:67], v142 offset0:2 offset1:3
	ds_read2_b64 v[40:43], v142 offset0:4 offset1:5
	ds_read2_b64 v[32:35], v142 offset0:6 offset1:7
	ds_read2_b64 v[76:79], v142 offset0:8 offset1:9
	ds_read2_b64 v[68:71], v142 offset0:10 offset1:11
	ds_read2_b64 v[56:59], v142 offset0:12 offset1:13
	ds_read2_b64 v[36:39], v142 offset0:14 offset1:15
	ds_read2_b64 v[92:95], v142 offset0:16 offset1:17
	ds_read2_b64 v[72:75], v142 offset0:18 offset1:19
	ds_read2_b64 v[52:55], v142 offset0:20 offset1:21
	ds_read2_b64 v[44:47], v142 offset0:22 offset1:23
	ds_read2_b64 v[88:91], v142 offset0:24 offset1:25
	ds_read2_b64 v[84:87], v142 offset0:26 offset1:27
	ds_read2_b64 v[60:63], v142 offset0:28 offset1:29
	ds_read2_b64 v[48:51], v142 offset0:30 offset1:31
	s_mov_b32 s33, 0
	s_waitcnt lgkmcnt(6)
	v_pk_add_f32 v[100:101], v[64:65], v[72:73]
	v_pk_add_f32 v[64:65], v[64:65], v[72:73] neg_lo:[0,1] neg_hi:[0,1]
	s_mov_b32 s8, s79
	s_mov_b32 s9, s81
	v_mul_f32_e32 v72, 0x3f6c835e, v65
	s_waitcnt lgkmcnt(2)
	v_pk_add_f32 v[120:121], v[68:69], v[84:85]
	v_pk_add_f32 v[68:69], v[68:69], v[84:85] neg_lo:[0,1] neg_hi:[0,1]
	v_pk_add_f32 v[96:97], v[80:81], v[92:93]
	v_pk_add_f32 v[98:99], v[82:83], v[94:95]
	v_mul_f32_e32 v141, 0x3f6c835e, v64
	v_mul_f32_e32 v159, 0x3ec3ef15, v65
	v_pk_fma_f32 v[64:65], v[64:65], s[8:9], v[72:73] op_sel_hi:[1,1,0]
	v_pk_add_f32 v[102:103], v[66:67], v[74:75]
	v_pk_add_f32 v[104:105], v[40:41], v[52:53]
	v_pk_add_f32 v[106:107], v[42:43], v[54:55]
	v_pk_add_f32 v[108:109], v[32:33], v[44:45]
	v_pk_add_f32 v[110:111], v[34:35], v[46:47]
	v_pk_add_f32 v[116:117], v[76:77], v[88:89]
	v_pk_add_f32 v[72:73], v[76:77], v[88:89] neg_lo:[0,1] neg_hi:[0,1]
	v_pk_add_f32 v[114:115], v[78:79], v[90:91]
	v_mul_f32_e32 v77, 0xbec3ef15, v68
	v_mul_f32_e32 v89, 0x3f6c835e, v69
	v_mul_f32_e32 v152, 0x3f6c835e, v68
	v_mul_f32_e32 v154, 0x3ec3ef15, v69
	v_pk_add_f32 v[68:69], v[70:71], v[86:87]
	s_waitcnt lgkmcnt(1)
	v_pk_add_f32 v[84:85], v[56:57], v[60:61]
	v_pk_add_f32 v[118:119], v[58:59], v[62:63]
	s_waitcnt lgkmcnt(0)
	v_pk_add_f32 v[160:161], v[36:37], v[48:49]
	v_pk_add_f32 v[162:163], v[38:39], v[50:51]
	v_pk_add_f32 v[124:125], v[98:99], v[114:115]
	v_pk_add_f32 v[98:99], v[98:99], v[114:115] neg_lo:[0,1] neg_hi:[0,1]
	v_pk_add_f32 v[170:171], v[106:107], v[118:119]
	v_mul_f32_e32 v72, 0x3f6c835e, v99
	v_pk_add_f32 v[106:107], v[106:107], v[118:119] neg_lo:[0,1] neg_hi:[0,1]
	v_pk_add_f32 v[122:123], v[96:97], v[116:117]
	v_mul_f32_e32 v165, 0x3f6c835e, v98
	v_mul_f32_e32 v167, 0x3ec3ef15, v99
	v_pk_fma_f32 v[98:99], v[98:99], s[8:9], v[72:73] op_sel_hi:[1,1,0]
	v_pk_add_f32 v[114:115], v[100:101], v[120:121]
	v_pk_add_f32 v[126:127], v[102:103], v[68:69]
	v_pk_add_f32 v[128:129], v[104:105], v[84:85]
	v_pk_add_f32 v[168:169], v[104:105], v[84:85] neg_lo:[0,1] neg_hi:[0,1]
	v_mul_f32_e32 v105, 0xbec3ef15, v106
	v_mul_f32_e32 v85, 0x3f6c835e, v107
	v_mul_f32_e32 v106, 0x3f6c835e, v106
	v_mul_f32_e32 v172, 0x3ec3ef15, v107
	v_pk_add_f32 v[118:119], v[108:109], v[160:161]
	v_pk_add_f32 v[174:175], v[110:111], v[162:163]
	v_pk_add_f32 v[130:131], v[122:123], v[128:129]
	v_pk_add_f32 v[132:133], v[124:125], v[170:171]
	v_pk_add_f32 v[134:135], v[114:115], v[118:119]
	v_pk_add_f32 v[136:137], v[126:127], v[174:175]
	v_pk_add_f32 v[148:149], v[130:131], v[134:135]
	v_pk_add_f32 v[130:131], v[130:131], v[134:135] neg_lo:[0,1] neg_hi:[0,1]
	v_pk_add_f32 v[176:177], v[132:133], v[136:137]
	v_pk_add_f32 v[178:179], v[132:133], v[136:137] neg_lo:[0,1] neg_hi:[0,1]
	v_pk_add_f32 v[150:151], v[148:149], v[176:177]
	v_pk_add_f32 v[134:135], v[130:131], v[178:179] op_sel:[0,1] op_sel_hi:[1,0] neg_lo:[0,1] neg_hi:[0,1]
	v_pk_add_f32 v[136:137], v[130:131], v[178:179] op_sel:[1,0] op_sel_hi:[0,1]
	v_pk_add_f32 v[132:133], v[130:131], v[178:179] op_sel:[1,0] op_sel_hi:[0,1] neg_lo:[0,1] neg_hi:[0,1]
	v_pk_add_f32 v[130:131], v[130:131], v[178:179] op_sel:[0,1] op_sel_hi:[1,0]
	v_pk_mov_b32 v[96:97], v[96:97], v[96:97] op_sel:[1,0]
	v_pk_mov_b32 v[116:117], v[116:117], v[116:117] op_sel:[1,0]
	v_mov_b32_e32 v107, v97
	v_mov_b32_e32 v173, v117
	v_mov_b32_e32 v164, v96
	v_pk_add_f32 v[84:85], v[104:105], v[84:85] neg_lo:[0,1] neg_hi:[0,1]
	v_pk_add_f32 v[96:97], v[106:107], v[172:173] neg_lo:[0,1] neg_hi:[0,1]
	v_mov_b32_e32 v104, v108
	v_mov_b32_e32 v105, v102
	v_mov_b32_e32 v106, v160
	v_mov_b32_e32 v107, v68
	v_mov_b32_e32 v102, v109
	v_mov_b32_e32 v68, v161
	v_pk_add_f32 v[104:105], v[104:105], v[106:107] neg_lo:[0,1] neg_hi:[0,1]
	v_pk_add_f32 v[68:69], v[102:103], v[68:69] neg_lo:[0,1] neg_hi:[0,1]
	s_mov_b32 s12, s76
	s_mov_b32 s13, s81
	s_mov_b32 s14, s77
	s_mov_b32 s15, s81
	s_mov_b32 s16, s77
	s_mov_b32 s17, s79
	v_pk_mul_f32 v[102:103], v[104:105], s[12:13]
	v_pk_mul_f32 v[106:107], v[68:69], s[14:15]
	v_pk_mul_f32 v[68:69], v[68:69], s[16:17]
	v_pk_add_f32 v[122:123], v[122:123], v[128:129] neg_lo:[0,1] neg_hi:[0,1]
	v_pk_add_f32 v[114:115], v[114:115], v[118:119] neg_lo:[0,1] neg_hi:[0,1]
	v_mov_b32_e32 v118, v124
	v_mov_b32_e32 v119, v126
	v_mov_b32_e32 v128, v170
	v_mov_b32_e32 v129, v174
	v_mov_b32_e32 v126, v125
	v_mov_b32_e32 v174, v171
	v_pk_add_f32 v[160:161], v[102:103], v[68:69] op_sel:[1,1] op_sel_hi:[0,0] neg_lo:[0,1] neg_hi:[0,1]
	v_pk_add_f32 v[68:69], v[102:103], v[68:69] op_sel:[1,1] op_sel_hi:[0,0]
	v_pk_fma_f32 v[102:103], v[104:105], s[16:17], v[106:107] neg_lo:[0,0,1] neg_hi:[0,0,1]
	v_mov_b32_e32 v105, v110
	v_mov_b32_e32 v107, v162
	v_mov_b32_e32 v110, v101
	v_mov_b32_e32 v162, v121
	v_pk_add_f32 v[118:119], v[118:119], v[128:129] neg_lo:[0,1] neg_hi:[0,1]
; __device__ __forceinline__ float2 cmul(float2 a, float2 b) { return make_float2(a.x * b.x - a.y * b.y, a.x * b.y + a.y * b.x); }
; __device__ __forceinline__ float2 cadd(float2 a, float2 b) { return make_float2(a.x + b.x, a.y + b.y); }
; __device__ __forceinline__ float2 csub(float2 a, float2 b) { return make_float2(a.x - b.x, a.y - b.y); }
; template <int R, int LOG, bool INV> __device__ __forceinline__ void reg_fft(float2 (&v)[R]) {
; #pragma unroll
;   for (int st = 0; st < LOG; ++st) {
;     const int ln = R >> st, h = ln >> 1;
; #pragma unroll
;     for (int blk = 0; blk < R; blk += ln)
; #pragma unroll
;       for (int j = 0; j < h; ++j) {
;         const float2 a = v[blk + j], b = v[blk + j + h];
;         v[blk + j] = cadd(a, b);
;         const float2 d = csub(a, b);
;         const int tk = j * (32 / ln);
;         if (tk == 0) v[blk + j + h] = d;
;         else if (tk == 8) v[blk + j + h] = INV ? make_float2(-d.y, d.x) : make_float2(d.y, -d.x);
;         else { const float c = tw32c(tk), s = tw32s(tk); v[blk + j + h] = cmul(d, make_float2(c, INV ? s : -s)); }
;       }
;     __builtin_amdgcn_sched_barrier(0);
;   }
; }
	v_pk_add_f32 v[124:125], v[126:127], v[174:175] neg_lo:[0,1] neg_hi:[0,1]
	s_mov_b32 s10, s77
	s_mov_b32 s11, s76
	s_mov_b32 s20, s77
	v_mov_b32_e32 v104, v100
	v_mov_b32_e32 v106, v120
	v_pk_add_f32 v[100:101], v[110:111], v[162:163] neg_lo:[0,1] neg_hi:[0,1]
	v_pk_mul_f32 v[126:127], v[118:119], s[10:11]
	v_pk_mul_f32 v[124:125], v[124:125], s[20:21] op_sel_hi:[1,0]
	v_pk_add_f32 v[104:105], v[104:105], v[106:107] neg_lo:[0,1] neg_hi:[0,1]
	s_mov_b32 s18, s77
	s_mov_b32 s19, s80
	v_pk_mul_f32 v[106:107], v[100:101], s[16:17]
	v_pk_add_f32 v[170:171], v[126:127], v[124:125] op_sel:[1,1] op_sel_hi:[0,0]
	v_pk_fma_f32 v[118:119], v[118:119], s[20:21], v[124:125] op_sel_hi:[1,0,1] neg_lo:[0,0,1] neg_hi:[0,0,1]
	v_mov_b32_e32 v166, v116
	v_pk_mul_f32 v[100:101], v[100:101], s[14:15]
	v_pk_fma_f32 v[108:109], v[104:105], s[18:19], v[106:107] neg_lo:[0,0,1] neg_hi:[0,0,1]
	v_pk_fma_f32 v[162:163], v[104:105], s[18:19], v[106:107]
	v_pk_add_f32 v[174:175], v[122:123], v[114:115] op_sel:[0,1] op_sel_hi:[1,0] neg_lo:[0,1] neg_hi:[0,1]
	v_pk_add_f32 v[114:115], v[122:123], v[114:115] op_sel:[0,1] op_sel_hi:[1,0]
	v_sub_f32_e32 v72, v171, v119
	v_pk_add_f32 v[164:165], v[164:165], v[166:167] neg_lo:[0,1] neg_hi:[0,1]
	v_mov_b32_e32 v69, v161
	v_mov_b32_e32 v163, v109
	v_pk_fma_f32 v[100:101], v[104:105], s[16:17], v[100:101] neg_lo:[0,0,1] neg_hi:[0,0,1]
	v_pk_add_f32 v[106:107], v[96:97], v[168:169] neg_lo:[0,1] neg_hi:[0,1]
	v_pk_add_f32 v[110:111], v[96:97], v[98:99]
	v_pk_add_f32 v[148:149], v[148:149], v[176:177] neg_lo:[0,1] neg_hi:[0,1]
	v_pk_add_f32 v[128:129], v[126:127], v[124:125] op_sel:[1,1] op_sel_hi:[0,0] neg_lo:[0,1] neg_hi:[0,1]
	v_mov_b32_e32 v177, v115
	v_pk_add_f32 v[122:123], v[114:115], v[72:73] op_sel_hi:[1,0] neg_lo:[0,1] neg_hi:[0,1]
	v_pk_add_f32 v[114:115], v[114:115], v[72:73] op_sel_hi:[1,0]
	v_pk_add_f32 v[104:105], v[164:165], v[84:85]
	v_mov_b32_e32 v111, v107
	v_sub_f32_e32 v65, v165, v85
	v_sub_f32_e32 v72, v98, v96
	v_pk_add_f32 v[106:107], v[102:103], v[162:163]
	v_pk_add_f32 v[116:117], v[100:101], v[68:69] op_sel:[1,0] op_sel_hi:[0,1]
	v_sub_f32_e32 v68, v68, v101
	v_mov_b32_e32 v129, v171
	v_pk_mov_b32 v[166:167], v[100:101], v[100:101] op_sel:[1,0]
	v_mul_f32_e32 v98, 0x3f3504f3, v65
	v_mul_f32_e32 v170, 0x3f3504f3, v72
	v_sub_f32_e32 v65, v103, v109
	v_mul_f32_e32 v160, 0x3f3504f3, v68
	v_pk_add_f32 v[68:69], v[104:105], v[106:107] neg_lo:[0,1] neg_hi:[0,1]
	v_pk_add_f32 v[100:101], v[110:111], v[116:117] neg_lo:[0,1] neg_hi:[0,1]
	v_pk_add_f32 v[172:173], v[104:105], v[106:107]
	v_pk_add_f32 v[116:117], v[110:111], v[116:117]
	v_mov_b32_e32 v171, v84
	v_mul_f32_e32 v163, 0x3f3504f3, v65
	v_pk_add_f32 v[108:109], v[100:101], v[100:101] op_sel:[1,0] op_sel_hi:[0,1] neg_lo:[0,1] neg_hi:[0,1]
	v_pk_add_f32 v[110:111], v[68:69], v[68:69] op_sel:[0,1] op_sel_hi:[1,0]
	v_pk_add_f32 v[106:107], v[68:69], v[68:69] op_sel:[0,1] op_sel_hi:[1,0] neg_lo:[0,1] neg_hi:[0,1]
	v_pk_add_f32 v[104:105], v[100:101], v[100:101] op_sel:[1,0] op_sel_hi:[0,1]
	v_pk_mov_b32 v[68:69], v[116:117], v[172:173] op_sel:[1,0]
	v_pk_mov_b32 v[100:101], v[172:173], v[116:117] op_sel:[1,0]
	v_mov_b32_e32 v99, v164
	v_mov_b32_e32 v84, v97
	v_mov_b32_e32 v85, v98
	v_pk_mov_b32 v[96:97], v[168:169], v[170:171] op_sel:[1,0]
	v_mov_b32_e32 v103, v160
	v_mul_f32_e32 v166, 0xbf3504f3, v65
	v_pk_add_f32 v[120:121], v[172:173], v[116:117]
	v_pk_add_f32 v[116:117], v[68:69], v[100:101] neg_lo:[0,1] neg_hi:[0,1]
	v_pk_add_f32 v[68:69], v[98:99], v[170:171] neg_lo:[0,1] neg_hi:[0,1]
	v_pk_add_f32 v[84:85], v[84:85], v[96:97]
	v_pk_add_f32 v[98:99], v[162:163], v[102:103] neg_lo:[0,1] neg_hi:[0,1]
	v_pk_add_f32 v[96:97], v[166:167], v[160:161] neg_lo:[0,1] neg_hi:[0,1]
	v_pk_add_f32 v[160:161], v[84:85], v[98:99]
	v_pk_add_f32 v[164:165], v[84:85], v[98:99] neg_lo:[0,1] neg_hi:[0,1]
	v_pk_add_f32 v[100:101], v[68:69], v[96:97] neg_lo:[0,1] neg_hi:[0,1]
	v_pk_add_f32 v[162:163], v[68:69], v[96:97]
	v_mov_b32_e32 v68, v164
	v_mov_b32_e32 v69, v161
	v_pk_add_f32 v[102:103], v[68:69], v[162:163]
	v_pk_add_f32 v[96:97], v[160:161], v[164:165] op_sel:[0,1] op_sel_hi:[1,0] neg_lo:[0,1] neg_hi:[0,1]
	v_pk_add_f32 v[68:69], v[160:161], v[164:165] op_sel:[0,1] op_sel_hi:[1,0]
	v_mov_b32_e32 v165, v163
	v_mov_b32_e32 v163, v161
	v_pk_mov_b32 v[160:161], v[80:81], v[80:81] op_sel:[1,0]
	v_pk_mov_b32 v[92:93], v[92:93], v[92:93] op_sel:[1,0]
	v_mov_b32_e32 v140, v160
	v_mov_b32_e32 v158, v92
	v_pk_add_f32 v[80:81], v[140:141], v[158:159] neg_lo:[0,1] neg_hi:[0,1]
	v_mov_b32_e32 v140, v78
	v_mov_b32_e32 v141, v82
	v_mov_b32_e32 v158, v90
	v_mov_b32_e32 v159, v94
	v_mov_b32_e32 v82, v79
	v_mov_b32_e32 v94, v91
	v_pk_add_f32 v[140:141], v[140:141], v[158:159] neg_lo:[0,1] neg_hi:[0,1]
	v_pk_add_f32 v[78:79], v[82:83], v[94:95] neg_lo:[0,1] neg_hi:[0,1]
	s_mov_b32 s51, s92
	v_pk_mul_f32 v[82:83], v[140:141], s[50:51]
	v_pk_mul_f32 v[90:91], v[78:79], s[64:65] op_sel_hi:[1,0]
	v_pk_mul_f32 v[78:79], v[78:79], s[92:93] op_sel_hi:[1,0]
	v_pk_add_f32 v[94:95], v[82:83], v[90:91] op_sel:[1,1] op_sel_hi:[0,0] neg_lo:[0,1] neg_hi:[0,1]
	v_pk_add_f32 v[82:83], v[82:83], v[90:91] op_sel:[1,1] op_sel_hi:[0,0]
	v_pk_fma_f32 v[90:91], v[140:141], s[64:65], v[78:79] op_sel_hi:[1,0,1] neg_lo:[0,0,1] neg_hi:[0,0,1]
	v_pk_add_f32 v[78:79], v[76:77], v[88:89] neg_lo:[0,1] neg_hi:[0,1]
	v_mov_b32_e32 v155, v93
	v_mov_b32_e32 v88, v70
	v_mov_b32_e32 v89, v66
	v_mov_b32_e32 v92, v86
	v_mov_b32_e32 v93, v74
	v_mov_b32_e32 v66, v71
	v_mov_b32_e32 v74, v87
	v_pk_add_f32 v[88:89], v[88:89], v[92:93] neg_lo:[0,1] neg_hi:[0,1]
	v_pk_add_f32 v[74:75], v[66:67], v[74:75] neg_lo:[0,1] neg_hi:[0,1]
; __device__ __forceinline__ float2 cmul(float2 a, float2 b) { return make_float2(a.x * b.x - a.y * b.y, a.x * b.y + a.y * b.x); }
; __device__ __forceinline__ float2 cadd(float2 a, float2 b) { return make_float2(a.x + b.x, a.y + b.y); }
; __device__ __forceinline__ float2 csub(float2 a, float2 b) { return make_float2(a.x - b.x, a.y - b.y); }
; template <int R, int LOG, bool INV> __device__ __forceinline__ void reg_fft(float2 (&v)[R]) {
; #pragma unroll
;   for (int st = 0; st < LOG; ++st) {
;     const int ln = R >> st, h = ln >> 1;
; #pragma unroll
;     for (int blk = 0; blk < R; blk += ln)
; #pragma unroll
;       for (int j = 0; j < h; ++j) {
;         const float2 a = v[blk + j], b = v[blk + j + h];
;         v[blk + j] = cadd(a, b);
;         const float2 d = csub(a, b);
;         const int tk = j * (32 / ln);
;         if (tk == 0) v[blk + j + h] = d;
;         else if (tk == 8) v[blk + j + h] = INV ? make_float2(-d.y, d.x) : make_float2(d.y, -d.x);
;         else { const float c = tw32c(tk), s = tw32s(tk); v[blk + j + h] = cmul(d, make_float2(c, INV ? s : -s)); }
;       }
;     __builtin_amdgcn_sched_barrier(0);
;   }
; }
	s_mov_b32 s73, s54
	v_pk_mul_f32 v[66:67], v[88:89], s[72:73]
	v_pk_mul_f32 v[86:87], v[74:75], s[58:59] op_sel_hi:[1,0]
	v_pk_mul_f32 v[74:75], v[74:75], s[54:55] op_sel_hi:[1,0]
	v_pk_add_f32 v[70:71], v[66:67], v[86:87] op_sel:[1,1] op_sel_hi:[0,0] neg_lo:[0,1] neg_hi:[0,1]
	v_pk_add_f32 v[66:67], v[66:67], v[86:87] op_sel:[1,1] op_sel_hi:[0,0]
	v_pk_fma_f32 v[74:75], v[88:89], s[58:59], v[74:75] op_sel_hi:[1,0,1] neg_lo:[0,0,1] neg_hi:[0,0,1]
	v_mov_b32_e32 v86, v56
	v_mov_b32_e32 v87, v32
	v_mov_b32_e32 v88, v60
	v_mov_b32_e32 v89, v44
	v_mov_b32_e32 v32, v57
	v_mov_b32_e32 v44, v61
	v_pk_add_f32 v[86:87], v[86:87], v[88:89] neg_lo:[0,1] neg_hi:[0,1]
	v_pk_add_f32 v[32:33], v[32:33], v[44:45] neg_lo:[0,1] neg_hi:[0,1]
	v_pk_mul_f32 v[44:45], v[86:87], s[12:13]
	v_pk_mul_f32 v[56:57], v[32:33], s[14:15]
	v_pk_mul_f32 v[32:33], v[32:33], s[16:17]
	s_mov_b32 s63, s58
	v_pk_add_f32 v[60:61], v[44:45], v[32:33] op_sel:[1,1] op_sel_hi:[0,0] neg_lo:[0,1] neg_hi:[0,1]
	v_pk_add_f32 v[32:33], v[44:45], v[32:33] op_sel:[1,1] op_sel_hi:[0,0]
	v_pk_fma_f32 v[44:45], v[86:87], s[16:17], v[56:57] neg_lo:[0,0,1] neg_hi:[0,0,1]
	v_mov_b32_e32 v56, v58
	v_mov_b32_e32 v57, v42
	v_mov_b32_e32 v86, v62
	v_mov_b32_e32 v87, v54
	v_mov_b32_e32 v42, v59
	v_mov_b32_e32 v54, v63
	v_pk_add_f32 v[56:57], v[56:57], v[86:87] neg_lo:[0,1] neg_hi:[0,1]
	v_pk_add_f32 v[42:43], v[42:43], v[54:55] neg_lo:[0,1] neg_hi:[0,1]
	v_pk_mul_f32 v[54:55], v[56:57], s[62:63]
	v_pk_mul_f32 v[58:59], v[42:43], s[54:55] op_sel_hi:[1,0]
	v_pk_mul_f32 v[42:43], v[42:43], s[58:59] op_sel_hi:[1,0]
	v_pk_add_f32 v[62:63], v[54:55], v[58:59] op_sel:[1,1] op_sel_hi:[0,0] neg_lo:[0,1] neg_hi:[0,1]
	v_pk_add_f32 v[54:55], v[54:55], v[58:59] op_sel:[1,1] op_sel_hi:[0,0]
	v_pk_fma_f32 v[42:43], v[56:57], s[54:55], v[42:43] op_sel_hi:[1,0,1] neg_lo:[0,0,1] neg_hi:[0,0,1]
	v_mov_b32_e32 v57, v36
	v_mov_b32_e32 v59, v48
	v_mov_b32_e32 v36, v41
	v_mov_b32_e32 v48, v53
	v_mov_b32_e32 v56, v40
	v_mov_b32_e32 v58, v52
	v_pk_add_f32 v[36:37], v[36:37], v[48:49] neg_lo:[0,1] neg_hi:[0,1]
	v_pk_add_f32 v[56:57], v[56:57], v[58:59] neg_lo:[0,1] neg_hi:[0,1]
	v_pk_mul_f32 v[40:41], v[36:37], s[16:17]
	v_pk_mul_f32 v[36:37], v[36:37], s[14:15]
	v_pk_fma_f32 v[48:49], v[56:57], s[18:19], v[40:41] neg_lo:[0,0,1] neg_hi:[0,0,1]
	v_pk_fma_f32 v[40:41], v[56:57], s[18:19], v[40:41]
	v_pk_fma_f32 v[36:37], v[56:57], s[16:17], v[36:37] neg_lo:[0,0,1] neg_hi:[0,0,1]
	v_mov_b32_e32 v52, v38
	v_mov_b32_e32 v53, v34
	v_mov_b32_e32 v56, v50
	v_mov_b32_e32 v57, v46
	v_mov_b32_e32 v34, v39
	v_mov_b32_e32 v46, v51
	v_pk_add_f32 v[52:53], v[52:53], v[56:57] neg_lo:[0,1] neg_hi:[0,1]
	v_pk_add_f32 v[34:35], v[34:35], v[46:47] neg_lo:[0,1] neg_hi:[0,1]
	s_mov_b32 s61, s64
	v_mov_b32_e32 v153, v161
	v_pk_mul_f32 v[38:39], v[52:53], s[60:61]
	v_pk_mul_f32 v[46:47], v[34:35], s[92:93] op_sel_hi:[1,0]
	v_pk_add_f32 v[76:77], v[152:153], v[154:155] neg_lo:[0,1] neg_hi:[0,1]
	v_pk_add_f32 v[50:51], v[38:39], v[46:47] op_sel:[1,1] op_sel_hi:[0,0] neg_lo:[0,1] neg_hi:[0,1]
	v_pk_add_f32 v[38:39], v[38:39], v[46:47] op_sel:[1,1] op_sel_hi:[0,0]
	v_pk_mul_f32 v[34:35], v[34:35], s[64:65] op_sel_hi:[1,0]
	v_mov_b32_e32 v65, v73
	v_mov_b32_e32 v83, v95
	v_mov_b32_e32 v67, v71
	v_mov_b32_e32 v33, v61
	v_mov_b32_e32 v55, v63
	v_mov_b32_e32 v41, v49
	v_mov_b32_e32 v39, v51
	v_pk_fma_f32 v[34:35], v[52:53], s[92:93], v[34:35] op_sel_hi:[1,0,1] neg_lo:[0,0,1] neg_hi:[0,0,1]
	v_pk_add_f32 v[86:87], v[76:77], v[64:65] neg_lo:[0,1] neg_hi:[0,1]
	v_pk_add_f32 v[88:89], v[76:77], v[64:65]
	v_pk_add_f32 v[46:47], v[90:91], v[82:83]
	v_sub_f32_e32 v48, v91, v95
	v_sub_f32_e32 v50, v82, v90
	v_pk_add_f32 v[82:83], v[80:81], v[78:79]
	v_mov_b32_e32 v89, v87
	v_pk_add_f32 v[90:91], v[74:75], v[66:67]
	v_pk_add_f32 v[92:93], v[42:43], v[54:55]
	v_pk_add_f32 v[94:95], v[44:45], v[40:41]
	v_pk_add_f32 v[140:141], v[36:37], v[32:33] op_sel:[1,0] op_sel_hi:[0,1]
	v_pk_add_f32 v[152:153], v[34:35], v[38:39]
	v_pk_add_f32 v[98:99], v[100:101], v[100:101] op_sel:[1,0] op_sel_hi:[0,1]
	v_pk_add_f32 v[84:85], v[100:101], v[100:101] op_sel:[1,0] op_sel_hi:[0,1] neg_lo:[0,1] neg_hi:[0,1]
	v_pk_add_f32 v[100:101], v[164:165], v[162:163] neg_lo:[0,1] neg_hi:[0,1]
	v_mul_f32_e32 v53, 0x3f6c835e, v48
	v_mul_f32_e32 v58, 0x3ec3ef15, v48
	v_sub_f32_e32 v48, v43, v63
	v_sub_f32_e32 v42, v54, v42
	v_pk_add_f32 v[154:155], v[46:47], v[92:93]
	v_pk_add_f32 v[158:159], v[82:83], v[94:95]
	v_pk_add_f32 v[160:161], v[88:89], v[140:141]
	v_pk_add_f32 v[162:163], v[90:91], v[152:153]
	v_mul_f32_e32 v43, 0xbec3ef15, v48
	v_mul_f32_e32 v55, 0x3f6c835e, v42
	v_mul_f32_e32 v62, 0x3ec3ef15, v42
	v_pk_add_f32 v[166:167], v[158:159], v[160:161] neg_lo:[0,1] neg_hi:[0,1]
	v_pk_add_f32 v[168:169], v[154:155], v[162:163]
	v_pk_add_f32 v[154:155], v[154:155], v[162:163] neg_lo:[0,1] neg_hi:[0,1]
	v_sub_f32_e32 v42, v161, v159
	v_pk_add_f32 v[164:165], v[158:159], v[160:161]
	v_pk_add_f32 v[158:159], v[42:43], v[154:155] op_sel_hi:[0,1] neg_lo:[0,1] neg_hi:[0,1]
	v_pk_add_f32 v[160:161], v[166:167], v[154:155] op_sel:[0,1] op_sel_hi:[1,0]
	v_pk_add_f32 v[166:167], v[166:167], v[154:155] op_sel:[0,1] op_sel_hi:[1,0] neg_lo:[0,1] neg_hi:[0,1]
	v_pk_add_f32 v[154:155], v[42:43], v[154:155] op_sel_hi:[0,1]
	v_mov_b32_e32 v131, v132
	v_mov_b32_e32 v155, v166
	ds_write2_b64 v142, v[130:131], v[154:155] offset0:24 offset1:25
	v_pk_mov_b32 v[130:131], v[140:141], v[94:95] op_sel:[1,0]
	v_mov_b32_e32 v89, v83
	v_mov_b32_e32 v141, v95
	v_pk_mov_b32 v[86:87], v[86:87], v[82:83] op_sel:[1,0]
	v_pk_add_f32 v[82:83], v[88:89], v[140:141] neg_lo:[0,1] neg_hi:[0,1]
	v_mov_b32_e32 v88, v47
; __device__ __forceinline__ float2 cmul(float2 a, float2 b) { return make_float2(a.x * b.x - a.y * b.y, a.x * b.y + a.y * b.x); }
; __device__ __forceinline__ float2 cadd(float2 a, float2 b) { return make_float2(a.x + b.x, a.y + b.y); }
; __device__ __forceinline__ float2 csub(float2 a, float2 b) { return make_float2(a.x - b.x, a.y - b.y); }
; template <int R, int LOG, bool INV> __device__ __forceinline__ void reg_fft(float2 (&v)[R]) {
; #pragma unroll
;   for (int st = 0; st < LOG; ++st) {
;     const int ln = R >> st, h = ln >> 1;
; #pragma unroll
;     for (int blk = 0; blk < R; blk += ln)
; #pragma unroll
;       for (int j = 0; j < h; ++j) {
;         const float2 a = v[blk + j], b = v[blk + j + h];
;         v[blk + j] = cadd(a, b);
;         const float2 d = csub(a, b);
;         const int tk = j * (32 / ln);
;         if (tk == 0) v[blk + j + h] = d;
;         else if (tk == 8) v[blk + j + h] = INV ? make_float2(-d.y, d.x) : make_float2(d.y, -d.x);
;         else { const float c = tw32c(tk), s = tw32s(tk); v[blk + j + h] = cmul(d, make_float2(c, INV ? s : -s)); }
;       }
;     __builtin_amdgcn_sched_barrier(0);
;   }
; }
; __device__ __forceinline__ void fft_inv(float2* X, int tid) {
;     ...
;     for (int x = 0; x < 32; ++x) xb[brev_n(x, 5)] = v[x];
	v_mov_b32_e32 v89, v91
	v_mov_b32_e32 v94, v93
	v_mov_b32_e32 v95, v153
	v_mov_b32_e32 v47, v90
	v_mov_b32_e32 v93, v152
	v_pk_add_f32 v[88:89], v[88:89], v[94:95] neg_lo:[0,1] neg_hi:[0,1]
	v_pk_add_f32 v[46:47], v[46:47], v[92:93] neg_lo:[0,1] neg_hi:[0,1]
	v_pk_mul_f32 v[90:91], v[88:89], s[10:11]
	v_pk_mul_f32 v[46:47], v[46:47], s[20:21] op_sel_hi:[1,0]
	v_pk_add_f32 v[86:87], v[86:87], v[130:131] neg_lo:[0,1] neg_hi:[0,1]
	v_pk_add_f32 v[92:93], v[90:91], v[46:47] op_sel:[1,1] op_sel_hi:[0,0] neg_lo:[0,1] neg_hi:[0,1]
	v_pk_add_f32 v[90:91], v[90:91], v[46:47] op_sel:[1,1] op_sel_hi:[0,0]
	v_pk_fma_f32 v[46:47], v[88:89], s[20:21], v[46:47] op_sel_hi:[1,0,1] neg_lo:[0,0,1] neg_hi:[0,0,1]
	v_mov_b32_e32 v93, v91
	v_pk_add_f32 v[88:89], v[86:87], v[82:83] neg_lo:[0,1] neg_hi:[0,1]
	v_pk_add_f32 v[82:83], v[86:87], v[82:83]
	v_sub_f32_e32 v42, v91, v47
	v_mov_b32_e32 v87, v83
	v_pk_add_f32 v[94:95], v[46:47], v[92:93]
	v_pk_add_f32 v[92:93], v[46:47], v[92:93] neg_lo:[0,1] neg_hi:[0,1]
	v_pk_add_f32 v[46:47], v[82:83], v[42:43] op_sel_hi:[1,0] neg_lo:[0,1] neg_hi:[0,1]
	v_pk_add_f32 v[82:83], v[82:83], v[42:43] op_sel_hi:[1,0]
	v_mov_b32_e32 v42, v36
	v_mov_b32_e32 v63, v44
	v_mov_b32_e32 v44, v45
	v_mov_b32_e32 v45, v75
	v_mov_b32_e32 v70, v49
	v_mov_b32_e32 v33, v66
	v_pk_mov_b32 v[36:37], v[36:37], v[74:75] op_sel:[1,0]
	v_pk_add_f32 v[44:45], v[44:45], v[70:71] neg_lo:[0,1] neg_hi:[0,1]
	v_pk_add_f32 v[32:33], v[32:33], v[36:37] neg_lo:[0,1] neg_hi:[0,1]
	v_pk_add_f32 v[178:179], v[118:119], v[128:129]
	v_pk_add_f32 v[128:129], v[118:119], v[128:129] neg_lo:[0,1] neg_hi:[0,1]
	v_mul_f32_e32 v60, 0x3f6c835e, v48
	v_mov_b32_e32 v59, v77
	v_mov_b32_e32 v54, v61
	v_pk_mul_f32 v[36:37], v[44:45], s[12:13]
	v_pk_mul_f32 v[48:49], v[32:33], s[14:15]
	v_pk_mul_f32 v[32:33], v[32:33], s[16:17]
	v_mov_b32_e32 v65, v38
	v_mov_b32_e32 v77, v34
	v_pk_add_f32 v[124:125], v[174:175], v[128:129] op_sel:[1,0] op_sel_hi:[0,1]
	v_mul_f32_e32 v57, 0x3ec3ef15, v50
	v_mul_f32_e32 v72, 0x3f6c835e, v50
	v_pk_add_f32 v[90:91], v[88:89], v[92:93] op_sel:[1,0] op_sel_hi:[0,1]
	v_pk_add_f32 v[42:43], v[42:43], v[54:55] neg_lo:[0,1] neg_hi:[0,1]
	v_pk_add_f32 v[54:55], v[36:37], v[32:33] op_sel:[1,1] op_sel_hi:[0,0] neg_lo:[0,1] neg_hi:[0,1]
	v_pk_add_f32 v[32:33], v[36:37], v[32:33] op_sel:[1,1] op_sel_hi:[0,0]
	v_pk_fma_f32 v[36:37], v[44:45], s[16:17], v[48:49] neg_lo:[0,0,1] neg_hi:[0,0,1]
	v_mov_b32_e32 v44, v81
	v_mov_b32_e32 v45, v35
	v_mov_b32_e32 v50, v79
	v_pk_add_f32 v[34:35], v[64:65], v[76:77] neg_lo:[0,1] neg_hi:[0,1]
	v_mov_b32_e32 v123, v124
	v_mov_b32_e32 v47, v90
	v_mov_b32_e32 v52, v80
	v_mov_b32_e32 v56, v78
	v_mov_b32_e32 v61, v40
	v_pk_add_f32 v[44:45], v[44:45], v[50:51] neg_lo:[0,1] neg_hi:[0,1]
	v_pk_mul_f32 v[38:39], v[34:35], s[16:17]
	ds_write2_b64 v142, v[122:123], v[46:47] offset0:12 offset1:13
	v_pk_add_f32 v[46:47], v[52:53], v[56:57] neg_lo:[0,1] neg_hi:[0,1]
	v_pk_add_f32 v[52:53], v[58:59], v[72:73]
	v_pk_add_f32 v[40:41], v[60:61], v[62:63] neg_lo:[0,1] neg_hi:[0,1]
	v_pk_mul_f32 v[34:35], v[34:35], s[14:15]
	v_pk_fma_f32 v[48:49], v[44:45], s[18:19], v[38:39] neg_lo:[0,0,1] neg_hi:[0,0,1]
	v_pk_fma_f32 v[38:39], v[44:45], s[18:19], v[38:39]
	v_mov_b32_e32 v33, v55
	v_mov_b32_e32 v39, v49
	v_pk_fma_f32 v[34:35], v[44:45], s[16:17], v[34:35] neg_lo:[0,0,1] neg_hi:[0,0,1]
	v_pk_add_f32 v[56:57], v[52:53], v[40:41] neg_lo:[0,1] neg_hi:[0,1]
	v_pk_add_f32 v[58:59], v[52:53], v[40:41]
	v_pk_mov_b32 v[44:45], v[34:35], v[34:35] op_sel:[1,0]
	v_pk_add_f32 v[50:51], v[46:47], v[42:43]
	v_mov_b32_e32 v59, v57
	v_pk_add_f32 v[60:61], v[36:37], v[38:39]
	v_pk_add_f32 v[62:63], v[34:35], v[32:33] op_sel:[1,0] op_sel_hi:[0,1]
	v_sub_f32_e32 v33, v37, v49
	v_sub_f32_e32 v32, v32, v35
	v_mul_f32_e32 v44, 0xbf3504f3, v33
	v_mul_f32_e32 v54, 0x3f3504f3, v32
	v_mul_f32_e32 v39, 0x3f3504f3, v33
	v_pk_add_f32 v[32:33], v[50:51], v[60:61] neg_lo:[0,1] neg_hi:[0,1]
	v_pk_add_f32 v[34:35], v[58:59], v[62:63] neg_lo:[0,1] neg_hi:[0,1]
	v_sub_f32_e32 v40, v47, v43
	v_pk_add_f32 v[58:59], v[58:59], v[62:63]
	v_pk_add_f32 v[62:63], v[34:35], v[34:35] op_sel:[1,0] op_sel_hi:[0,1] neg_lo:[0,1] neg_hi:[0,1]
	v_pk_add_f32 v[64:65], v[32:33], v[32:33] op_sel:[0,1] op_sel_hi:[1,0]
	v_pk_add_f32 v[32:33], v[32:33], v[32:33] op_sel:[0,1] op_sel_hi:[1,0] neg_lo:[0,1] neg_hi:[0,1]
	v_pk_add_f32 v[34:35], v[34:35], v[34:35] op_sel:[1,0] op_sel_hi:[0,1]
	v_mul_f32_e32 v48, 0x3f3504f3, v40
	v_mul_f32_e32 v56, 0x3f3504f3, v56
	v_mov_b32_e32 v105, v106
	v_mov_b32_e32 v35, v32
	ds_write2_b64 v142, v[104:105], v[34:35] offset0:26 offset1:27
	v_mov_b32_e32 v34, v53
	v_mov_b32_e32 v35, v48
	v_mov_b32_e32 v40, v41
	v_mov_b32_e32 v41, v56
	v_mov_b32_e32 v37, v54
	v_mov_b32_e32 v49, v46
	v_mov_b32_e32 v57, v42
	v_pk_add_f32 v[34:35], v[34:35], v[40:41]
	v_pk_add_f32 v[36:37], v[38:39], v[36:37] neg_lo:[0,1] neg_hi:[0,1]
	v_pk_add_f32 v[32:33], v[48:49], v[56:57] neg_lo:[0,1] neg_hi:[0,1]
	v_pk_add_f32 v[40:41], v[44:45], v[54:55] neg_lo:[0,1] neg_hi:[0,1]
	v_pk_add_f32 v[42:43], v[34:35], v[36:37]
	v_pk_add_f32 v[34:35], v[34:35], v[36:37] neg_lo:[0,1] neg_hi:[0,1]
	v_pk_add_f32 v[38:39], v[32:33], v[40:41] neg_lo:[0,1] neg_hi:[0,1]
	v_pk_add_f32 v[32:33], v[32:33], v[40:41]
	v_mov_b32_e32 v36, v34
	v_mov_b32_e32 v37, v43
	v_pk_add_f32 v[36:37], v[36:37], v[32:33]
	v_pk_add_f32 v[40:41], v[42:43], v[34:35] op_sel:[0,1] op_sel_hi:[1,0] neg_lo:[0,1] neg_hi:[0,1]
	v_pk_add_f32 v[46:47], v[42:43], v[34:35] op_sel:[0,1] op_sel_hi:[1,0]
	v_mov_b32_e32 v35, v33
	v_mov_b32_e32 v33, v43
	v_pk_add_f32 v[32:33], v[34:35], v[32:33] neg_lo:[0,1] neg_hi:[0,1]
; __device__ __forceinline__ float hw_sin_rev(float r) { return __builtin_amdgcn_sinf(r); }
; __device__ __forceinline__ float hw_cos_rev(float r) { return __builtin_amdgcn_cosf(r); }
; __device__ __forceinline__ float2 cmul(float2 a, float2 b) { return make_float2(a.x * b.x - a.y * b.y, a.x * b.y + a.y * b.x); }
; __device__ __forceinline__ void fft_inv(float2* X, int tid) {
;     ...
;     for (int x = 0; x < 32; ++x) xb[brev_n(x, 5)] = v[x];
;   }
;   __syncthreads();
;   {
;     const int blk = tid >> 5, i = tid & 31;
;     float2* xb = X + blk * 1056 + i;
;     float2 v[32];
;     float rv = (float)i * (1.0f / 1024.0f); asm volatile("" : "+v"(rv));
;     const float2 w1 = make_float2(hw_cos_rev(rv), hw_sin_rev(rv)); float2 w = w1;
;     v[0] = xb[0];
; #pragma unroll
;     for (int r = 1; r < 32; ++r) { v[r] = cmul(xb[33 * r], w); w = cmul(w, w1);  if ((r & 3) == 3) __builtin_amdgcn_sched_barrier(0); }
	v_pk_add_f32 v[162:163], v[164:165], v[168:169]
	v_pk_add_f32 v[50:51], v[50:51], v[60:61]
	ds_write2_b64 v142, v[100:101], v[32:33] offset0:22 offset1:23
	v_lshrrev_b32_e32 v32, 5, v145
	v_and_b32_e32 v33, 31, v156
	v_mov_b32_e32 v170, v163
	v_mov_b32_e32 v171, v162
	v_pk_add_f32 v[60:61], v[50:51], v[58:59]
	v_mul_lo_u32 v32, v32, s74
	v_lshlrev_b32_e32 v34, 3, v33
	v_mov_b32_e32 v176, v174
	v_pk_add_f32 v[118:119], v[174:175], v[128:129] op_sel:[1,0] op_sel_hi:[0,1] neg_lo:[0,1] neg_hi:[0,1]
	ds_write2_b64 v142, v[150:151], v[170:171] offset1:1
	v_pk_add_f32 v[150:151], v[164:165], v[168:169] neg_lo:[0,1] neg_hi:[0,1]
	v_mov_b32_e32 v86, v88
	v_pk_add_f32 v[88:89], v[88:89], v[92:93] op_sel:[1,0] op_sel_hi:[0,1] neg_lo:[0,1] neg_hi:[0,1]
	v_mov_b32_e32 v70, v61
	v_mov_b32_e32 v71, v60
	v_pk_mov_b32 v[60:61], v[58:59], v[50:51] op_sel:[1,0]
	v_pk_mov_b32 v[50:51], v[50:51], v[58:59] op_sel:[1,0]
	v_pk_add_f32 v[44:45], v[38:39], v[38:39] op_sel:[1,0] op_sel_hi:[0,1]
	v_pk_add_f32 v[38:39], v[38:39], v[38:39] op_sel:[1,0] op_sel_hi:[0,1] neg_lo:[0,1] neg_hi:[0,1]
	v_add3_u32 v138, 0, v32, v34
	v_cvt_f32_ubyte0_e32 v32, v33
	v_pk_add_f32 v[126:127], v[176:177], v[178:179]
	v_pk_add_f32 v[128:129], v[176:177], v[178:179] neg_lo:[0,1] neg_hi:[0,1]
	v_mov_b32_e32 v162, v151
	v_mov_b32_e32 v163, v150
	v_mov_b32_e32 v135, v136
	v_mov_b32_e32 v159, v160
	v_pk_add_f32 v[130:131], v[86:87], v[94:95]
	v_pk_add_f32 v[86:87], v[86:87], v[94:95] neg_lo:[0,1] neg_hi:[0,1]
	v_mov_b32_e32 v115, v118
	v_mov_b32_e32 v83, v88
	v_mov_b32_e32 v66, v121
	v_mov_b32_e32 v67, v120
	v_pk_add_f32 v[50:51], v[60:61], v[50:51] neg_lo:[0,1] neg_hi:[0,1]
	v_mov_b32_e32 v109, v110
	v_mov_b32_e32 v63, v64
	v_mov_b32_e32 v97, v98
	v_mov_b32_e32 v41, v44
	v_mov_b32_e32 v69, v84
	v_mov_b32_e32 v47, v38
	v_mul_f32_e32 v32, 0x3a800000, v32
	ds_write2_b64 v142, v[148:149], v[162:163] offset0:16 offset1:17
	ds_write2_b64 v142, v[134:135], v[158:159] offset0:8 offset1:9
	ds_write2_b64 v142, v[126:127], v[130:131] offset0:4 offset1:5
	ds_write2_b64 v142, v[128:129], v[86:87] offset0:20 offset1:21
	ds_write2_b64 v142, v[114:115], v[82:83] offset0:28 offset1:29
	ds_write2_b64 v142, v[66:67], v[70:71] offset0:2 offset1:3
	ds_write2_b64 v142, v[116:117], v[50:51] offset0:18 offset1:19
	ds_write2_b64 v142, v[108:109], v[62:63] offset0:10 offset1:11
	ds_write2_b64 v142, v[102:103], v[36:37] offset0:6 offset1:7
	ds_write2_b64 v142, v[96:97], v[40:41] offset0:14 offset1:15
	ds_write2_b64 v142, v[68:69], v[46:47] offset0:30 offset1:31
	s_waitcnt lgkmcnt(0)
	s_barrier
	ds_read2_b64 v[176:179], v138 offset0:66 offset1:99
	v_sin_f32_e32 v39, v32
	v_cos_f32_e32 v38, v32
	v_mov_b32_e32 v42, v39
	v_pk_mul_f32 v[32:33], v[42:43], v[38:39] op_sel:[0,1] op_sel_hi:[0,0]
	v_pk_fma_f32 v[36:37], v[38:39], v[38:39], v[32:33] op_sel_hi:[1,0,1] neg_lo:[0,0,1] neg_hi:[0,0,1]
	v_pk_fma_f32 v[44:45], v[38:39], v[38:39], v[32:33] op_sel_hi:[1,0,1]
	v_mov_b32_e32 v32, v36
	v_mov_b32_e32 v33, v45
	v_mul_f32_e32 v34, v39, v45
	v_pk_fma_f32 v[40:41], v[38:39], v[32:33], v[34:35] op_sel_hi:[1,1,0] neg_lo:[0,0,1] neg_hi:[0,0,1]
	v_mov_b32_e32 v34, v39
	v_mov_b32_e32 v35, v38
	v_mul_f32_e32 v46, v38, v45
	v_pk_fma_f32 v[46:47], v[34:35], v[32:33], v[46:47] op_sel_hi:[1,1,0]
	v_mov_b32_e32 v33, v40
	v_mov_b32_e32 v32, v46
	v_pk_mul_f32 v[32:33], v[42:43], v[32:33] op_sel_hi:[0,1]
	v_mov_b32_e32 v48, v40
	v_mov_b32_e32 v49, v46
	v_pk_fma_f32 v[54:55], v[38:39], v[48:49], v[32:33] op_sel_hi:[0,1,1] neg_lo:[0,0,1] neg_hi:[0,0,1]
	v_pk_fma_f32 v[172:173], v[38:39], v[48:49], v[32:33] op_sel_hi:[0,1,1]
	v_pk_mov_b32 v[48:49], v[172:173], v[54:55] op_sel:[1,0]
	v_mov_b32_e32 v32, v54
	v_mov_b32_e32 v33, v173
	v_pk_mul_f32 v[48:49], v[42:43], v[48:49] op_sel_hi:[0,1]
	v_pk_fma_f32 v[56:57], v[38:39], v[32:33], v[48:49] op_sel_hi:[0,1,1] neg_lo:[0,0,1] neg_hi:[0,0,1]
	v_pk_fma_f32 v[174:175], v[38:39], v[32:33], v[48:49] op_sel_hi:[0,1,1]
	v_pk_mov_b32 v[48:49], v[174:175], v[56:57] op_sel:[1,0]
	v_mov_b32_e32 v32, v56
	v_mov_b32_e32 v33, v175
	v_pk_mul_f32 v[48:49], v[42:43], v[48:49] op_sel_hi:[0,1]
	v_pk_fma_f32 v[50:51], v[38:39], v[32:33], v[48:49] op_sel_hi:[0,1,1] neg_lo:[0,0,1] neg_hi:[0,0,1]
	v_pk_fma_f32 v[52:53], v[38:39], v[32:33], v[48:49] op_sel_hi:[0,1,1]
	v_mov_b32_e32 v32, v50
	v_mov_b32_e32 v33, v53
	v_mul_f32_e32 v48, v39, v53
	v_pk_fma_f32 v[58:59], v[38:39], v[32:33], v[48:49] op_sel_hi:[1,1,0] neg_lo:[0,0,1] neg_hi:[0,0,1]
	v_mul_f32_e32 v48, v38, v53
	v_pk_fma_f32 v[62:63], v[34:35], v[32:33], v[48:49] op_sel_hi:[1,1,0]
	v_mov_b32_e32 v33, v58
	v_mov_b32_e32 v32, v62
	v_pk_mul_f32 v[32:33], v[42:43], v[32:33] op_sel_hi:[0,1]
	v_mov_b32_e32 v48, v58
	v_mov_b32_e32 v49, v62
	v_pk_fma_f32 v[60:61], v[38:39], v[48:49], v[32:33] op_sel_hi:[0,1,1] neg_lo:[0,0,1] neg_hi:[0,0,1]
	v_pk_fma_f32 v[74:75], v[38:39], v[48:49], v[32:33] op_sel_hi:[0,1,1]
	v_pk_mov_b32 v[48:49], v[74:75], v[60:61] op_sel:[1,0]
	v_mov_b32_e32 v32, v60
	v_mov_b32_e32 v33, v75
	v_pk_mul_f32 v[48:49], v[42:43], v[48:49] op_sel_hi:[0,1]
	v_pk_fma_f32 v[72:73], v[38:39], v[32:33], v[48:49] op_sel_hi:[0,1,1] neg_lo:[0,0,1] neg_hi:[0,0,1]
	v_pk_fma_f32 v[164:165], v[38:39], v[32:33], v[48:49] op_sel_hi:[0,1,1]
	v_pk_mov_b32 v[48:49], v[164:165], v[72:73] op_sel:[1,0]
	v_mov_b32_e32 v32, v72
	v_mov_b32_e32 v33, v165
	v_pk_mul_f32 v[48:49], v[42:43], v[48:49] op_sel_hi:[0,1]
	v_pk_fma_f32 v[64:65], v[38:39], v[32:33], v[48:49] op_sel_hi:[0,1,1] neg_lo:[0,0,1] neg_hi:[0,0,1]
	v_pk_fma_f32 v[68:69], v[38:39], v[32:33], v[48:49] op_sel_hi:[0,1,1]
	v_mov_b32_e32 v32, v64
	v_mov_b32_e32 v33, v69
	v_mul_f32_e32 v48, v39, v69
; __device__ __forceinline__ float hw_sin_rev(float r) { return __builtin_amdgcn_sinf(r); }
; __device__ __forceinline__ float hw_cos_rev(float r) { return __builtin_amdgcn_cosf(r); }
; __device__ __forceinline__ float2 cmul(float2 a, float2 b) { return make_float2(a.x * b.x - a.y * b.y, a.x * b.y + a.y * b.x); }
; __device__ __forceinline__ void fft_inv(float2* X, int tid) {
;     ...
;     float rv = (float)i * (1.0f / 1024.0f); asm volatile("" : "+v"(rv));
;     const float2 w1 = make_float2(hw_cos_rev(rv), hw_sin_rev(rv)); float2 w = w1;
;     v[0] = xb[0];
; #pragma unroll
;     for (int r = 1; r < 32; ++r) { v[r] = cmul(xb[33 * r], w); w = cmul(w, w1);  if ((r & 3) == 3) __builtin_amdgcn_sched_barrier(0); }
	v_pk_fma_f32 v[66:67], v[38:39], v[32:33], v[48:49] op_sel_hi:[1,1,0] neg_lo:[0,0,1] neg_hi:[0,0,1]
	v_mul_f32_e32 v48, v38, v69
	v_pk_fma_f32 v[70:71], v[34:35], v[32:33], v[48:49] op_sel_hi:[1,1,0]
	v_mov_b32_e32 v33, v66
	v_mov_b32_e32 v32, v70
	v_pk_mul_f32 v[32:33], v[42:43], v[32:33] op_sel_hi:[0,1]
	v_mov_b32_e32 v48, v66
	v_mov_b32_e32 v49, v70
	v_pk_fma_f32 v[80:81], v[38:39], v[48:49], v[32:33] op_sel_hi:[0,1,1] neg_lo:[0,0,1] neg_hi:[0,0,1]
	v_pk_fma_f32 v[168:169], v[38:39], v[48:49], v[32:33] op_sel_hi:[0,1,1]
	v_pk_mov_b32 v[48:49], v[168:169], v[80:81] op_sel:[1,0]
	v_mov_b32_e32 v32, v80
	v_mov_b32_e32 v33, v169
	v_pk_mul_f32 v[48:49], v[42:43], v[48:49] op_sel_hi:[0,1]
	v_pk_fma_f32 v[82:83], v[38:39], v[32:33], v[48:49] op_sel_hi:[0,1,1] neg_lo:[0,0,1] neg_hi:[0,0,1]
	v_pk_fma_f32 v[170:171], v[38:39], v[32:33], v[48:49] op_sel_hi:[0,1,1]
	v_pk_mov_b32 v[48:49], v[170:171], v[82:83] op_sel:[1,0]
	v_mov_b32_e32 v32, v82
	v_mov_b32_e32 v33, v171
	v_pk_mul_f32 v[48:49], v[42:43], v[48:49] op_sel_hi:[0,1]
	v_pk_fma_f32 v[76:77], v[38:39], v[32:33], v[48:49] op_sel_hi:[0,1,1] neg_lo:[0,0,1] neg_hi:[0,0,1]
	v_pk_fma_f32 v[78:79], v[38:39], v[32:33], v[48:49] op_sel_hi:[0,1,1]
	v_mov_b32_e32 v32, v76
	v_mov_b32_e32 v33, v79
	v_mul_f32_e32 v48, v39, v79
	v_pk_fma_f32 v[110:111], v[38:39], v[32:33], v[48:49] op_sel_hi:[1,1,0] neg_lo:[0,0,1] neg_hi:[0,0,1]
	v_mul_f32_e32 v48, v38, v79
	v_pk_fma_f32 v[116:117], v[34:35], v[32:33], v[48:49] op_sel_hi:[1,1,0]
	v_mov_b32_e32 v33, v110
	v_mov_b32_e32 v32, v116
	v_pk_mul_f32 v[32:33], v[42:43], v[32:33] op_sel_hi:[0,1]
	v_mov_b32_e32 v48, v110
	v_mov_b32_e32 v49, v116
	v_pk_fma_f32 v[114:115], v[38:39], v[48:49], v[32:33] op_sel_hi:[0,1,1] neg_lo:[0,0,1] neg_hi:[0,0,1]
	v_pk_fma_f32 v[118:119], v[38:39], v[48:49], v[32:33] op_sel_hi:[0,1,1]
	v_pk_mov_b32 v[48:49], v[118:119], v[114:115] op_sel:[1,0]
	v_mov_b32_e32 v32, v114
	v_mov_b32_e32 v33, v119
	v_pk_mul_f32 v[48:49], v[42:43], v[48:49] op_sel_hi:[0,1]
	v_pk_fma_f32 v[156:157], v[38:39], v[32:33], v[48:49] op_sel_hi:[0,1,1] neg_lo:[0,0,1] neg_hi:[0,0,1]
	v_pk_fma_f32 v[166:167], v[38:39], v[32:33], v[48:49] op_sel_hi:[0,1,1]
	v_pk_mov_b32 v[48:49], v[166:167], v[156:157] op_sel:[1,0]
	v_mov_b32_e32 v32, v156
	v_mov_b32_e32 v33, v167
	v_pk_mul_f32 v[48:49], v[42:43], v[48:49] op_sel_hi:[0,1]
	v_pk_fma_f32 v[120:121], v[38:39], v[32:33], v[48:49] op_sel_hi:[0,1,1] neg_lo:[0,0,1] neg_hi:[0,0,1]
	v_pk_fma_f32 v[124:125], v[38:39], v[32:33], v[48:49] op_sel_hi:[0,1,1]
	v_mov_b32_e32 v32, v120
	v_mov_b32_e32 v33, v125
	v_mul_f32_e32 v48, v39, v125
	v_pk_fma_f32 v[122:123], v[38:39], v[32:33], v[48:49] op_sel_hi:[1,1,0] neg_lo:[0,0,1] neg_hi:[0,0,1]
	v_mul_f32_e32 v48, v38, v125
	v_pk_fma_f32 v[154:155], v[34:35], v[32:33], v[48:49] op_sel_hi:[1,1,0]
	v_mov_b32_e32 v33, v122
	v_mov_b32_e32 v32, v154
	v_pk_mul_f32 v[32:33], v[42:43], v[32:33] op_sel_hi:[0,1]
	v_mov_b32_e32 v48, v122
	v_mov_b32_e32 v49, v154
	v_pk_fma_f32 v[126:127], v[38:39], v[48:49], v[32:33] op_sel_hi:[0,1,1] neg_lo:[0,0,1] neg_hi:[0,0,1]
	v_pk_fma_f32 v[160:161], v[38:39], v[48:49], v[32:33] op_sel_hi:[0,1,1]
	v_pk_mov_b32 v[48:49], v[160:161], v[126:127] op_sel:[1,0]
	v_mov_b32_e32 v32, v126
	v_mov_b32_e32 v33, v161
	v_pk_mul_f32 v[48:49], v[42:43], v[48:49] op_sel_hi:[0,1]
	v_pk_fma_f32 v[158:159], v[38:39], v[32:33], v[48:49] op_sel_hi:[0,1,1] neg_lo:[0,0,1] neg_hi:[0,0,1]
	v_pk_fma_f32 v[162:163], v[38:39], v[32:33], v[48:49] op_sel_hi:[0,1,1]
	v_pk_mov_b32 v[48:49], v[162:163], v[158:159] op_sel:[1,0]
	v_mov_b32_e32 v32, v158
	v_mov_b32_e32 v33, v163
	v_pk_mul_f32 v[48:49], v[42:43], v[48:49] op_sel_hi:[0,1]
	v_pk_fma_f32 v[128:129], v[38:39], v[32:33], v[48:49] op_sel_hi:[0,1,1] neg_lo:[0,0,1] neg_hi:[0,0,1]
	v_pk_fma_f32 v[134:135], v[38:39], v[32:33], v[48:49] op_sel_hi:[0,1,1]
	v_mov_b32_e32 v32, v128
	v_mov_b32_e32 v33, v135
	v_mul_f32_e32 v48, v39, v135
	v_pk_fma_f32 v[130:131], v[38:39], v[32:33], v[48:49] op_sel_hi:[1,1,0] neg_lo:[0,0,1] neg_hi:[0,0,1]
	v_mul_f32_e32 v48, v38, v135
	v_pk_fma_f32 v[148:149], v[34:35], v[32:33], v[48:49] op_sel_hi:[1,1,0]
	v_mov_b32_e32 v33, v130
	v_mov_b32_e32 v32, v148
	v_pk_mul_f32 v[32:33], v[42:43], v[32:33] op_sel_hi:[0,1]
	v_mov_b32_e32 v48, v130
	v_mov_b32_e32 v49, v148
	v_pk_fma_f32 v[132:133], v[38:39], v[48:49], v[32:33] op_sel_hi:[0,1,1] neg_lo:[0,0,1] neg_hi:[0,0,1]
	v_pk_fma_f32 v[150:151], v[38:39], v[48:49], v[32:33] op_sel_hi:[0,1,1]
	v_pk_mov_b32 v[48:49], v[150:151], v[132:133] op_sel:[1,0]
	v_mov_b32_e32 v32, v132
	v_mov_b32_e32 v33, v151
	v_pk_mul_f32 v[48:49], v[42:43], v[48:49] op_sel_hi:[0,1]
	v_pk_fma_f32 v[136:137], v[38:39], v[32:33], v[48:49] op_sel_hi:[0,1,1] neg_lo:[0,0,1] neg_hi:[0,0,1]
	v_pk_fma_f32 v[152:153], v[38:39], v[32:33], v[48:49] op_sel_hi:[0,1,1]
	v_pk_mov_b32 v[48:49], v[152:153], v[136:137] op_sel:[1,0]
	v_mov_b32_e32 v32, v136
	v_mov_b32_e32 v33, v153
	v_pk_mul_f32 v[48:49], v[42:43], v[48:49] op_sel_hi:[0,1]
	v_pk_fma_f32 v[94:95], v[38:39], v[32:33], v[48:49] op_sel_hi:[0,1,1] neg_lo:[0,0,1] neg_hi:[0,0,1]
	v_pk_fma_f32 v[98:99], v[38:39], v[32:33], v[48:49] op_sel_hi:[0,1,1]
	v_mov_b32_e32 v32, v94
	v_mov_b32_e32 v33, v99
	v_mul_f32_e32 v48, v39, v99
	v_pk_fma_f32 v[96:97], v[38:39], v[32:33], v[48:49] op_sel_hi:[1,1,0] neg_lo:[0,0,1] neg_hi:[0,0,1]
	v_mul_f32_e32 v48, v38, v99
	v_pk_fma_f32 v[102:103], v[34:35], v[32:33], v[48:49] op_sel_hi:[1,1,0]
	v_mov_b32_e32 v33, v96
	v_mov_b32_e32 v32, v102
	v_pk_mul_f32 v[32:33], v[42:43], v[32:33] op_sel_hi:[0,1]
	v_mov_b32_e32 v48, v96
	v_mov_b32_e32 v49, v102
	v_pk_fma_f32 v[100:101], v[38:39], v[48:49], v[32:33] op_sel_hi:[0,1,1] neg_lo:[0,0,1] neg_hi:[0,0,1]
	v_pk_fma_f32 v[106:107], v[38:39], v[48:49], v[32:33] op_sel_hi:[0,1,1]
	v_pk_mov_b32 v[48:49], v[106:107], v[100:101] op_sel:[1,0]
	v_mov_b32_e32 v32, v100
	v_mov_b32_e32 v33, v107
	v_pk_mul_f32 v[48:49], v[42:43], v[48:49] op_sel_hi:[0,1]
	v_pk_fma_f32 v[104:105], v[38:39], v[32:33], v[48:49] op_sel_hi:[0,1,1] neg_lo:[0,0,1] neg_hi:[0,0,1]
	v_pk_fma_f32 v[108:109], v[38:39], v[32:33], v[48:49] op_sel_hi:[0,1,1]
	v_pk_mov_b32 v[48:49], v[108:109], v[104:105] op_sel:[1,0]
	v_mov_b32_e32 v32, v104
	v_mov_b32_e32 v33, v109
	v_pk_mul_f32 v[48:49], v[42:43], v[48:49] op_sel_hi:[0,1]
	v_pk_fma_f32 v[86:87], v[38:39], v[32:33], v[48:49] op_sel_hi:[0,1,1] neg_lo:[0,0,1] neg_hi:[0,0,1]
	v_pk_fma_f32 v[90:91], v[38:39], v[32:33], v[48:49] op_sel_hi:[0,1,1]
	v_mov_b32_e32 v32, v86
	v_mov_b32_e32 v33, v91
	v_pk_mul_f32 v[84:85], v[38:39], v[32:33]
	v_pk_mul_f32 v[88:89], v[34:35], v[32:33]
	ds_read2_b64 v[32:35], v138 offset1:33
	s_waitcnt lgkmcnt(0)
; __device__ __forceinline__ float2 cmul(float2 a, float2 b) { return make_float2(a.x * b.x - a.y * b.y, a.x * b.y + a.y * b.x); }
; __device__ __forceinline__ void fft_inv(float2* X, int tid) {
;     ...
;     v[0] = xb[0];
; #pragma unroll
;     for (int r = 1; r < 32; ++r) { v[r] = cmul(xb[33 * r], w); w = cmul(w, w1);  if ((r & 3) == 3) __builtin_amdgcn_sched_barrier(0); }
	v_pk_mul_f32 v[48:49], v[42:43], v[34:35] op_sel_hi:[0,1]
	v_pk_fma_f32 v[42:43], v[38:39], v[34:35], v[48:49] op_sel:[0,0,1] op_sel_hi:[0,1,0] neg_lo:[0,0,1] neg_hi:[0,0,1]
	v_pk_fma_f32 v[38:39], v[38:39], v[34:35], v[48:49] op_sel:[0,0,1] op_sel_hi:[0,1,0]
	v_pk_mul_f32 v[34:35], v[44:45], v[176:177] op_sel:[1,1] op_sel_hi:[1,0]
	v_mov_b32_e32 v43, v39
	v_pk_fma_f32 v[92:93], v[36:37], v[176:177], v[34:35] neg_lo:[0,0,1] neg_hi:[0,0,1]
	v_pk_fma_f32 v[34:35], v[36:37], v[176:177], v[34:35] op_sel_hi:[0,1,1]
	v_mov_b32_e32 v93, v35
	v_pk_mul_f32 v[34:35], v[46:47], v[178:179] op_sel:[0,1] op_sel_hi:[0,0]
	v_pk_fma_f32 v[48:49], v[40:41], v[178:179], v[34:35] op_sel_hi:[0,1,1] neg_lo:[0,0,1] neg_hi:[0,0,1]
	v_pk_fma_f32 v[46:47], v[40:41], v[178:179], v[34:35] op_sel_hi:[0,1,1]
	v_mov_b32_e32 v49, v47
	ds_read2_b64 v[176:179], v138 offset0:132 offset1:165
	s_waitcnt lgkmcnt(0)
	v_pk_mul_f32 v[34:35], v[172:173], v[176:177] op_sel:[1,1] op_sel_hi:[1,0]
	v_pk_mul_f32 v[40:41], v[174:175], v[178:179] op_sel:[1,1] op_sel_hi:[1,0]
	ds_read2_b64 v[172:175], v138 offset0:198 offset1:231
	v_pk_fma_f32 v[36:37], v[54:55], v[176:177], v[34:35] op_sel_hi:[0,1,1] neg_lo:[0,0,1] neg_hi:[0,0,1]
	v_pk_fma_f32 v[34:35], v[54:55], v[176:177], v[34:35] op_sel_hi:[0,1,1]
	v_pk_fma_f32 v[44:45], v[56:57], v[178:179], v[40:41] op_sel_hi:[0,1,1] neg_lo:[0,0,1] neg_hi:[0,0,1]
	v_pk_fma_f32 v[40:41], v[56:57], v[178:179], v[40:41] op_sel_hi:[0,1,1]
	s_waitcnt lgkmcnt(0)
	v_pk_mul_f32 v[52:53], v[52:53], v[172:173] op_sel:[1,1] op_sel_hi:[1,0]
	v_mov_b32_e32 v37, v35
	v_pk_fma_f32 v[56:57], v[50:51], v[172:173], v[52:53] op_sel_hi:[0,1,1] neg_lo:[0,0,1] neg_hi:[0,0,1]
	v_pk_fma_f32 v[54:55], v[50:51], v[172:173], v[52:53] op_sel_hi:[0,1,1]
	v_pk_mul_f32 v[50:51], v[62:63], v[174:175] op_sel:[0,1] op_sel_hi:[0,0]
	v_pk_fma_f32 v[52:53], v[58:59], v[174:175], v[50:51] op_sel_hi:[0,1,1] neg_lo:[0,0,1] neg_hi:[0,0,1]
	v_pk_fma_f32 v[50:51], v[58:59], v[174:175], v[50:51] op_sel_hi:[0,1,1]
	v_mov_b32_e32 v45, v41
	v_mov_b32_e32 v57, v55
	v_mov_b32_e32 v53, v51
	v_add_u32_e32 v34, 0x800, v138
	ds_read2_b64 v[172:175], v34 offset0:8 offset1:41
	s_waitcnt lgkmcnt(0)
	v_pk_mul_f32 v[62:63], v[74:75], v[172:173] op_sel:[1,1] op_sel_hi:[1,0]
	s_nop 0
	v_pk_fma_f32 v[58:59], v[60:61], v[172:173], v[62:63] neg_lo:[0,0,1] neg_hi:[0,0,1]
	v_pk_fma_f32 v[60:61], v[60:61], v[172:173], v[62:63] op_sel_hi:[0,1,1]
	v_mov_b32_e32 v59, v61
	v_pk_mul_f32 v[60:61], v[164:165], v[174:175] op_sel:[1,1] op_sel_hi:[1,0]
	s_nop 0
	v_pk_fma_f32 v[62:63], v[72:73], v[174:175], v[60:61] op_sel_hi:[0,1,1] neg_lo:[0,0,1] neg_hi:[0,0,1]
	v_pk_fma_f32 v[60:61], v[72:73], v[174:175], v[60:61] op_sel_hi:[0,1,1]
	ds_read2_b64 v[172:175], v34 offset0:74 offset1:107
	v_mov_b32_e32 v63, v61
	s_waitcnt lgkmcnt(0)
	v_pk_mul_f32 v[68:69], v[68:69], v[172:173] op_sel:[1,1] op_sel_hi:[1,0]
	s_nop 0
	v_pk_fma_f32 v[164:165], v[64:65], v[172:173], v[68:69] neg_lo:[0,0,1] neg_hi:[0,0,1]
	v_pk_fma_f32 v[64:65], v[64:65], v[172:173], v[68:69] op_sel_hi:[0,1,1]
	v_mov_b32_e32 v165, v65
	v_pk_mul_f32 v[64:65], v[70:71], v[174:175] op_sel:[0,1] op_sel_hi:[0,0]
	v_pk_fma_f32 v[74:75], v[66:67], v[174:175], v[64:65] op_sel_hi:[0,1,1] neg_lo:[0,0,1] neg_hi:[0,0,1]
	v_pk_fma_f32 v[72:73], v[66:67], v[174:175], v[64:65] op_sel_hi:[0,1,1]
	v_mov_b32_e32 v75, v73
	ds_read2_b64 v[172:175], v34 offset0:140 offset1:173
	s_waitcnt lgkmcnt(0)
	v_pk_mul_f32 v[64:65], v[168:169], v[172:173] op_sel:[1,1] op_sel_hi:[1,0]
	s_nop 0
	v_pk_fma_f32 v[70:71], v[80:81], v[172:173], v[64:65] op_sel_hi:[0,1,1] neg_lo:[0,0,1] neg_hi:[0,0,1]
	v_pk_fma_f32 v[68:69], v[80:81], v[172:173], v[64:65] op_sel_hi:[0,1,1]
	v_pk_mul_f32 v[64:65], v[170:171], v[174:175] op_sel:[1,1] op_sel_hi:[1,0]
	ds_read2_b64 v[168:171], v34 offset0:206 offset1:239
	v_pk_fma_f32 v[66:67], v[82:83], v[174:175], v[64:65] op_sel_hi:[0,1,1] neg_lo:[0,0,1] neg_hi:[0,0,1]
	v_pk_fma_f32 v[64:65], v[82:83], v[174:175], v[64:65] op_sel_hi:[0,1,1]
	v_mov_b32_e32 v71, v69
	v_mov_b32_e32 v67, v65
	s_waitcnt lgkmcnt(0)
	v_pk_mul_f32 v[78:79], v[78:79], v[168:169] op_sel:[1,1] op_sel_hi:[1,0]
	s_nop 0
	v_pk_fma_f32 v[82:83], v[76:77], v[168:169], v[78:79] op_sel_hi:[0,1,1] neg_lo:[0,0,1] neg_hi:[0,0,1]
	v_pk_fma_f32 v[80:81], v[76:77], v[168:169], v[78:79] op_sel_hi:[0,1,1]
	v_pk_mul_f32 v[76:77], v[116:117], v[170:171] op_sel:[0,1] op_sel_hi:[0,0]
	v_pk_fma_f32 v[78:79], v[110:111], v[170:171], v[76:77] op_sel_hi:[0,1,1] neg_lo:[0,0,1] neg_hi:[0,0,1]
	v_pk_fma_f32 v[76:77], v[110:111], v[170:171], v[76:77] op_sel_hi:[0,1,1]
	v_mov_b32_e32 v83, v81
	v_mov_b32_e32 v79, v77
	v_add_u32_e32 v64, 0x1000, v138
	ds_read2_b64 v[168:171], v64 offset0:16 offset1:49
	s_waitcnt lgkmcnt(0)
	v_pk_mul_f32 v[110:111], v[118:119], v[168:169] op_sel:[1,1] op_sel_hi:[1,0]
	s_nop 0
	v_pk_fma_f32 v[116:117], v[114:115], v[168:169], v[110:111] op_sel_hi:[0,1,1] neg_lo:[0,0,1] neg_hi:[0,0,1]
	v_pk_fma_f32 v[118:119], v[114:115], v[168:169], v[110:111] op_sel_hi:[0,1,1]
	v_pk_mul_f32 v[110:111], v[166:167], v[170:171] op_sel:[1,1] op_sel_hi:[1,0]
	v_mov_b32_e32 v168, v116
	v_pk_fma_f32 v[114:115], v[156:157], v[170:171], v[110:111] op_sel_hi:[0,1,1] neg_lo:[0,0,1] neg_hi:[0,0,1]
	v_pk_fma_f32 v[110:111], v[156:157], v[170:171], v[110:111] op_sel_hi:[0,1,1]
	ds_read2_b64 v[170:173], v64 offset0:82 offset1:115
	v_mov_b32_e32 v169, v119
	v_mov_b32_e32 v115, v111
	s_waitcnt lgkmcnt(0)
; __device__ __forceinline__ float2 cmul(float2 a, float2 b) { return make_float2(a.x * b.x - a.y * b.y, a.x * b.y + a.y * b.x); }
; __device__ __forceinline__ float2 cadd(float2 a, float2 b) { return make_float2(a.x + b.x, a.y + b.y); }
; __device__ __forceinline__ float2 csub(float2 a, float2 b) { return make_float2(a.x - b.x, a.y - b.y); }
; template <int R, int LOG, bool INV> __device__ __forceinline__ void reg_fft(float2 (&v)[R]) {
; #pragma unroll
;   for (int st = 0; st < LOG; ++st) {
;     const int ln = R >> st, h = ln >> 1;
; #pragma unroll
;     for (int blk = 0; blk < R; blk += ln)
; #pragma unroll
;       for (int j = 0; j < h; ++j) {
;         const float2 a = v[blk + j], b = v[blk + j + h];
;         v[blk + j] = cadd(a, b);
;         const float2 d = csub(a, b);
;         const int tk = j * (32 / ln);
;         if (tk == 0) v[blk + j + h] = d;
;         else if (tk == 8) v[blk + j + h] = INV ? make_float2(-d.y, d.x) : make_float2(d.y, -d.x);
;         else { const float c = tw32c(tk), s = tw32s(tk); v[blk + j + h] = cmul(d, make_float2(c, INV ? s : -s)); }
;       }
;     __builtin_amdgcn_sched_barrier(0);
;   }
; }
; __device__ __forceinline__ void fft_inv(float2* X, int tid) {
;     ...
;     for (int r = 1; r < 32; ++r) { v[r] = cmul(xb[33 * r], w); w = cmul(w, w1);  if ((r & 3) == 3) __builtin_amdgcn_sched_barrier(0); }
;     __builtin_amdgcn_sched_barrier(0);
;     reg_fft<32, 5, true>(v);
	v_pk_mul_f32 v[124:125], v[124:125], v[170:171] op_sel:[1,1] op_sel_hi:[1,0]
	s_nop 0
	v_pk_fma_f32 v[166:167], v[120:121], v[170:171], v[124:125] neg_lo:[0,0,1] neg_hi:[0,0,1]
	v_pk_fma_f32 v[120:121], v[120:121], v[170:171], v[124:125] op_sel_hi:[0,1,1]
	v_mov_b32_e32 v167, v121
	v_pk_mul_f32 v[120:121], v[154:155], v[172:173] op_sel:[0,1] op_sel_hi:[0,0]
	v_pk_fma_f32 v[156:157], v[122:123], v[172:173], v[120:121] op_sel_hi:[0,1,1] neg_lo:[0,0,1] neg_hi:[0,0,1]
	v_pk_fma_f32 v[154:155], v[122:123], v[172:173], v[120:121] op_sel_hi:[0,1,1]
	v_mov_b32_e32 v157, v155
	ds_read2_b64 v[170:173], v64 offset0:148 offset1:181
	s_waitcnt lgkmcnt(0)
	v_pk_mul_f32 v[120:121], v[160:161], v[170:171] op_sel:[1,1] op_sel_hi:[1,0]
	v_pk_mul_f32 v[124:125], v[162:163], v[172:173] op_sel:[1,1] op_sel_hi:[1,0]
	v_pk_fma_f32 v[122:123], v[126:127], v[170:171], v[120:121] op_sel_hi:[0,1,1] neg_lo:[0,0,1] neg_hi:[0,0,1]
	v_pk_fma_f32 v[120:121], v[126:127], v[170:171], v[120:121] op_sel_hi:[0,1,1]
	v_pk_fma_f32 v[126:127], v[158:159], v[172:173], v[124:125] op_sel_hi:[0,1,1] neg_lo:[0,0,1] neg_hi:[0,0,1]
	v_pk_fma_f32 v[124:125], v[158:159], v[172:173], v[124:125] op_sel_hi:[0,1,1]
	ds_read2_b64 v[170:173], v64 offset0:214 offset1:247
	v_mov_b32_e32 v123, v121
	v_mov_b32_e32 v127, v125
	s_waitcnt lgkmcnt(0)
	v_pk_mul_f32 v[134:135], v[134:135], v[170:171] op_sel:[1,1] op_sel_hi:[1,0]
	s_nop 0
	v_pk_fma_f32 v[160:161], v[128:129], v[170:171], v[134:135] op_sel_hi:[0,1,1] neg_lo:[0,0,1] neg_hi:[0,0,1]
	v_pk_fma_f32 v[158:159], v[128:129], v[170:171], v[134:135] op_sel_hi:[0,1,1]
	v_pk_mul_f32 v[128:129], v[148:149], v[172:173] op_sel:[0,1] op_sel_hi:[0,0]
	v_pk_fma_f32 v[134:135], v[130:131], v[172:173], v[128:129] op_sel_hi:[0,1,1] neg_lo:[0,0,1] neg_hi:[0,0,1]
	v_pk_fma_f32 v[128:129], v[130:131], v[172:173], v[128:129] op_sel_hi:[0,1,1]
	v_mov_b32_e32 v161, v159
	v_mov_b32_e32 v135, v129
	v_add_u32_e32 v68, 0x1800, v138
	ds_read2_b64 v[170:173], v68 offset0:24 offset1:57
	s_waitcnt lgkmcnt(0)
	v_pk_mul_f32 v[140:141], v[150:151], v[170:171] op_sel:[1,1] op_sel_hi:[1,0]
	s_nop 0
	v_pk_fma_f32 v[130:131], v[132:133], v[170:171], v[140:141] neg_lo:[0,0,1] neg_hi:[0,0,1]
	v_pk_fma_f32 v[132:133], v[132:133], v[170:171], v[140:141] op_sel_hi:[0,1,1]
	v_mov_b32_e32 v131, v133
	v_pk_mul_f32 v[132:133], v[152:153], v[172:173] op_sel:[1,1] op_sel_hi:[1,0]
	ds_read2_b64 v[150:153], v68 offset0:90 offset1:123
	v_pk_fma_f32 v[148:149], v[136:137], v[172:173], v[132:133] op_sel_hi:[0,1,1] neg_lo:[0,0,1] neg_hi:[0,0,1]
	v_pk_fma_f32 v[132:133], v[136:137], v[172:173], v[132:133] op_sel_hi:[0,1,1]
	v_mov_b32_e32 v149, v133
	s_waitcnt lgkmcnt(0)
	v_pk_mul_f32 v[98:99], v[98:99], v[150:151] op_sel:[1,1] op_sel_hi:[1,0]
	s_nop 0
	v_pk_fma_f32 v[140:141], v[94:95], v[150:151], v[98:99] neg_lo:[0,0,1] neg_hi:[0,0,1]
	v_pk_fma_f32 v[94:95], v[94:95], v[150:151], v[98:99] op_sel_hi:[0,1,1]
	v_mov_b32_e32 v141, v95
	v_pk_mul_f32 v[94:95], v[102:103], v[152:153] op_sel:[0,1] op_sel_hi:[0,0]
	v_pk_fma_f32 v[150:151], v[96:97], v[152:153], v[94:95] op_sel_hi:[0,1,1] neg_lo:[0,0,1] neg_hi:[0,0,1]
	v_pk_fma_f32 v[136:137], v[96:97], v[152:153], v[94:95] op_sel_hi:[0,1,1]
	v_mov_b32_e32 v151, v137
	ds_read2_b64 v[170:173], v68 offset0:156 offset1:189
	v_pk_add_f32 v[84:85], v[84:85], v[84:85] op_sel:[0,1] op_sel_hi:[0,1] neg_lo:[0,1] neg_hi:[0,1]
	s_waitcnt lgkmcnt(0)
	v_pk_mul_f32 v[94:95], v[106:107], v[170:171] op_sel:[1,1] op_sel_hi:[1,0]
	s_nop 0
	v_pk_fma_f32 v[102:103], v[100:101], v[170:171], v[94:95] op_sel_hi:[0,1,1] neg_lo:[0,0,1] neg_hi:[0,0,1]
	v_pk_fma_f32 v[98:99], v[100:101], v[170:171], v[94:95] op_sel_hi:[0,1,1]
	v_pk_mul_f32 v[94:95], v[108:109], v[172:173] op_sel:[1,1] op_sel_hi:[1,0]
	v_mov_b32_e32 v103, v99
	v_pk_fma_f32 v[96:97], v[104:105], v[172:173], v[94:95] op_sel_hi:[0,1,1] neg_lo:[0,0,1] neg_hi:[0,0,1]
	v_pk_fma_f32 v[94:95], v[104:105], v[172:173], v[94:95] op_sel_hi:[0,1,1]
	ds_read2_b64 v[104:107], v68 offset0:222 offset1:255
	v_mov_b32_e32 v97, v95
	s_waitcnt lgkmcnt(0)
	v_pk_mul_f32 v[90:91], v[90:91], v[104:105] op_sel:[1,1] op_sel_hi:[1,0]
	s_nop 0
	v_pk_fma_f32 v[180:181], v[86:87], v[104:105], v[90:91] op_sel_hi:[0,1,1] neg_lo:[0,0,1] neg_hi:[0,0,1]
	v_pk_fma_f32 v[174:175], v[86:87], v[104:105], v[90:91] op_sel_hi:[0,1,1]
	v_pk_add_f32 v[86:87], v[88:89], v[88:89] op_sel:[0,1] op_sel_hi:[0,1]
	v_pk_mul_f32 v[86:87], v[86:87], v[106:107] op_sel:[0,1] op_sel_hi:[1,0]
	v_mov_b32_e32 v181, v175
	v_pk_fma_f32 v[152:153], v[84:85], v[106:107], v[86:87] neg_lo:[0,0,1] neg_hi:[0,0,1]
	v_pk_fma_f32 v[100:101], v[84:85], v[106:107], v[86:87]
	s_nop 0
	v_mov_b32_e32 v153, v101
	v_pk_add_f32 v[84:85], v[92:93], v[166:167] neg_lo:[0,1] neg_hi:[0,1]
	v_pk_add_f32 v[210:211], v[164:165], v[140:141]
	v_mul_f32_e32 v38, 0x3f6c835e, v85
	v_pk_add_f32 v[140:141], v[164:165], v[140:141] neg_lo:[0,1] neg_hi:[0,1]
	v_pk_add_f32 v[88:89], v[32:33], v[168:169]
	v_pk_add_f32 v[90:91], v[42:43], v[114:115]
	v_pk_add_f32 v[104:105], v[92:93], v[166:167]
	v_mul_f32_e32 v187, 0x3f6c835e, v84
	v_mul_f32_e32 v189, 0x3ec3ef15, v85
	v_pk_fma_f32 v[84:85], v[84:85], s[8:9], v[38:39] op_sel_hi:[1,1,0]
	v_pk_add_f32 v[92:93], v[48:49], v[156:157]
	v_pk_add_f32 v[108:109], v[36:37], v[122:123]
	v_pk_add_f32 v[106:107], v[44:45], v[126:127]
	v_pk_add_f32 v[162:163], v[56:57], v[160:161]
	v_pk_add_f32 v[168:169], v[52:53], v[134:135]
	v_pk_add_f32 v[172:173], v[58:59], v[130:131]
	v_pk_add_f32 v[86:87], v[58:59], v[130:131] neg_lo:[0,1] neg_hi:[0,1]
	v_pk_add_f32 v[166:167], v[62:63], v[148:149]
	v_mul_f32_e32 v59, 0xbec3ef15, v140
	v_mul_f32_e32 v131, 0x3f6c835e, v141
; __device__ __forceinline__ float2 cmul(float2 a, float2 b) { return make_float2(a.x * b.x - a.y * b.y, a.x * b.y + a.y * b.x); }
; __device__ __forceinline__ float2 cadd(float2 a, float2 b) { return make_float2(a.x + b.x, a.y + b.y); }
; __device__ __forceinline__ float2 csub(float2 a, float2 b) { return make_float2(a.x - b.x, a.y - b.y); }
; template <int R, int LOG, bool INV> __device__ __forceinline__ void reg_fft(float2 (&v)[R]) {
; #pragma unroll
;   for (int st = 0; st < LOG; ++st) {
;     const int ln = R >> st, h = ln >> 1;
; #pragma unroll
;     for (int blk = 0; blk < R; blk += ln)
; #pragma unroll
;       for (int j = 0; j < h; ++j) {
;         const float2 a = v[blk + j], b = v[blk + j + h];
;         v[blk + j] = cadd(a, b);
;         const float2 d = csub(a, b);
;         const int tk = j * (32 / ln);
;         if (tk == 0) v[blk + j + h] = d;
;         else if (tk == 8) v[blk + j + h] = INV ? make_float2(-d.y, d.x) : make_float2(d.y, -d.x);
;         else { const float c = tw32c(tk), s = tw32s(tk); v[blk + j + h] = cmul(d, make_float2(c, INV ? s : -s)); }
;       }
;     __builtin_amdgcn_sched_barrier(0);
;   }
; }
	v_mul_f32_e32 v60, 0x3f6c835e, v140
	v_mul_f32_e32 v132, 0x3ec3ef15, v141
	v_pk_add_f32 v[140:141], v[74:75], v[150:151]
	v_pk_add_f32 v[212:213], v[70:71], v[102:103]
	v_pk_add_f32 v[164:165], v[66:67], v[96:97]
	v_pk_add_f32 v[214:215], v[82:83], v[180:181]
	v_pk_add_f32 v[216:217], v[78:79], v[152:153]
	v_pk_add_f32 v[218:219], v[90:91], v[166:167]
	v_pk_add_f32 v[90:91], v[90:91], v[166:167] neg_lo:[0,1] neg_hi:[0,1]
	v_pk_add_f32 v[230:231], v[106:107], v[164:165]
	v_mul_f32_e32 v38, 0x3f6c835e, v91
	v_pk_add_f32 v[106:107], v[106:107], v[164:165] neg_lo:[0,1] neg_hi:[0,1]
	v_pk_add_f32 v[170:171], v[88:89], v[172:173]
	v_mul_f32_e32 v221, 0x3f6c835e, v90
	v_mul_f32_e32 v223, 0x3ec3ef15, v91
	v_pk_fma_f32 v[90:91], v[90:91], s[8:9], v[38:39] op_sel_hi:[1,1,0]
	v_pk_add_f32 v[166:167], v[104:105], v[210:211]
	v_pk_add_f32 v[224:225], v[92:93], v[140:141]
	v_pk_add_f32 v[226:227], v[108:109], v[212:213]
	v_pk_add_f32 v[228:229], v[108:109], v[212:213] neg_lo:[0,1] neg_hi:[0,1]
	v_mul_f32_e32 v109, 0xbec3ef15, v106
	v_mul_f32_e32 v213, 0x3f6c835e, v107
	v_mul_f32_e32 v232, 0x3f6c835e, v106
	v_mul_f32_e32 v234, 0x3ec3ef15, v107
	v_pk_add_f32 v[106:107], v[162:163], v[214:215]
	v_pk_add_f32 v[164:165], v[168:169], v[216:217]
	v_pk_add_f32 v[176:177], v[170:171], v[226:227]
	v_pk_add_f32 v[178:179], v[218:219], v[230:231]
	v_pk_add_f32 v[236:237], v[166:167], v[106:107]
	v_pk_add_f32 v[238:239], v[224:225], v[164:165]
	v_pk_add_f32 v[182:183], v[176:177], v[236:237]
	v_pk_add_f32 v[240:241], v[178:179], v[238:239]
	s_nop 0
	v_pk_add_f32 v[184:185], v[182:183], v[240:241]
	v_pk_add_f32 v[170:171], v[170:171], v[226:227] neg_lo:[0,1] neg_hi:[0,1]
	v_pk_add_f32 v[106:107], v[166:167], v[106:107] neg_lo:[0,1] neg_hi:[0,1]
	v_mov_b32_e32 v166, v218
	v_mov_b32_e32 v167, v224
	v_mov_b32_e32 v226, v230
	v_mov_b32_e32 v227, v164
	v_mov_b32_e32 v224, v219
	v_mov_b32_e32 v164, v231
	v_pk_mov_b32 v[172:173], v[172:173], v[172:173] op_sel:[1,0]
	v_pk_add_f32 v[166:167], v[166:167], v[226:227] neg_lo:[0,1] neg_hi:[0,1]
	v_pk_add_f32 v[164:165], v[224:225], v[164:165] neg_lo:[0,1] neg_hi:[0,1]
	v_mov_b32_e32 v222, v172
	v_pk_add_f32 v[108:109], v[108:109], v[212:213] neg_lo:[0,1] neg_hi:[0,1]
	v_mov_b32_e32 v235, v173
	v_mov_b32_e32 v172, v162
	v_mov_b32_e32 v173, v92
	v_mov_b32_e32 v212, v214
	v_mov_b32_e32 v213, v140
	v_mov_b32_e32 v92, v163
	v_mov_b32_e32 v140, v215
	v_pk_mul_f32 v[218:219], v[166:167], s[10:11]
	v_pk_mul_f32 v[164:165], v[164:165], s[20:21] op_sel_hi:[1,0]
	v_pk_add_f32 v[172:173], v[172:173], v[212:213] neg_lo:[0,1] neg_hi:[0,1]
	v_pk_add_f32 v[92:93], v[92:93], v[140:141] neg_lo:[0,1] neg_hi:[0,1]
	v_pk_add_f32 v[224:225], v[218:219], v[164:165] op_sel:[1,1] op_sel_hi:[0,0] neg_lo:[0,1] neg_hi:[0,1]
	v_pk_add_f32 v[218:219], v[218:219], v[164:165] op_sel:[1,1] op_sel_hi:[0,0]
	v_pk_mul_f32 v[140:141], v[172:173], s[12:13]
	v_pk_mul_f32 v[162:163], v[92:93], s[14:15]
	v_pk_mul_f32 v[92:93], v[92:93], s[16:17]
	v_mov_b32_e32 v226, v224
	v_mov_b32_e32 v227, v219
	v_pk_fma_f32 v[164:165], v[166:167], s[20:21], v[164:165] op_sel_hi:[1,0,1] neg_lo:[0,0,1] neg_hi:[0,0,1]
	v_pk_add_f32 v[212:213], v[140:141], v[92:93] op_sel:[1,1] op_sel_hi:[0,0] neg_lo:[0,1] neg_hi:[0,1]
	v_pk_add_f32 v[92:93], v[140:141], v[92:93] op_sel:[1,1] op_sel_hi:[0,0]
	v_pk_fma_f32 v[140:141], v[172:173], s[16:17], v[162:163] neg_lo:[0,0,1] neg_hi:[0,0,1]
	v_mov_b32_e32 v163, v168
	v_mov_b32_e32 v173, v216
	v_mov_b32_e32 v168, v105
	v_mov_b32_e32 v216, v211
	v_pk_add_f32 v[230:231], v[170:171], v[106:107] op_sel:[0,1] op_sel_hi:[1,0] neg_lo:[0,1] neg_hi:[0,1]
	v_pk_add_f32 v[106:107], v[170:171], v[106:107] op_sel:[0,1] op_sel_hi:[1,0]
	v_pk_add_f32 v[226:227], v[164:165], v[226:227]
	v_pk_mov_b32 v[218:219], v[218:219], v[164:165] op_sel:[1,0]
	v_pk_mov_b32 v[164:165], v[164:165], v[224:225] op_sel:[1,0]
	v_pk_mov_b32 v[88:89], v[88:89], v[88:89] op_sel:[1,0]
	v_mov_b32_e32 v162, v104
	v_mov_b32_e32 v172, v210
	v_pk_add_f32 v[104:105], v[168:169], v[216:217] neg_lo:[0,1] neg_hi:[0,1]
	v_mov_b32_e32 v167, v107
	v_mov_b32_e32 v107, v231
	v_pk_add_f32 v[164:165], v[218:219], v[164:165] neg_lo:[0,1] neg_hi:[0,1]
	v_mov_b32_e32 v233, v89
	v_pk_add_f32 v[162:163], v[162:163], v[172:173] neg_lo:[0,1] neg_hi:[0,1]
	v_pk_mul_f32 v[168:169], v[104:105], s[16:17]
	v_pk_add_f32 v[218:219], v[106:107], v[164:165] neg_lo:[0,1] neg_hi:[0,1]
	v_pk_add_f32 v[106:107], v[106:107], v[164:165]
	v_mov_b32_e32 v220, v88
	v_pk_add_f32 v[88:89], v[232:233], v[234:235] neg_lo:[0,1] neg_hi:[0,1]
	v_pk_mul_f32 v[104:105], v[104:105], s[14:15]
	v_pk_fma_f32 v[172:173], v[162:163], s[18:19], v[168:169] neg_lo:[0,0,1] neg_hi:[0,0,1]
	v_pk_fma_f32 v[210:211], v[162:163], s[18:19], v[168:169]
	v_mov_b32_e32 v91, v229
	v_mov_b32_e32 v166, v230
	v_mov_b32_e32 v164, v218
	v_mov_b32_e32 v165, v107
	v_mov_b32_e32 v107, v219
	v_pk_add_f32 v[218:219], v[220:221], v[222:223] neg_lo:[0,1] neg_hi:[0,1]
	v_mov_b32_e32 v93, v213
	v_mov_b32_e32 v211, v173
	v_pk_fma_f32 v[104:105], v[162:163], s[16:17], v[104:105] neg_lo:[0,0,1] neg_hi:[0,0,1]
	v_pk_add_f32 v[216:217], v[88:89], v[90:91] neg_lo:[0,1] neg_hi:[0,1]
	v_pk_add_f32 v[220:221], v[88:89], v[90:91]
	v_pk_add_f32 v[170:171], v[166:167], v[226:227]
	v_pk_add_f32 v[166:167], v[166:167], v[226:227] neg_lo:[0,1] neg_hi:[0,1]
	v_pk_add_f32 v[162:163], v[218:219], v[108:109]
	v_mov_b32_e32 v221, v217
	v_sub_f32_e32 v38, v90, v88
	v_pk_add_f32 v[224:225], v[140:141], v[210:211]
	v_pk_add_f32 v[226:227], v[104:105], v[92:93] op_sel:[1,0] op_sel_hi:[0,1]
	v_pk_mov_b32 v[214:215], v[104:105], v[104:105] op_sel:[1,0]
	v_mul_f32_e32 v222, 0x3f3504f3, v38
; __device__ __forceinline__ float2 cmul(float2 a, float2 b) { return make_float2(a.x * b.x - a.y * b.y, a.x * b.y + a.y * b.x); }
; __device__ __forceinline__ float2 cadd(float2 a, float2 b) { return make_float2(a.x + b.x, a.y + b.y); }
; __device__ __forceinline__ float2 csub(float2 a, float2 b) { return make_float2(a.x - b.x, a.y - b.y); }
; template <int R, int LOG, bool INV> __device__ __forceinline__ void reg_fft(float2 (&v)[R]) {
; #pragma unroll
;   for (int st = 0; st < LOG; ++st) {
;     const int ln = R >> st, h = ln >> 1;
; #pragma unroll
;     for (int blk = 0; blk < R; blk += ln)
; #pragma unroll
;       for (int j = 0; j < h; ++j) {
;         const float2 a = v[blk + j], b = v[blk + j + h];
;         v[blk + j] = cadd(a, b);
;         const float2 d = csub(a, b);
;         const int tk = j * (32 / ln);
;         if (tk == 0) v[blk + j + h] = d;
;         else if (tk == 8) v[blk + j + h] = INV ? make_float2(-d.y, d.x) : make_float2(d.y, -d.x);
;         else { const float c = tw32c(tk), s = tw32s(tk); v[blk + j + h] = cmul(d, make_float2(c, INV ? s : -s)); }
;       }
;     __builtin_amdgcn_sched_barrier(0);
;   }
; }
	v_sub_f32_e32 v38, v92, v105
	v_pk_add_f32 v[92:93], v[162:163], v[224:225]
	v_pk_add_f32 v[104:105], v[220:221], v[226:227]
	v_sub_f32_e32 v37, v219, v109
	v_pk_add_f32 v[168:169], v[92:93], v[104:105]
	v_mul_f32_e32 v90, 0x3f3504f3, v37
	v_sub_f32_e32 v37, v141, v173
	v_pk_mov_b32 v[172:173], v[168:169], v[168:169] op_sel:[1,0]
	v_pk_mov_b32 v[168:169], v[104:105], v[92:93] op_sel:[1,0]
	v_pk_mov_b32 v[92:93], v[92:93], v[104:105] op_sel:[1,0]
	v_pk_mov_b32 v[104:105], v[226:227], v[224:225] op_sel:[1,0]
	v_pk_add_f32 v[168:169], v[168:169], v[92:93] neg_lo:[0,1] neg_hi:[0,1]
	v_pk_mov_b32 v[92:93], v[216:217], v[162:163] op_sel:[1,0]
	v_mov_b32_e32 v221, v163
	v_mov_b32_e32 v227, v225
	v_pk_add_f32 v[92:93], v[92:93], v[104:105] neg_lo:[0,1] neg_hi:[0,1]
	v_pk_add_f32 v[104:105], v[220:221], v[226:227] neg_lo:[0,1] neg_hi:[0,1]
	v_mul_f32_e32 v212, 0x3f3504f3, v38
	v_pk_add_f32 v[216:217], v[92:93], v[104:105] neg_lo:[0,1] neg_hi:[0,1]
	v_pk_add_f32 v[104:105], v[92:93], v[104:105]
	v_mov_b32_e32 v91, v218
	v_mov_b32_e32 v223, v108
	v_mul_f32_e32 v211, 0x3f3504f3, v37
	v_mov_b32_e32 v162, v216
	v_mov_b32_e32 v163, v105
	v_mov_b32_e32 v105, v217
	v_pk_add_f32 v[216:217], v[90:91], v[222:223] neg_lo:[0,1] neg_hi:[0,1]
	v_mov_b32_e32 v88, v89
	v_mov_b32_e32 v89, v90
	v_pk_mov_b32 v[90:91], v[228:229], v[222:223] op_sel:[1,0]
	v_mov_b32_e32 v141, v212
	v_mul_f32_e32 v214, 0xbf3504f3, v37
	v_pk_add_f32 v[88:89], v[88:89], v[90:91]
	v_pk_add_f32 v[140:141], v[210:211], v[140:141] neg_lo:[0,1] neg_hi:[0,1]
	v_pk_add_f32 v[90:91], v[214:215], v[212:213] neg_lo:[0,1] neg_hi:[0,1]
	v_pk_add_f32 v[210:211], v[88:89], v[140:141] neg_lo:[0,1] neg_hi:[0,1]
	v_pk_add_f32 v[212:213], v[88:89], v[140:141]
	v_pk_add_f32 v[92:93], v[216:217], v[90:91]
	v_mov_b32_e32 v211, v213
	v_pk_add_f32 v[108:109], v[210:211], v[92:93]
	v_mov_b32_e32 v211, v93
	v_mov_b32_e32 v93, v213
	v_pk_add_f32 v[92:93], v[210:211], v[92:93] neg_lo:[0,1] neg_hi:[0,1]
	v_pk_add_f32 v[210:211], v[216:217], v[90:91] neg_lo:[0,1] neg_hi:[0,1]
	v_pk_mov_b32 v[88:89], v[88:89], v[216:217] op_sel:[1,0]
	v_pk_mov_b32 v[90:91], v[140:141], v[90:91] op_sel:[1,0]
	v_mov_b32_e32 v213, v211
	v_pk_add_f32 v[88:89], v[88:89], v[90:91] neg_lo:[0,1] neg_hi:[0,1]
	v_mov_b32_e32 v38, v61
	v_pk_add_f32 v[140:141], v[212:213], v[88:89] neg_lo:[0,1] neg_hi:[0,1]
	v_pk_add_f32 v[88:89], v[212:213], v[88:89]
	v_mov_b32_e32 v110, v133
	v_mov_b32_e32 v46, v73
	v_mov_b32_e32 v154, v137
	v_mov_b32_e32 v90, v140
	v_mov_b32_e32 v91, v89
	v_mov_b32_e32 v89, v141
	v_pk_mov_b32 v[140:141], v[32:33], v[32:33] op_sel:[1,0]
	v_pk_mov_b32 v[116:117], v[118:119], v[116:117] op_sel:[1,0]
	v_mov_b32_e32 v63, v42
	v_mov_b32_e32 v149, v114
	v_pk_add_f32 v[38:39], v[38:39], v[110:111] neg_lo:[0,1] neg_hi:[0,1]
	v_mov_b32_e32 v75, v48
	v_mov_b32_e32 v151, v156
	v_pk_add_f32 v[46:47], v[46:47], v[154:155] neg_lo:[0,1] neg_hi:[0,1]
	v_pk_add_f32 v[42:43], v[62:63], v[148:149] neg_lo:[0,1] neg_hi:[0,1]
	v_pk_mul_f32 v[110:111], v[38:39], s[64:65] op_sel_hi:[1,0]
	v_pk_mul_f32 v[38:39], v[38:39], s[92:93] op_sel_hi:[1,0]
	v_mov_b32_e32 v61, v141
	v_mov_b32_e32 v133, v117
	v_pk_add_f32 v[48:49], v[74:75], v[150:151] neg_lo:[0,1] neg_hi:[0,1]
	v_pk_mul_f32 v[72:73], v[46:47], s[58:59] op_sel_hi:[1,0]
	v_pk_mul_f32 v[46:47], v[46:47], s[54:55] op_sel_hi:[1,0]
	v_mov_b32_e32 v71, v56
	v_mov_b32_e32 v103, v160
	v_mov_b32_e32 v54, v69
	v_mov_b32_e32 v158, v99
	v_mov_b32_e32 v40, v65
	v_mov_b32_e32 v124, v95
	v_pk_mul_f32 v[62:63], v[42:43], s[50:51]
	v_pk_fma_f32 v[38:39], v[42:43], s[64:65], v[38:39] op_sel_hi:[1,0,1] neg_lo:[0,0,1] neg_hi:[0,0,1]
	v_pk_add_f32 v[42:43], v[58:59], v[130:131] neg_lo:[0,1] neg_hi:[0,1]
	v_pk_add_f32 v[58:59], v[60:61], v[132:133] neg_lo:[0,1] neg_hi:[0,1]
	v_pk_mul_f32 v[60:61], v[48:49], s[72:73]
	v_pk_fma_f32 v[46:47], v[48:49], s[58:59], v[46:47] op_sel_hi:[1,0,1] neg_lo:[0,0,1] neg_hi:[0,0,1]
	v_pk_add_f32 v[48:49], v[70:71], v[102:103] neg_lo:[0,1] neg_hi:[0,1]
	v_pk_add_f32 v[54:55], v[54:55], v[158:159] neg_lo:[0,1] neg_hi:[0,1]
	v_mov_b32_e32 v67, v44
	v_mov_b32_e32 v97, v126
	v_pk_add_f32 v[40:41], v[40:41], v[124:125] neg_lo:[0,1] neg_hi:[0,1]
	v_pk_mul_f32 v[56:57], v[48:49], s[12:13]
	v_pk_mul_f32 v[70:71], v[54:55], s[14:15]
	v_pk_mul_f32 v[54:55], v[54:55], s[16:17]
	v_pk_add_f32 v[44:45], v[66:67], v[96:97] neg_lo:[0,1] neg_hi:[0,1]
	v_pk_mul_f32 v[66:67], v[40:41], s[54:55] op_sel_hi:[1,0]
	v_pk_mul_f32 v[40:41], v[40:41], s[58:59] op_sel_hi:[1,0]
	v_mov_b32_e32 v80, v35
	v_mov_b32_e32 v174, v121
	v_pk_add_f32 v[74:75], v[60:61], v[72:73] op_sel:[1,1] op_sel_hi:[0,0] neg_lo:[0,1] neg_hi:[0,1]
	v_pk_add_f32 v[60:61], v[60:61], v[72:73] op_sel:[1,1] op_sel_hi:[0,0]
	v_pk_add_f32 v[72:73], v[56:57], v[54:55] op_sel:[1,1] op_sel_hi:[0,0] neg_lo:[0,1] neg_hi:[0,1]
	v_pk_add_f32 v[54:55], v[56:57], v[54:55] op_sel:[1,1] op_sel_hi:[0,0]
	v_pk_mul_f32 v[56:57], v[44:45], s[62:63]
	v_pk_fma_f32 v[40:41], v[44:45], s[54:55], v[40:41] op_sel_hi:[1,0,1] neg_lo:[0,0,1] neg_hi:[0,0,1]
	v_mov_b32_e32 v37, v82
	v_mov_b32_e32 v123, v180
	v_pk_add_f32 v[44:45], v[80:81], v[174:175] neg_lo:[0,1] neg_hi:[0,1]
	v_pk_fma_f32 v[48:49], v[48:49], s[16:17], v[70:71] neg_lo:[0,0,1] neg_hi:[0,0,1]
	v_pk_add_f32 v[70:71], v[56:57], v[66:67] op_sel:[1,1] op_sel_hi:[0,0] neg_lo:[0,1] neg_hi:[0,1]
	v_pk_add_f32 v[56:57], v[56:57], v[66:67] op_sel:[1,1] op_sel_hi:[0,0]
	v_pk_add_f32 v[36:37], v[36:37], v[122:123] neg_lo:[0,1] neg_hi:[0,1]
	v_pk_mul_f32 v[66:67], v[44:45], s[16:17]
	v_pk_mul_f32 v[44:45], v[44:45], s[14:15]
	v_mov_b32_e32 v79, v52
	v_mov_b32_e32 v153, v134
	v_mov_b32_e32 v50, v77
	v_mov_b32_e32 v128, v101
; __device__ __forceinline__ float2 cmul(float2 a, float2 b) { return make_float2(a.x * b.x - a.y * b.y, a.x * b.y + a.y * b.x); }
; __device__ __forceinline__ float2 cadd(float2 a, float2 b) { return make_float2(a.x + b.x, a.y + b.y); }
; __device__ __forceinline__ float2 csub(float2 a, float2 b) { return make_float2(a.x - b.x, a.y - b.y); }
; template <int R, int LOG, bool INV> __device__ __forceinline__ void reg_fft(float2 (&v)[R]) {
; #pragma unroll
;   for (int st = 0; st < LOG; ++st) {
;     const int ln = R >> st, h = ln >> 1;
; #pragma unroll
;     for (int blk = 0; blk < R; blk += ln)
; #pragma unroll
;       for (int j = 0; j < h; ++j) {
;         const float2 a = v[blk + j], b = v[blk + j + h];
;         v[blk + j] = cadd(a, b);
;         const float2 d = csub(a, b);
;         const int tk = j * (32 / ln);
;         if (tk == 0) v[blk + j + h] = d;
;         else if (tk == 8) v[blk + j + h] = INV ? make_float2(-d.y, d.x) : make_float2(d.y, -d.x);
;         else { const float c = tw32c(tk), s = tw32s(tk); v[blk + j + h] = cmul(d, make_float2(c, INV ? s : -s)); }
;       }
;     __builtin_amdgcn_sched_barrier(0);
;   }
; }
; __device__ __forceinline__ void fft_inv(float2* X, int tid) {
;     ...
;     for (int x = 0; x < 32; ++x) xb[33 * brev_n(x, 5)] = v[x];
	v_pk_fma_f32 v[80:81], v[36:37], s[18:19], v[66:67] neg_lo:[0,0,1] neg_hi:[0,0,1]
	v_pk_fma_f32 v[66:67], v[36:37], s[18:19], v[66:67]
	v_pk_fma_f32 v[36:37], v[36:37], s[16:17], v[44:45] neg_lo:[0,0,1] neg_hi:[0,0,1]
	v_pk_add_f32 v[44:45], v[78:79], v[152:153] neg_lo:[0,1] neg_hi:[0,1]
	v_pk_add_f32 v[50:51], v[50:51], v[128:129] neg_lo:[0,1] neg_hi:[0,1]
	v_pk_mul_f32 v[52:53], v[44:45], s[60:61]
	v_pk_mul_f32 v[76:77], v[50:51], s[92:93] op_sel_hi:[1,0]
	v_mov_b32_e32 v186, v140
	v_mov_b32_e32 v188, v116
	v_pk_add_f32 v[114:115], v[62:63], v[110:111] op_sel:[1,1] op_sel_hi:[0,0] neg_lo:[0,1] neg_hi:[0,1]
	v_pk_add_f32 v[62:63], v[62:63], v[110:111] op_sel:[1,1] op_sel_hi:[0,0]
	v_pk_add_f32 v[78:79], v[52:53], v[76:77] op_sel:[1,1] op_sel_hi:[0,0] neg_lo:[0,1] neg_hi:[0,1]
	v_pk_add_f32 v[52:53], v[52:53], v[76:77] op_sel:[1,1] op_sel_hi:[0,0]
	v_pk_mul_f32 v[50:51], v[50:51], s[64:65] op_sel_hi:[1,0]
	v_mov_b32_e32 v85, v87
	v_pk_add_f32 v[32:33], v[186:187], v[188:189] neg_lo:[0,1] neg_hi:[0,1]
	v_mov_b32_e32 v63, v115
	v_mov_b32_e32 v61, v75
	v_mov_b32_e32 v55, v73
	v_mov_b32_e32 v57, v71
	v_mov_b32_e32 v67, v81
	v_mov_b32_e32 v53, v79
	v_pk_fma_f32 v[44:45], v[44:45], s[92:93], v[50:51] op_sel_hi:[1,0,1] neg_lo:[0,0,1] neg_hi:[0,0,1]
	v_pk_add_f32 v[82:83], v[58:59], v[84:85] neg_lo:[0,1] neg_hi:[0,1]
	v_pk_add_f32 v[94:95], v[58:59], v[84:85]
	v_pk_add_f32 v[50:51], v[38:39], v[62:63]
	v_sub_f32_e32 v35, v39, v115
	v_pk_add_f32 v[76:77], v[32:33], v[42:43]
	v_mov_b32_e32 v95, v83
	v_pk_add_f32 v[96:97], v[46:47], v[60:61]
	v_pk_add_f32 v[98:99], v[40:41], v[56:57]
	v_pk_add_f32 v[102:103], v[48:49], v[66:67]
	v_pk_add_f32 v[110:111], v[36:37], v[54:55] op_sel:[1,0] op_sel_hi:[0,1]
	v_pk_add_f32 v[114:115], v[44:45], v[52:53]
	v_pk_add_f32 v[116:117], v[50:51], v[98:99]
	v_pk_add_f32 v[118:119], v[76:77], v[102:103]
	v_pk_add_f32 v[120:121], v[94:95], v[110:111]
	v_pk_add_f32 v[122:123], v[96:97], v[114:115]
	v_pk_add_f32 v[124:125], v[118:119], v[120:121]
	v_pk_add_f32 v[126:127], v[116:117], v[122:123]
	v_pk_add_f32 v[182:183], v[182:183], v[240:241] neg_lo:[0,1] neg_hi:[0,1]
	v_pk_add_f32 v[128:129], v[124:125], v[126:127]
	v_pk_add_f32 v[124:125], v[124:125], v[126:127] neg_lo:[0,1] neg_hi:[0,1]
	v_pk_add_f32 v[176:177], v[176:177], v[236:237] neg_lo:[0,1] neg_hi:[0,1]
	v_pk_mov_b32 v[124:125], v[124:125], v[124:125] op_sel:[1,0]
	ds_write2_b64 v64, v[182:183], v[124:125] offset0:16 offset1:49
	v_pk_mov_b32 v[124:125], v[120:121], v[118:119] op_sel:[1,0]
	v_pk_mov_b32 v[118:119], v[118:119], v[120:121] op_sel:[1,0]
	v_pk_add_f32 v[178:179], v[178:179], v[238:239] neg_lo:[0,1] neg_hi:[0,1]
	v_pk_add_f32 v[118:119], v[124:125], v[118:119] neg_lo:[0,1] neg_hi:[0,1]
	v_pk_add_f32 v[116:117], v[116:117], v[122:123] neg_lo:[0,1] neg_hi:[0,1]
	v_pk_add_f32 v[236:237], v[176:177], v[178:179] op_sel:[0,1] op_sel_hi:[1,0] neg_lo:[0,1] neg_hi:[0,1]
	v_pk_add_f32 v[176:177], v[176:177], v[178:179] op_sel:[0,1] op_sel_hi:[1,0]
	v_pk_add_f32 v[120:121], v[118:119], v[116:117] neg_lo:[0,1] neg_hi:[0,1]
	v_pk_add_f32 v[116:117], v[118:119], v[116:117]
	v_mov_b32_e32 v179, v177
	v_mov_b32_e32 v177, v237
	v_mov_b32_e32 v119, v117
	v_mov_b32_e32 v117, v121
	ds_write2_b64 v68, v[176:177], v[116:117] offset0:24 offset1:57
	v_pk_mov_b32 v[116:117], v[110:111], v[102:103] op_sel:[1,0]
	v_mov_b32_e32 v95, v77
	v_mov_b32_e32 v111, v103
	v_pk_mov_b32 v[82:83], v[82:83], v[76:77] op_sel:[1,0]
	v_pk_add_f32 v[76:77], v[94:95], v[110:111] neg_lo:[0,1] neg_hi:[0,1]
	v_mov_b32_e32 v94, v51
	v_mov_b32_e32 v95, v97
	v_mov_b32_e32 v102, v99
	v_mov_b32_e32 v103, v115
	v_mov_b32_e32 v51, v96
	v_mov_b32_e32 v99, v114
	v_pk_add_f32 v[94:95], v[94:95], v[102:103] neg_lo:[0,1] neg_hi:[0,1]
	v_pk_add_f32 v[50:51], v[50:51], v[98:99] neg_lo:[0,1] neg_hi:[0,1]
	v_pk_mul_f32 v[96:97], v[94:95], s[10:11]
	v_pk_mul_f32 v[50:51], v[50:51], s[20:21] op_sel_hi:[1,0]
	v_pk_add_f32 v[82:83], v[82:83], v[116:117] neg_lo:[0,1] neg_hi:[0,1]
	v_pk_add_f32 v[98:99], v[96:97], v[50:51] op_sel:[1,1] op_sel_hi:[0,0] neg_lo:[0,1] neg_hi:[0,1]
	v_pk_add_f32 v[96:97], v[96:97], v[50:51] op_sel:[1,1] op_sel_hi:[0,0]
	v_mov_b32_e32 v102, v98
	v_mov_b32_e32 v103, v97
	v_pk_fma_f32 v[50:51], v[94:95], s[20:21], v[50:51] op_sel_hi:[1,0,1] neg_lo:[0,0,1] neg_hi:[0,0,1]
	v_pk_add_f32 v[94:95], v[82:83], v[76:77] neg_lo:[0,1] neg_hi:[0,1]
	v_pk_add_f32 v[76:77], v[82:83], v[76:77]
	v_mov_b32_e32 v82, v94
	v_mov_b32_e32 v83, v77
	v_pk_add_f32 v[102:103], v[50:51], v[102:103]
	v_sub_f32_e32 v38, v62, v38
	v_pk_add_f32 v[110:111], v[82:83], v[102:103]
	v_pk_add_f32 v[82:83], v[82:83], v[102:103] neg_lo:[0,1] neg_hi:[0,1]
	ds_write2_b64 v64, v[166:167], v[82:83] offset0:148 offset1:181
	v_pk_mov_b32 v[82:83], v[96:97], v[50:51] op_sel:[1,0]
	v_pk_mov_b32 v[50:51], v[50:51], v[98:99] op_sel:[1,0]
	v_mul_f32_e32 v39, 0x3f6c835e, v35
	v_mul_f32_e32 v63, 0x3ec3ef15, v38
	v_mul_f32_e32 v70, 0x3ec3ef15, v35
	v_mul_f32_e32 v86, 0x3f6c835e, v38
	v_sub_f32_e32 v35, v41, v71
	v_sub_f32_e32 v38, v56, v40
	v_mov_b32_e32 v77, v95
	v_pk_add_f32 v[50:51], v[82:83], v[50:51] neg_lo:[0,1] neg_hi:[0,1]
	v_mov_b32_e32 v71, v59
	v_mov_b32_e32 v40, v36
	v_mov_b32_e32 v101, v48
	v_mov_b32_e32 v48, v49
	v_mov_b32_e32 v49, v47
	v_mov_b32_e32 v74, v81
	v_mov_b32_e32 v55, v60
	v_pk_mov_b32 v[36:37], v[36:37], v[46:47] op_sel:[1,0]
	v_mov_b32_e32 v85, v52
	v_mov_b32_e32 v59, v44
	v_mul_f32_e32 v57, 0x3f6c835e, v38
; __device__ __forceinline__ float2 cmul(float2 a, float2 b) { return make_float2(a.x * b.x - a.y * b.y, a.x * b.y + a.y * b.x); }
; __device__ __forceinline__ float2 cadd(float2 a, float2 b) { return make_float2(a.x + b.x, a.y + b.y); }
; __device__ __forceinline__ float2 csub(float2 a, float2 b) { return make_float2(a.x - b.x, a.y - b.y); }
; template <int R, int LOG, bool INV> __device__ __forceinline__ void reg_fft(float2 (&v)[R]) {
; #pragma unroll
;   for (int st = 0; st < LOG; ++st) {
;     const int ln = R >> st, h = ln >> 1;
; #pragma unroll
;     for (int blk = 0; blk < R; blk += ln)
; #pragma unroll
;       for (int j = 0; j < h; ++j) {
;         const float2 a = v[blk + j], b = v[blk + j + h];
;         v[blk + j] = cadd(a, b);
;         const float2 d = csub(a, b);
;         const int tk = j * (32 / ln);
;         if (tk == 0) v[blk + j + h] = d;
;         else if (tk == 8) v[blk + j + h] = INV ? make_float2(-d.y, d.x) : make_float2(d.y, -d.x);
;         else { const float c = tw32c(tk), s = tw32s(tk); v[blk + j + h] = cmul(d, make_float2(c, INV ? s : -s)); }
;       }
;     __builtin_amdgcn_sched_barrier(0);
;   }
; }
; __device__ __forceinline__ void fft_inv(float2* X, int tid) {
;     ...
;     for (int x = 0; x < 32; ++x) xb[33 * brev_n(x, 5)] = v[x];
;   }
;   __syncthreads();
	v_mul_f32_e32 v100, 0x3ec3ef15, v38
	v_pk_add_f32 v[82:83], v[76:77], v[50:51] neg_lo:[0,1] neg_hi:[0,1]
	v_pk_add_f32 v[50:51], v[76:77], v[50:51]
	v_mov_b32_e32 v38, v32
	v_mov_b32_e32 v62, v42
	v_pk_add_f32 v[48:49], v[48:49], v[74:75] neg_lo:[0,1] neg_hi:[0,1]
	v_pk_add_f32 v[36:37], v[54:55], v[36:37] neg_lo:[0,1] neg_hi:[0,1]
	v_mov_b32_e32 v32, v33
	v_mov_b32_e32 v33, v45
	v_mov_b32_e32 v78, v43
	v_pk_add_f32 v[42:43], v[84:85], v[58:59] neg_lo:[0,1] neg_hi:[0,1]
	v_mul_f32_e32 v41, 0xbec3ef15, v35
	v_mul_f32_e32 v72, 0x3f6c835e, v35
	v_mov_b32_e32 v77, v51
	v_mov_b32_e32 v51, v83
	v_mov_b32_e32 v56, v73
	v_mov_b32_e32 v73, v66
	v_pk_mul_f32 v[46:47], v[48:49], s[12:13]
	v_pk_mul_f32 v[54:55], v[36:37], s[14:15]
	v_pk_mul_f32 v[36:37], v[36:37], s[16:17]
	v_pk_add_f32 v[32:33], v[32:33], v[78:79] neg_lo:[0,1] neg_hi:[0,1]
	v_pk_mul_f32 v[44:45], v[42:43], s[16:17]
	ds_write2_b64 v68, v[106:107], v[50:51] offset0:156 offset1:189
	v_pk_add_f32 v[50:51], v[70:71], v[86:87]
	v_pk_add_f32 v[40:41], v[40:41], v[56:57] neg_lo:[0,1] neg_hi:[0,1]
	v_pk_add_f32 v[56:57], v[72:73], v[100:101] neg_lo:[0,1] neg_hi:[0,1]
	v_pk_add_f32 v[60:61], v[46:47], v[36:37] op_sel:[1,1] op_sel_hi:[0,0] neg_lo:[0,1] neg_hi:[0,1]
	v_pk_add_f32 v[36:37], v[46:47], v[36:37] op_sel:[1,1] op_sel_hi:[0,0]
	v_pk_fma_f32 v[46:47], v[48:49], s[16:17], v[54:55] neg_lo:[0,0,1] neg_hi:[0,0,1]
	v_pk_mul_f32 v[42:43], v[42:43], s[14:15]
	v_pk_fma_f32 v[48:49], v[32:33], s[18:19], v[44:45] neg_lo:[0,0,1] neg_hi:[0,0,1]
	v_pk_fma_f32 v[44:45], v[32:33], s[18:19], v[44:45]
	v_pk_add_f32 v[38:39], v[38:39], v[62:63] neg_lo:[0,1] neg_hi:[0,1]
	v_mov_b32_e32 v37, v61
	v_mov_b32_e32 v45, v49
	v_pk_fma_f32 v[32:33], v[32:33], s[16:17], v[42:43] neg_lo:[0,0,1] neg_hi:[0,0,1]
	v_pk_add_f32 v[54:55], v[50:51], v[56:57] neg_lo:[0,1] neg_hi:[0,1]
	v_pk_add_f32 v[58:59], v[50:51], v[56:57]
	v_pk_mov_b32 v[42:43], v[32:33], v[32:33] op_sel:[1,0]
	v_pk_add_f32 v[52:53], v[38:39], v[40:41]
	v_mov_b32_e32 v59, v55
	v_pk_add_f32 v[66:67], v[46:47], v[44:45]
	v_pk_add_f32 v[70:71], v[32:33], v[36:37] op_sel:[1,0] op_sel_hi:[0,1]
	v_sub_f32_e32 v32, v47, v49
	v_sub_f32_e32 v33, v36, v33
	v_mul_f32_e32 v42, 0xbf3504f3, v32
	v_mul_f32_e32 v60, 0x3f3504f3, v33
	v_mul_f32_e32 v45, 0x3f3504f3, v32
	v_pk_add_f32 v[32:33], v[52:53], v[66:67]
	v_pk_add_f32 v[36:37], v[58:59], v[70:71]
	v_mov_b32_e32 v59, v53
	v_pk_add_f32 v[72:73], v[32:33], v[36:37]
	v_sub_f32_e32 v35, v39, v41
	v_pk_mov_b32 v[72:73], v[72:73], v[72:73] op_sel:[1,0]
	ds_write2_b64 v138, v[172:173], v[72:73] offset0:66 offset1:99
	v_pk_mov_b32 v[72:73], v[36:37], v[32:33] op_sel:[1,0]
	v_pk_mov_b32 v[32:33], v[32:33], v[36:37] op_sel:[1,0]
	v_pk_mov_b32 v[36:37], v[70:71], v[66:67] op_sel:[1,0]
	v_pk_add_f32 v[32:33], v[72:73], v[32:33] neg_lo:[0,1] neg_hi:[0,1]
	ds_write2_b64 v64, v[168:169], v[32:33] offset0:82 offset1:115
	v_pk_mov_b32 v[32:33], v[54:55], v[52:53] op_sel:[1,0]
	v_mov_b32_e32 v71, v67
	v_pk_add_f32 v[32:33], v[32:33], v[36:37] neg_lo:[0,1] neg_hi:[0,1]
	v_pk_add_f32 v[36:37], v[58:59], v[70:71] neg_lo:[0,1] neg_hi:[0,1]
	v_mul_f32_e32 v48, 0x3f3504f3, v35
	v_pk_add_f32 v[52:53], v[32:33], v[36:37] neg_lo:[0,1] neg_hi:[0,1]
	v_pk_add_f32 v[32:33], v[32:33], v[36:37]
	v_mul_f32_e32 v62, 0x3f3504f3, v54
	v_mov_b32_e32 v36, v52
	v_mov_b32_e32 v37, v33
	ds_write2_b64 v34, v[162:163], v[36:37] offset0:74 offset1:107
	v_mov_b32_e32 v49, v38
	v_mov_b32_e32 v36, v51
	v_mov_b32_e32 v37, v48
	v_mov_b32_e32 v38, v57
	v_mov_b32_e32 v39, v62
	v_mov_b32_e32 v47, v60
	v_mov_b32_e32 v33, v53
	v_mov_b32_e32 v63, v40
	v_pk_add_f32 v[36:37], v[36:37], v[38:39]
	v_pk_add_f32 v[40:41], v[44:45], v[46:47] neg_lo:[0,1] neg_hi:[0,1]
	ds_write2_b64 v68, v[104:105], v[32:33] offset0:90 offset1:123
	v_pk_add_f32 v[32:33], v[48:49], v[62:63] neg_lo:[0,1] neg_hi:[0,1]
	v_pk_add_f32 v[38:39], v[42:43], v[60:61] neg_lo:[0,1] neg_hi:[0,1]
	v_pk_add_f32 v[44:45], v[36:37], v[40:41] neg_lo:[0,1] neg_hi:[0,1]
	v_pk_add_f32 v[46:47], v[36:37], v[40:41]
	v_pk_add_f32 v[42:43], v[32:33], v[38:39]
	v_mov_b32_e32 v45, v47
	v_pk_add_f32 v[48:49], v[44:45], v[42:43]
	v_mov_b32_e32 v45, v43
	v_mov_b32_e32 v43, v47
	v_pk_add_f32 v[42:43], v[44:45], v[42:43] neg_lo:[0,1] neg_hi:[0,1]
	ds_write2_b64 v64, v[92:93], v[42:43] offset0:214 offset1:247
	v_pk_add_f32 v[42:43], v[32:33], v[38:39] neg_lo:[0,1] neg_hi:[0,1]
	v_pk_mov_b32 v[32:33], v[36:37], v[32:33] op_sel:[1,0]
	v_pk_mov_b32 v[36:37], v[40:41], v[38:39] op_sel:[1,0]
	v_mov_b32_e32 v47, v43
	v_pk_add_f32 v[32:33], v[32:33], v[36:37] neg_lo:[0,1] neg_hi:[0,1]
	v_mov_b32_e32 v178, v236
	v_pk_add_f32 v[36:37], v[46:47], v[32:33] neg_lo:[0,1] neg_hi:[0,1]
	v_pk_add_f32 v[32:33], v[46:47], v[32:33]
	v_pk_mov_b32 v[128:129], v[128:129], v[128:129] op_sel:[1,0]
	v_mov_b32_e32 v118, v120
	v_mov_b32_e32 v76, v82
	v_mov_b32_e32 v38, v36
	v_mov_b32_e32 v39, v33
	v_mov_b32_e32 v33, v37
	s_mov_b64 s[20:21], -1
	ds_write2_b64 v138, v[184:185], v[128:129] offset1:33
	ds_write2_b64 v34, v[178:179], v[118:119] offset0:8 offset1:41
	ds_write2_b64 v138, v[170:171], v[110:111] offset0:132 offset1:165
	ds_write2_b64 v34, v[164:165], v[76:77] offset0:140 offset1:173
	ds_write2_b64 v138, v[108:109], v[48:49] offset0:198 offset1:231
	ds_write2_b64 v34, v[90:91], v[38:39] offset0:206 offset1:239
	ds_write2_b64 v68, v[88:89], v[32:33] offset0:222 offset1:255
	s_waitcnt lgkmcnt(0)
	s_barrier
